# GEMM K-loops: 8 phases merged into 4 super-phases (32 MFMA per barrier interval, half the barriers), lgkmcnt(0)+vmcnt(8) before each barrier, prologue vmcnt(2)
# speedup vs baseline: 1.0308x; 1.0308x over previous
; #define PG8_STAGE(bufoff, gbase, voff) do { _Pragma("unroll") for (int _i = 0; _i < 2; ++_i) \
;         __builtin_amdgcn_global_load_lds((const unsigned*)((const char*)(gbase) + (voff)[_i]), (PG8_LAS unsigned*)(lds + (bufoff) + ldsw + _i * 8192), 16, 0, 0); } while (0)
; #define PG8_WAIT_V(n) asm volatile("s_waitcnt vmcnt(" #n ")" ::: "memory")
; #define PG8_BAR __builtin_amdgcn_s_barrier()
; template <class Epi, class Sched>
; __device__ __forceinline__ void gemm_phase(PG8_LAS unsigned char* lds, const Gemm g, const Sched& S, const Epi& E) {
;     const int tid = threadIdx.x, wid = __builtin_amdgcn_readfirstlane(tid >> 6), lane = tid & 63, wr = wid >> 2, wc = wid & 3, fr = lane & 15, fq = lane >> 4;
;     const int K = g.K, nt = K / BK;
;     unsigned voffA[2], voffB[2];
; #pragma unroll
;     for (int i = 0; i < 2; ++i) { int R, C; stage_rc(tid * 16 + i * 8192, R, C); const int Rb = Epi::PERM ? ((R & ~31) + perm32(R & 31)) : R;
;         voffA[i] = (unsigned)(R * K + C) * 2u; voffB[i] = (unsigned)(Rb * K + C) * 2u; }
;     const size_t kstep = (size_t)(BK * 2);
;     const size_t hstep = (size_t)HALF * K * 2;
;     const size_t tstep = 2 * hstep;
;     const unsigned ldsw = (unsigned)wid * 1024u;
;     const int aoff = lds_byte(wr * 64 + fr, fq * 8), boff = lds_byte(wc * 32 + fr, fq * 8);
;     ...
;     PG8_STAGE(PG8_SB(0, 0), cB, voffB); PG8_STAGE(PG8_SA(0, 0), cA, voffA); PG8_STAGE(PG8_SB(0, 1), cB + hstep, voffB); PG8_STAGE(PG8_SA(0, 1), cA + hstep, voffA);
;     if (wr == 1) PG8_BAR;
;     PG8_WAIT_V(4); PG8_BAR;
;     PG8_STAGE(PG8_SB(1, 0), cB + kstep, voffB); PG8_STAGE(PG8_SA(1, 0), cA + kstep, voffA); PG8_STAGE(PG8_SB(1, 1), cB + hstep + kstep, voffB);
;     PG8_WAIT_V(6); PG8_BAR;
.LBB0_230:
	s_add_u32 s6, s58, 0x23d86000
	s_addc_u32 s7, s59, 0
	s_add_u32 s82, s58, 0xfc86000
	s_addc_u32 s83, s59, 0
	s_add_u32 s8, s58, 0x1fd86000
	s_addc_u32 s9, s59, 0
	s_waitcnt lgkmcnt(0)
	s_add_u32 s20, s58, 0x6a24000
	s_addc_u32 s21, s59, 0
	s_lshl_b32 s3, s3, 5
	s_mov_b64 s[26:27], 0x80
	s_and_b32 s3, s3, 0x60
	s_add_i32 m0, s67, 0x18000
	v_lshl_add_u64 v[6:7], v[6:7], 0, s[26:27]
	s_lshl_b32 s5, s2, 13
	s_lshl_b32 s10, s3, 7
	s_waitcnt vmcnt(2)
	s_barrier
	global_load_lds_dwordx4 v[6:7], off
	v_lshl_add_u64 v[4:5], v[4:5], 0, s[26:27]
	s_add_i32 m0, s67, 0x1a000
	s_add_i32 s84, s67, 0x8000
	s_add_i32 s85, s67, 0xa000
	global_load_lds_dwordx4 v[4:5], off
	v_lshl_add_u64 v[0:1], v[0:1], 0, s[26:27]
	s_mov_b32 m0, s84
	s_add_u32 s28, s70, 0x80080
	global_load_lds_dwordx4 v[0:1], off
	v_lshl_add_u64 v[0:1], v[2:3], 0, s[26:27]
	s_mov_b32 m0, s85
	s_addc_u32 s29, s71, 0
	global_load_lds_dwordx4 v[0:1], off
	s_add_i32 m0, s67, 0x1c000
	v_lshl_add_u64 v[0:1], s[28:29], 0, v[138:139]
	global_load_lds_dwordx4 v[0:1], off
	v_lshl_add_u64 v[0:1], s[28:29], 0, v[142:143]
	s_add_i32 m0, s67, 0x1e000
	v_lshlrev_b32_e32 v2, 2, v242
	global_load_lds_dwordx4 v[0:1], off
	v_and_b32_e32 v0, 15, v242
	v_lshl_or_b32 v147, s2, 6, v0
	v_lshlrev_b32_e32 v1, 1, v12
	v_lshlrev_b32_e32 v3, 6, v242
	s_movk_i32 s2, 0x3c0
	v_lshl_or_b32 v0, v0, 6, v1
	v_and_b32_e32 v2, 32, v2
	v_and_or_b32 v1, v3, s2, v1
	v_bitop3_b32 v160, s10, v1, v2 bitop3:0xf6
	v_lshlrev_b32_e32 v1, 9, v242
	v_bitop3_b32 v0, v0, s5, v2 bitop3:0xde
	v_and_b32_e32 v1, 0x70000, v1
	v_lshlrev_b32_e32 v2, 12, v10
	v_or3_b32 v1, v8, v1, v2
	v_add_u32_e32 v148, v1, v9
	v_lshlrev_b32_e32 v1, 5, v11
	s_waitcnt vmcnt(6)
	v_and_b32_e32 v1, 0xf0000, v1
	v_or_b32_e32 v146, s3, v12
	v_or3_b32 v1, v8, v1, v2
	s_add_i32 s90, 0, 0x10000
	s_add_i32 s91, 0, 0x14000
	v_or_b32_e32 v161, 0xfffff400, v146
	s_ashr_i32 s86, s62, 31
	s_mov_b32 s87, s62
	s_ashr_i32 s88, s12, 31
	s_lshl_b32 s89, s74, 2
	v_mov_b32_e32 v149, v145
	v_add_u32_e32 v150, v1, v9
	v_mov_b32_e32 v151, v145
	v_mov_b64_e32 v[152:153], s[0:1]
	v_add_u32_e32 v162, s90, v160
	v_add_u32_e32 v163, 0, v0
	v_add_u32_e32 v164, s91, v160
	s_mov_b64 s[28:29], 0x40000
	s_mov_b64 s[30:31], 0x48000
	s_mov_b64 s[34:35], 0x50000
	s_mov_b64 s[38:39], 0x58000
	s_mov_b32 s92, 0x80000
	s_mov_b64 s[40:41], 0x90000
	s_mov_b32 s93, 0x90000
	s_mov_b64 s[42:43], 0xa0000
	s_mov_b32 s94, 0xa0000
	s_mov_b64 s[44:45], 0xb0000
	s_mov_b32 s95, 0xb0000
	s_mov_b32 s96, 0
	s_barrier
	s_branch .LBB0_232

; #define PG8_STAGE(bufoff, gbase, voff) do { _Pragma("unroll") for (int _i = 0; _i < 2; ++_i) \
;         __builtin_amdgcn_global_load_lds((const unsigned*)((const char*)(gbase) + (voff)[_i]), (PG8_LAS unsigned*)(lds + (bufoff) + ldsw + _i * 8192), 16, 0, 0); } while (0)
; #define PG8_LDA(dst, b, h) do { _Pragma("unroll") for (int m = 0; m < 4; ++m) _Pragma("unroll") for (int k = 0; k < 2; ++k) dst[m][k] = *(const PG8_LAS bf16x8*)(lds + PG8_SA(b, h) + aoff + m * 2048 + k * 1024); } while (0)
; #define PG8_LDB(dst, b, h) do { _Pragma("unroll") for (int n = 0; n < 2; ++n) _Pragma("unroll") for (int k = 0; k < 2; ++k) dst[n][k] = *(const PG8_LAS bf16x8*)(lds + PG8_SB(b, h) + boff + n * 2048 + k * 1024); } while (0)
; #define PG8_MMA(ai, bj, At, Bt) do { __builtin_amdgcn_s_setprio(1); _Pragma("unroll") for (int m = 0; m < 4; ++m) _Pragma("unroll") for (int n = 0; n < 2; ++n) _Pragma("unroll") for (int k = 0; k < 2; ++k) \
;         acc[ai][bj][m][n] = __builtin_amdgcn_mfma_f32_16x16x32_bf16(Bt[n][k], At[m][k], acc[ai][bj][m][n], 0, 0, 0); __builtin_amdgcn_s_setprio(0); } while (0)
; #define PG8_WAIT_L(n) asm volatile("s_waitcnt lgkmcnt(" #n ")" ::: "memory")
; #define PG8_BAR __builtin_amdgcn_s_barrier()
; #define PG8_SCHED __builtin_amdgcn_sched_barrier(0)
; template <class Epi, class Sched>
; __device__ __forceinline__ void gemm_phase(PG8_LAS unsigned char* lds, const Gemm g, const Sched& S, const Epi& E) {
;     ...
;             const bool last = (t == nt - 2);
;             const char* a1 = cA + (size_t)(t + 1) * kstep;
;             const char* a2 = last ? nA : cA + (size_t)(t + 2) * kstep; const char* b2 = last ? nB : cB + (size_t)(t + 2) * kstep;
;             const char* a3 = a2 + kstep; const char* b3 = b2 + kstep;
;             if (last && has_next) S.a_ready(nxt);
;             PG8_LDB(B0, 0, 0); PG8_SCHED; PG8_LDA(At, 0, 0); PG8_STAGE(PG8_SA(1, 1), a1 + hstep, voffA);
;             PG8_WAIT_L(8); PG8_BAR; PG8_WAIT_L(0); PG8_MMA(0, 0, At, B0); PG8_BAR; PG8_SCHED;
;             PG8_LDB(B1, 0, 1); PG8_STAGE(PG8_SB(0, 0), b2, voffB);
;             PG8_BAR; PG8_WAIT_L(0); PG8_MMA(0, 1, At, B1); PG8_BAR;
;             PG8_LDA(At, 0, 1); PG8_STAGE(PG8_SA(0, 0), a2, voffA);
;             PG8_BAR; PG8_WAIT_L(0); PG8_MMA(1, 0, At, B0); PG8_BAR; PG8_SCHED;
;             PG8_STAGE(PG8_SB(0, 1), b2 + hstep, voffB);
.LBB0_235:
	ds_read_b128 v[128:131], v162
	ds_read_b128 v[132:135], v162 offset:1024
	ds_read_b128 v[154:157], v162 offset:2048
	ds_read_b128 v[166:169], v162 offset:3072
	ds_read_b128 v[170:173], v163
	ds_read_b128 v[174:177], v163 offset:1024
	ds_read_b128 v[178:181], v163 offset:2048
	ds_read_b128 v[182:185], v163 offset:3072
	ds_read_b128 v[186:189], v163 offset:4096
	ds_read_b128 v[190:193], v163 offset:5120
	ds_read_b128 v[194:197], v163 offset:6144
	ds_read_b128 v[198:201], v163 offset:7168
	ds_read_b128 v[202:205], v164
	ds_read_b128 v[206:209], v164 offset:1024
	ds_read_b128 v[210:213], v164 offset:2048
	ds_read_b128 v[214:217], v164 offset:3072
	s_add_u32 s10, s68, 0xfff80080
	s_addc_u32 s11, s69, -1
	s_cmp_eq_u32 vcc_hi, 28
	s_cselect_b32 s73, s0, s11
	s_cselect_b32 s72, s5, s10
	s_cselect_b32 s71, s47, vcc_lo
	s_cselect_b32 s70, s49, s97
	v_lshl_add_u64 v[158:159], s[68:69], 0, v[148:149]
	s_add_i32 m0, s67, 0xc000
	s_nop 0
	global_load_lds_dwordx4 v[158:159], off
	v_lshl_add_u64 v[158:159], s[68:69], 0, v[150:151]
	s_add_i32 m0, s67, 0xe000
	s_nop 0
	global_load_lds_dwordx4 v[158:159], off
	s_waitcnt vmcnt(8)
	s_waitcnt lgkmcnt(0)
	s_barrier
	s_setprio 1
	v_mfma_f32_16x16x32_bf16 v[124:127], v[128:131], v[170:173], v[124:127]
	v_mfma_f32_16x16x32_bf16 v[120:123], v[154:157], v[170:173], v[120:123]
	v_mfma_f32_16x16x32_bf16 v[116:119], v[128:131], v[178:181], v[116:119]
	v_mfma_f32_16x16x32_bf16 v[112:115], v[154:157], v[178:181], v[112:115]
	v_mfma_f32_16x16x32_bf16 v[108:111], v[128:131], v[186:189], v[108:111]
	v_mfma_f32_16x16x32_bf16 v[104:107], v[154:157], v[186:189], v[104:107]
	v_mfma_f32_16x16x32_bf16 v[100:103], v[128:131], v[194:197], v[100:103]
	v_mfma_f32_16x16x32_bf16 v[96:99], v[154:157], v[194:197], v[96:99]
	v_mfma_f32_16x16x32_bf16 v[124:127], v[132:135], v[174:177], v[124:127]
	v_mfma_f32_16x16x32_bf16 v[120:123], v[166:169], v[174:177], v[120:123]
	v_mfma_f32_16x16x32_bf16 v[116:119], v[132:135], v[182:185], v[116:119]
	v_mfma_f32_16x16x32_bf16 v[112:115], v[166:169], v[182:185], v[112:115]
	v_mfma_f32_16x16x32_bf16 v[108:111], v[132:135], v[190:193], v[108:111]
	v_mfma_f32_16x16x32_bf16 v[104:107], v[166:169], v[190:193], v[104:107]
	v_mfma_f32_16x16x32_bf16 v[100:103], v[132:135], v[198:201], v[100:103]
	v_mfma_f32_16x16x32_bf16 v[96:99], v[166:169], v[198:201], v[96:99]
	v_mfma_f32_16x16x32_bf16 v[60:63], v[202:205], v[170:173], v[60:63]
	v_mfma_f32_16x16x32_bf16 v[56:59], v[210:213], v[170:173], v[56:59]
	v_mfma_f32_16x16x32_bf16 v[52:55], v[202:205], v[178:181], v[52:55]
	v_mfma_f32_16x16x32_bf16 v[48:51], v[210:213], v[178:181], v[48:51]
	v_mfma_f32_16x16x32_bf16 v[44:47], v[202:205], v[186:189], v[44:47]
	v_mfma_f32_16x16x32_bf16 v[40:43], v[210:213], v[186:189], v[40:43]
	v_mfma_f32_16x16x32_bf16 v[36:39], v[202:205], v[194:197], v[36:39]
	v_mfma_f32_16x16x32_bf16 v[32:35], v[210:213], v[194:197], v[32:35]
	v_mfma_f32_16x16x32_bf16 v[60:63], v[206:209], v[174:177], v[60:63]
	v_mfma_f32_16x16x32_bf16 v[56:59], v[214:217], v[174:177], v[56:59]
	v_mfma_f32_16x16x32_bf16 v[52:55], v[206:209], v[182:185], v[52:55]
	v_mfma_f32_16x16x32_bf16 v[48:51], v[214:217], v[182:185], v[48:51]
	v_mfma_f32_16x16x32_bf16 v[44:47], v[206:209], v[190:193], v[44:47]
	v_mfma_f32_16x16x32_bf16 v[40:43], v[214:217], v[190:193], v[40:43]
	v_mfma_f32_16x16x32_bf16 v[36:39], v[206:209], v[198:201], v[36:39]
	v_mfma_f32_16x16x32_bf16 v[32:35], v[214:217], v[198:201], v[32:35]
	s_setprio 0
	s_barrier
	ds_read_b128 v[170:173], v163 offset:16384
	ds_read_b128 v[174:177], v163 offset:17408
	ds_read_b128 v[178:181], v163 offset:18432
	ds_read_b128 v[182:185], v163 offset:19456
	ds_read_b128 v[186:189], v163 offset:20480
	ds_read_b128 v[190:193], v163 offset:21504
	ds_read_b128 v[194:197], v163 offset:22528
	ds_read_b128 v[198:201], v163 offset:23552
	s_add_i32 s10, s90, s78
	v_lshl_add_u64 v[158:159], s[70:71], 0, v[138:139]
	s_mov_b32 m0, s10
	s_nop 0
	global_load_lds_dwordx4 v[158:159], off
	v_lshl_add_u64 v[218:219], s[70:71], 0, v[142:143]
	s_add_i32 m0, s10, 0x2000
	s_nop 0
	global_load_lds_dwordx4 v[218:219], off
	s_mov_b32 m0, s67
	v_lshl_add_u64 v[220:221], s[72:73], 0, v[136:137]
	global_load_lds_dwordx4 v[220:221], off
	v_lshl_add_u64 v[222:223], s[72:73], 0, v[140:141]
	s_mov_b32 m0, s79
	s_nop 0
	global_load_lds_dwordx4 v[222:223], off
	s_add_u32 s10, s70, 0x80000
	s_addc_u32 s11, s71, 0
	s_add_i32 s33, s91, s78
	v_lshl_add_u64 v[224:225], s[10:11], 0, v[138:139]
	s_mov_b32 m0, s33
	s_nop 0
	global_load_lds_dwordx4 v[224:225], off
	v_lshl_add_u64 v[224:225], s[10:11], 0, v[142:143]
	s_add_i32 m0, s33, 0x2000
	s_nop 0
	global_load_lds_dwordx4 v[224:225], off
	s_waitcnt vmcnt(8)
	s_waitcnt lgkmcnt(0)
	s_barrier
; #define PG8_STAGE(bufoff, gbase, voff) do { _Pragma("unroll") for (int _i = 0; _i < 2; ++_i) \
;         __builtin_amdgcn_global_load_lds((const unsigned*)((const char*)(gbase) + (voff)[_i]), (PG8_LAS unsigned*)(lds + (bufoff) + ldsw + _i * 8192), 16, 0, 0); } while (0)
; #define PG8_LDA(dst, b, h) do { _Pragma("unroll") for (int m = 0; m < 4; ++m) _Pragma("unroll") for (int k = 0; k < 2; ++k) dst[m][k] = *(const PG8_LAS bf16x8*)(lds + PG8_SA(b, h) + aoff + m * 2048 + k * 1024); } while (0)
; #define PG8_LDB(dst, b, h) do { _Pragma("unroll") for (int n = 0; n < 2; ++n) _Pragma("unroll") for (int k = 0; k < 2; ++k) dst[n][k] = *(const PG8_LAS bf16x8*)(lds + PG8_SB(b, h) + boff + n * 2048 + k * 1024); } while (0)
; #define PG8_MMA(ai, bj, At, Bt) do { __builtin_amdgcn_s_setprio(1); _Pragma("unroll") for (int m = 0; m < 4; ++m) _Pragma("unroll") for (int n = 0; n < 2; ++n) _Pragma("unroll") for (int k = 0; k < 2; ++k) \
;         acc[ai][bj][m][n] = __builtin_amdgcn_mfma_f32_16x16x32_bf16(Bt[n][k], At[m][k], acc[ai][bj][m][n], 0, 0, 0); __builtin_amdgcn_s_setprio(0); } while (0)
; #define PG8_WAIT_V(n) asm volatile("s_waitcnt vmcnt(" #n ")" ::: "memory")
; #define PG8_WAIT_L(n) asm volatile("s_waitcnt lgkmcnt(" #n ")" ::: "memory")
; #define PG8_BAR __builtin_amdgcn_s_barrier()
; #define PG8_SCHED __builtin_amdgcn_sched_barrier(0)
; template <class Epi, class Sched>
; __device__ __forceinline__ void gemm_phase(PG8_LAS unsigned char* lds, const Gemm g, const Sched& S, const Epi& E) {
;     ...
;             PG8_BAR; PG8_WAIT_L(0); PG8_MMA(1, 0, At, B0); PG8_BAR; PG8_SCHED;
;             PG8_STAGE(PG8_SB(0, 1), b2 + hstep, voffB);
;             PG8_WAIT_V(6); PG8_BAR; PG8_MMA(1, 1, At, B1); PG8_BAR;
;             PG8_LDB(B0, 1, 0); PG8_SCHED; PG8_LDA(At, 1, 0); PG8_STAGE(PG8_SA(0, 1), a2 + hstep, voffA);
;             PG8_WAIT_L(8); PG8_BAR; PG8_WAIT_L(0); PG8_MMA(0, 0, At, B0); PG8_BAR; PG8_SCHED;
;             PG8_LDB(B1, 1, 1); PG8_STAGE(PG8_SB(1, 0), b3, voffB);
;             PG8_BAR; PG8_WAIT_L(0); PG8_MMA(0, 1, At, B1); PG8_BAR;
	s_setprio 1
	v_mfma_f32_16x16x32_bf16 v[92:95], v[128:131], v[170:173], v[92:95]
	v_mfma_f32_16x16x32_bf16 v[88:91], v[154:157], v[170:173], v[88:91]
	v_mfma_f32_16x16x32_bf16 v[84:87], v[128:131], v[178:181], v[84:87]
	v_mfma_f32_16x16x32_bf16 v[80:83], v[154:157], v[178:181], v[80:83]
	v_mfma_f32_16x16x32_bf16 v[76:79], v[128:131], v[186:189], v[76:79]
	v_mfma_f32_16x16x32_bf16 v[72:75], v[154:157], v[186:189], v[72:75]
	v_mfma_f32_16x16x32_bf16 v[68:71], v[128:131], v[194:197], v[68:71]
	v_mfma_f32_16x16x32_bf16 v[64:67], v[154:157], v[194:197], v[64:67]
	v_mfma_f32_16x16x32_bf16 v[92:95], v[132:135], v[174:177], v[92:95]
	v_mfma_f32_16x16x32_bf16 v[88:91], v[166:169], v[174:177], v[88:91]
	v_mfma_f32_16x16x32_bf16 v[84:87], v[132:135], v[182:185], v[84:87]
	v_mfma_f32_16x16x32_bf16 v[80:83], v[166:169], v[182:185], v[80:83]
	v_mfma_f32_16x16x32_bf16 v[76:79], v[132:135], v[190:193], v[76:79]
	v_mfma_f32_16x16x32_bf16 v[72:75], v[166:169], v[190:193], v[72:75]
	v_mfma_f32_16x16x32_bf16 v[68:71], v[132:135], v[198:201], v[68:71]
	v_mfma_f32_16x16x32_bf16 v[64:67], v[166:169], v[198:201], v[64:67]
	v_mfma_f32_16x16x32_bf16 v[28:31], v[202:205], v[170:173], v[28:31]
	v_mfma_f32_16x16x32_bf16 v[24:27], v[210:213], v[170:173], v[24:27]
	v_mfma_f32_16x16x32_bf16 v[20:23], v[202:205], v[178:181], v[20:23]
	v_mfma_f32_16x16x32_bf16 v[16:19], v[210:213], v[178:181], v[16:19]
	v_mfma_f32_16x16x32_bf16 v[12:15], v[202:205], v[186:189], v[12:15]
	v_mfma_f32_16x16x32_bf16 v[8:11], v[210:213], v[186:189], v[8:11]
	v_mfma_f32_16x16x32_bf16 v[4:7], v[202:205], v[194:197], v[4:7]
	v_mfma_f32_16x16x32_bf16 v[0:3], v[210:213], v[194:197], v[0:3]
	v_mfma_f32_16x16x32_bf16 v[28:31], v[206:209], v[174:177], v[28:31]
	v_mfma_f32_16x16x32_bf16 v[24:27], v[214:217], v[174:177], v[24:27]
	v_mfma_f32_16x16x32_bf16 v[20:23], v[206:209], v[182:185], v[20:23]
	v_mfma_f32_16x16x32_bf16 v[16:19], v[214:217], v[182:185], v[16:19]
	v_mfma_f32_16x16x32_bf16 v[12:15], v[206:209], v[190:193], v[12:15]
	v_mfma_f32_16x16x32_bf16 v[8:11], v[214:217], v[190:193], v[8:11]
	v_mfma_f32_16x16x32_bf16 v[4:7], v[206:209], v[198:201], v[4:7]
	v_mfma_f32_16x16x32_bf16 v[0:3], v[214:217], v[198:201], v[0:3]
	s_setprio 0
	s_add_i32 s33, 0, 0x18000
	v_add_u32_e32 v144, s33, v160
	s_barrier
	ds_read_b128 v[128:131], v162 offset:32768
	ds_read_b128 v[132:135], v162 offset:33792
	ds_read_b128 v[154:157], v162 offset:34816
	ds_read_b128 v[166:169], v162 offset:35840
	ds_read_b128 v[170:173], v163 offset:32768
	ds_read_b128 v[174:177], v163 offset:33792
	ds_read_b128 v[178:181], v163 offset:34816
	ds_read_b128 v[182:185], v163 offset:35840
	ds_read_b128 v[186:189], v163 offset:36864
	ds_read_b128 v[190:193], v163 offset:37888
	ds_read_b128 v[194:197], v163 offset:38912
	ds_read_b128 v[198:201], v163 offset:39936
	ds_read_b128 v[202:205], v164 offset:32768
	ds_read_b128 v[206:209], v164 offset:33792
	ds_read_b128 v[210:213], v164 offset:34816
	ds_read_b128 v[214:217], v164 offset:35840
	s_add_u32 s10, s72, 0x80000
	s_addc_u32 s11, s73, 0
	s_mov_b32 m0, s80
	v_lshl_add_u64 v[224:225], s[10:11], 0, v[136:137]
	global_load_lds_dwordx4 v[224:225], off
	v_lshl_add_u64 v[224:225], s[10:11], 0, v[140:141]
	s_mov_b32 m0, s81
	s_nop 0
	global_load_lds_dwordx4 v[224:225], off
	s_waitcnt vmcnt(8)
	s_waitcnt lgkmcnt(0)
	s_barrier
	s_setprio 1
	v_mfma_f32_16x16x32_bf16 v[124:127], v[128:131], v[170:173], v[124:127]
	v_mfma_f32_16x16x32_bf16 v[120:123], v[154:157], v[170:173], v[120:123]
	v_mfma_f32_16x16x32_bf16 v[116:119], v[128:131], v[178:181], v[116:119]
	v_mfma_f32_16x16x32_bf16 v[112:115], v[154:157], v[178:181], v[112:115]
	v_mfma_f32_16x16x32_bf16 v[108:111], v[128:131], v[186:189], v[108:111]
	v_mfma_f32_16x16x32_bf16 v[104:107], v[154:157], v[186:189], v[104:107]
	v_mfma_f32_16x16x32_bf16 v[100:103], v[128:131], v[194:197], v[100:103]
	v_mfma_f32_16x16x32_bf16 v[96:99], v[154:157], v[194:197], v[96:99]
	v_mfma_f32_16x16x32_bf16 v[124:127], v[132:135], v[174:177], v[124:127]
	v_mfma_f32_16x16x32_bf16 v[120:123], v[166:169], v[174:177], v[120:123]
	v_mfma_f32_16x16x32_bf16 v[116:119], v[132:135], v[182:185], v[116:119]
	v_mfma_f32_16x16x32_bf16 v[112:115], v[166:169], v[182:185], v[112:115]
	v_mfma_f32_16x16x32_bf16 v[108:111], v[132:135], v[190:193], v[108:111]
	v_mfma_f32_16x16x32_bf16 v[104:107], v[166:169], v[190:193], v[104:107]
	v_mfma_f32_16x16x32_bf16 v[100:103], v[132:135], v[198:201], v[100:103]
	v_mfma_f32_16x16x32_bf16 v[96:99], v[166:169], v[198:201], v[96:99]
	v_mfma_f32_16x16x32_bf16 v[60:63], v[202:205], v[170:173], v[60:63]
	v_mfma_f32_16x16x32_bf16 v[56:59], v[210:213], v[170:173], v[56:59]
	v_mfma_f32_16x16x32_bf16 v[52:55], v[202:205], v[178:181], v[52:55]
	v_mfma_f32_16x16x32_bf16 v[48:51], v[210:213], v[178:181], v[48:51]
	v_mfma_f32_16x16x32_bf16 v[44:47], v[202:205], v[186:189], v[44:47]
	v_mfma_f32_16x16x32_bf16 v[40:43], v[210:213], v[186:189], v[40:43]
	v_mfma_f32_16x16x32_bf16 v[36:39], v[202:205], v[194:197], v[36:39]
	v_mfma_f32_16x16x32_bf16 v[32:35], v[210:213], v[194:197], v[32:35]
	v_mfma_f32_16x16x32_bf16 v[60:63], v[206:209], v[174:177], v[60:63]
	v_mfma_f32_16x16x32_bf16 v[56:59], v[214:217], v[174:177], v[56:59]
	v_mfma_f32_16x16x32_bf16 v[52:55], v[206:209], v[182:185], v[52:55]
	v_mfma_f32_16x16x32_bf16 v[48:51], v[214:217], v[182:185], v[48:51]
	v_mfma_f32_16x16x32_bf16 v[44:47], v[206:209], v[190:193], v[44:47]
	v_mfma_f32_16x16x32_bf16 v[40:43], v[214:217], v[190:193], v[40:43]
	v_mfma_f32_16x16x32_bf16 v[36:39], v[206:209], v[198:201], v[36:39]
	v_mfma_f32_16x16x32_bf16 v[32:35], v[214:217], v[198:201], v[32:35]
	s_setprio 0
	s_barrier
; #define PG8_STAGE(bufoff, gbase, voff) do { _Pragma("unroll") for (int _i = 0; _i < 2; ++_i) \
;         __builtin_amdgcn_global_load_lds((const unsigned*)((const char*)(gbase) + (voff)[_i]), (PG8_LAS unsigned*)(lds + (bufoff) + ldsw + _i * 8192), 16, 0, 0); } while (0)
; #define PG8_LDA(dst, b, h) do { _Pragma("unroll") for (int m = 0; m < 4; ++m) _Pragma("unroll") for (int k = 0; k < 2; ++k) dst[m][k] = *(const PG8_LAS bf16x8*)(lds + PG8_SA(b, h) + aoff + m * 2048 + k * 1024); } while (0)
; #define PG8_WAIT_V(n) asm volatile("s_waitcnt vmcnt(" #n ")" ::: "memory")
; #define PG8_WAIT_L(n) asm volatile("s_waitcnt lgkmcnt(" #n ")" ::: "memory")
; #define PG8_BAR __builtin_amdgcn_s_barrier()
; template <class Epi, class Sched>
; __device__ __forceinline__ void gemm_phase(PG8_LAS unsigned char* lds, const Gemm g, const Sched& S, const Epi& E) {
;     ...
;             PG8_LDA(At, 1, 1); PG8_STAGE(PG8_SA(1, 0), a3, voffA);
;             PG8_BAR; PG8_WAIT_L(0); PG8_MMA(1, 0, At, B0); PG8_BAR; PG8_SCHED;
;             PG8_STAGE(PG8_SB(1, 1), b3 + hstep, voffB);
;             PG8_WAIT_V(6); PG8_BAR; PG8_MMA(1, 1, At, B1); PG8_BAR;
;         }
;     __device__ __forceinline__ void operator()(const AccT& acc, const pg8::Unit& u, int wr, int wc, int fr, int fq) const {
;         const int row0 = u.pm * 256 + wr * 64 + fr, cl = wc * 32 + 8 * fq, pn = u.pn;
;         if (pn < 8) {
; #pragma unroll
;             for (int bj = 0; bj < 2; ++bj) {
;                 const int col = pn * 256 + bj * 128 + cl;
;                 const f32x4 l0 = *(const f32x4*)(lb + col), l1 = *(const f32x4*)(lb + col + 4);
; #pragma unroll
;                 for (int ai = 0; ai < 2; ++ai)
; #pragma unroll
;                     for (int m = 0; m < 4; ++m) {
;                         const f32x4 a = acc[ai][bj][m][0], b = acc[ai][bj][m][1]; float g[8];
; #pragma unroll
;                         for (int j = 0; j < 4; ++j) { g[j] = (1.f - l0[j]) * __builtin_amdgcn_rcpf(1.f + __expf(a[j])); g[4 + j] = (1.f - l1[j]) * __builtin_amdgcn_rcpf(1.f + __expf(b[j])); }
;                         u32x4 w; w.x = pk_h2(g[0], g[1]); w.y = pk_h2(g[2], g[3]); w.z = pk_h2(g[4], g[5]); w.w = pk_h2(g[6], g[7]);
;                         *(u32x4*)(G + (size_t)(row0 + ai * 128 + m * 16) * 2048 + col) = w;
;                     }
;             }
;         } else if (pn < 24) {
;             if (u.pm >= 128 && pn >= 12) return;
	ds_read_b128 v[170:173], v163 offset:49152
	ds_read_b128 v[174:177], v163 offset:50176
	ds_read_b128 v[178:181], v163 offset:51200
	ds_read_b128 v[182:185], v163 offset:52224
	ds_read_b128 v[186:189], v163 offset:53248
	ds_read_b128 v[190:193], v163 offset:54272
	ds_read_b128 v[194:197], v163 offset:55296
	ds_read_b128 v[198:201], v163 offset:56320
	s_add_i32 s72, 0, 0x1c000
	s_add_i32 s10, s33, s78
	v_add_u32_e32 v144, s72, v160
	v_lshl_add_u64 v[158:159], v[158:159], 0, s[26:27]
	s_mov_b32 m0, s10
	s_nop 0
	global_load_lds_dwordx4 v[158:159], off
	v_lshl_add_u64 v[158:159], v[218:219], 0, s[26:27]
	s_add_i32 m0, s10, 0x2000
	s_nop 0
	global_load_lds_dwordx4 v[158:159], off
	s_mov_b32 m0, s84
	v_lshl_add_u64 v[158:159], v[220:221], 0, s[26:27]
	global_load_lds_dwordx4 v[158:159], off
	v_lshl_add_u64 v[158:159], v[222:223], 0, s[26:27]
	s_mov_b32 m0, s85
	s_nop 0
	global_load_lds_dwordx4 v[158:159], off
	s_add_u32 s10, s70, 0x80080
	s_addc_u32 s11, s71, 0
	s_add_i32 s33, s72, s78
	v_lshl_add_u64 v[224:225], s[10:11], 0, v[138:139]
	s_mov_b32 m0, s33
	s_nop 0
	global_load_lds_dwordx4 v[224:225], off
	v_lshl_add_u64 v[224:225], s[10:11], 0, v[142:143]
	s_add_i32 m0, s33, 0x2000
	s_nop 0
	global_load_lds_dwordx4 v[224:225], off
	s_waitcnt vmcnt(8)
	s_waitcnt lgkmcnt(0)
	s_barrier
	s_setprio 1
	v_mfma_f32_16x16x32_bf16 v[92:95], v[128:131], v[170:173], v[92:95]
	v_mfma_f32_16x16x32_bf16 v[88:91], v[154:157], v[170:173], v[88:91]
	v_mfma_f32_16x16x32_bf16 v[84:87], v[128:131], v[178:181], v[84:87]
	v_mfma_f32_16x16x32_bf16 v[80:83], v[154:157], v[178:181], v[80:83]
	v_mfma_f32_16x16x32_bf16 v[76:79], v[128:131], v[186:189], v[76:79]
	v_mfma_f32_16x16x32_bf16 v[72:75], v[154:157], v[186:189], v[72:75]
	v_mfma_f32_16x16x32_bf16 v[68:71], v[128:131], v[194:197], v[68:71]
	v_mfma_f32_16x16x32_bf16 v[64:67], v[154:157], v[194:197], v[64:67]
	v_mfma_f32_16x16x32_bf16 v[92:95], v[132:135], v[174:177], v[92:95]
	v_mfma_f32_16x16x32_bf16 v[88:91], v[166:169], v[174:177], v[88:91]
	v_mfma_f32_16x16x32_bf16 v[84:87], v[132:135], v[182:185], v[84:87]
	v_mfma_f32_16x16x32_bf16 v[80:83], v[166:169], v[182:185], v[80:83]
	v_mfma_f32_16x16x32_bf16 v[76:79], v[132:135], v[190:193], v[76:79]
	v_mfma_f32_16x16x32_bf16 v[72:75], v[166:169], v[190:193], v[72:75]
	v_mfma_f32_16x16x32_bf16 v[68:71], v[132:135], v[198:201], v[68:71]
	v_mfma_f32_16x16x32_bf16 v[64:67], v[166:169], v[198:201], v[64:67]
	v_mfma_f32_16x16x32_bf16 v[28:31], v[202:205], v[170:173], v[28:31]
	v_mfma_f32_16x16x32_bf16 v[24:27], v[210:213], v[170:173], v[24:27]
	v_mfma_f32_16x16x32_bf16 v[20:23], v[202:205], v[178:181], v[20:23]
	v_mfma_f32_16x16x32_bf16 v[16:19], v[210:213], v[178:181], v[16:19]
	v_mfma_f32_16x16x32_bf16 v[12:15], v[202:205], v[186:189], v[12:15]
	v_mfma_f32_16x16x32_bf16 v[8:11], v[210:213], v[186:189], v[8:11]
	v_mfma_f32_16x16x32_bf16 v[4:7], v[202:205], v[194:197], v[4:7]
	v_mfma_f32_16x16x32_bf16 v[0:3], v[210:213], v[194:197], v[0:3]
	v_mfma_f32_16x16x32_bf16 v[28:31], v[206:209], v[174:177], v[28:31]
	v_mfma_f32_16x16x32_bf16 v[24:27], v[214:217], v[174:177], v[24:27]
	v_mfma_f32_16x16x32_bf16 v[20:23], v[206:209], v[182:185], v[20:23]
	v_mfma_f32_16x16x32_bf16 v[16:19], v[214:217], v[182:185], v[16:19]
	v_mfma_f32_16x16x32_bf16 v[12:15], v[206:209], v[190:193], v[12:15]
	v_mfma_f32_16x16x32_bf16 v[8:11], v[214:217], v[190:193], v[8:11]
	v_mfma_f32_16x16x32_bf16 v[4:7], v[206:209], v[198:201], v[4:7]
	v_mfma_f32_16x16x32_bf16 v[0:3], v[214:217], v[198:201], v[0:3]
	s_setprio 0
	s_add_i32 vcc_hi, vcc_hi, 2
	s_add_u32 s68, s68, 0x100
	s_addc_u32 s69, s69, 0
	s_add_u32 s97, s97, 0x100
	s_addc_u32 vcc_lo, vcc_lo, 0
	s_cmp_gt_u32 vcc_hi, 29
	s_barrier
	s_cbranch_scc0 .LBB0_235
	v_lshl_add_u32 v154, s4, 8, v147
	s_cmp_gt_i32 s66, 7
	s_mov_b64 s[68:69], -1
	s_cbranch_scc0 .LBB0_277
	s_cmpk_gt_i32 s4, 0x7f
	s_cselect_b64 s[68:69], -1, 0
	s_cmpk_lt_i32 s4, 0x80
	s_cselect_b64 s[70:71], -1, 0
	s_cmp_gt_u32 s66, 23
	s_mov_b64 s[4:5], -1
	s_cbranch_scc0 .LBB0_241
	s_andn2_b64 vcc, exec, s[70:71]
	s_cbranch_vccnz .LBB0_240
; __device__ __forceinline__ unsigned cvt_pk_bf16(float lo, float hi) { const bf16v2_t v = __builtin_convertvector((f32x2){lo, hi}, bf16v2_t); return __builtin_bit_cast(unsigned, v); }
;     __device__ __forceinline__ void operator()(const AccT& acc, const pg8::Unit& u, int wr, int wc, int fr, int fq) const {
;     ...
;             const int col = (pn - 24) * 128 + cl;
; #pragma unroll
;             for (int ai = 0; ai < 2; ++ai)
; #pragma unroll
;                 for (int m = 0; m < 4; ++m) {
;                     const f32x4 a = acc[ai][0][m][0] * acc[ai][1][m][0], b = acc[ai][0][m][1] * acc[ai][1][m][1];
;                     u32x4 w; w.x = cvt_pk_bf16(a[0], a[1]); w.y = cvt_pk_bf16(a[2], a[3]); w.z = cvt_pk_bf16(b[0], b[1]); w.w = cvt_pk_bf16(b[2], b[3]);
;                     *(u32x4*)(P + (size_t)(row0 + ai * 128 + m * 16) * 1024 + col) = w;
;                 }
	v_pk_mul_f32 v[130:131], v[126:127], v[62:63]
	v_pk_mul_f32 v[128:129], v[124:125], v[60:61]
	v_pk_mul_f32 v[132:133], v[122:123], v[58:59]
	v_ashrrev_i32_e32 v155, 31, v154
	v_lshl_add_u32 v144, s66, 7, v161
	v_pk_mul_f32 v[134:135], v[120:121], v[56:57]
	v_cvt_pk_bf16_f32 v128, v128, v129
	v_cvt_pk_bf16_f32 v129, v130, v131
	v_cvt_pk_bf16_f32 v131, v132, v133
	v_lshlrev_b64 v[132:133], 11, v[154:155]
	v_cvt_pk_bf16_f32 v130, v134, v135
	v_lshl_add_u64 v[132:133], s[8:9], 0, v[132:133]
	v_lshlrev_b64 v[134:135], 1, v[144:145]
	v_lshl_add_u64 v[132:133], v[132:133], 0, v[134:135]
	global_store_dwordx4 v[132:133], v[128:131], off
	v_pk_mul_f32 v[156:157], v[114:115], v[50:51]
	v_pk_mul_f32 v[158:159], v[112:113], v[48:49]
	v_pk_mul_f32 v[130:131], v[118:119], v[54:55]
	v_pk_mul_f32 v[128:129], v[116:117], v[52:53]
	s_mov_b32 s0, 0x40000
	v_cvt_pk_bf16_f32 v128, v128, v129
	v_cvt_pk_bf16_f32 v129, v130, v131
	v_cvt_pk_bf16_f32 v131, v156, v157
	v_or_b32_e32 v156, 16, v154
	v_ashrrev_i32_e32 v157, 31, v156
	v_lshlrev_b64 v[156:157], 11, v[156:157]
	v_lshl_add_u64 v[156:157], s[8:9], 0, v[156:157]
	v_cvt_pk_bf16_f32 v130, v158, v159
	v_lshl_add_u64 v[156:157], v[156:157], 0, v[134:135]
	global_store_dwordx4 v[156:157], v[128:131], off
	v_pk_mul_f32 v[156:157], v[106:107], v[42:43]
	v_pk_mul_f32 v[158:159], v[104:105], v[40:41]
	v_pk_mul_f32 v[130:131], v[110:111], v[46:47]
	v_pk_mul_f32 v[128:129], v[108:109], v[44:45]
	s_nop 0
	v_cvt_pk_bf16_f32 v128, v128, v129
	v_cvt_pk_bf16_f32 v129, v130, v131
	v_cvt_pk_bf16_f32 v131, v156, v157
	v_or_b32_e32 v156, 32, v154
	v_ashrrev_i32_e32 v157, 31, v156
	v_lshlrev_b64 v[156:157], 11, v[156:157]
	v_lshl_add_u64 v[156:157], s[8:9], 0, v[156:157]
	v_cvt_pk_bf16_f32 v130, v158, v159
	v_lshl_add_u64 v[156:157], v[156:157], 0, v[134:135]
	global_store_dwordx4 v[156:157], v[128:131], off
	v_pk_mul_f32 v[156:157], v[98:99], v[34:35]
	v_pk_mul_f32 v[158:159], v[96:97], v[32:33]
	v_pk_mul_f32 v[130:131], v[102:103], v[38:39]
	v_pk_mul_f32 v[128:129], v[100:101], v[36:37]
	s_nop 0
	v_cvt_pk_bf16_f32 v128, v128, v129
	v_cvt_pk_bf16_f32 v129, v130, v131
	v_cvt_pk_bf16_f32 v131, v156, v157
	v_or_b32_e32 v156, 48, v154
	v_ashrrev_i32_e32 v157, 31, v156
	v_lshlrev_b64 v[156:157], 11, v[156:157]
	v_lshl_add_u64 v[156:157], s[8:9], 0, v[156:157]
	v_cvt_pk_bf16_f32 v130, v158, v159
	v_lshl_add_u64 v[134:135], v[156:157], 0, v[134:135]
	global_store_dwordx4 v[134:135], v[128:131], off
	v_pk_mul_f32 v[134:135], v[90:91], v[26:27]
	v_pk_mul_f32 v[156:157], v[88:89], v[24:25]
	v_pk_mul_f32 v[130:131], v[94:95], v[30:31]
	v_pk_mul_f32 v[128:129], v[92:93], v[28:29]
	s_nop 0
	v_cvt_pk_bf16_f32 v128, v128, v129
	v_cvt_pk_bf16_f32 v129, v130, v131
	v_cvt_pk_bf16_f32 v131, v134, v135
	v_add_co_u32_e32 v134, vcc, s0, v132
	v_cvt_pk_bf16_f32 v130, v156, v157
	s_nop 0
	v_addc_co_u32_e32 v135, vcc, 0, v133, vcc
	global_store_dwordx4 v[134:135], v[128:131], off
	v_pk_mul_f32 v[134:135], v[82:83], v[18:19]
	s_mov_b32 s0, 0x48000
	v_pk_mul_f32 v[130:131], v[86:87], v[22:23]
	v_pk_mul_f32 v[128:129], v[84:85], v[20:21]
	v_pk_mul_f32 v[156:157], v[80:81], v[16:17]
	v_cvt_pk_bf16_f32 v128, v128, v129
	v_cvt_pk_bf16_f32 v129, v130, v131
	v_cvt_pk_bf16_f32 v131, v134, v135
	v_add_co_u32_e32 v134, vcc, s0, v132
	v_cvt_pk_bf16_f32 v130, v156, v157
	s_nop 0
	v_addc_co_u32_e32 v135, vcc, 0, v133, vcc
	global_store_dwordx4 v[134:135], v[128:131], off
	v_pk_mul_f32 v[134:135], v[74:75], v[10:11]
	s_mov_b32 s0, 0x50000
	v_pk_mul_f32 v[130:131], v[78:79], v[14:15]
	v_pk_mul_f32 v[128:129], v[76:77], v[12:13]
	v_pk_mul_f32 v[156:157], v[72:73], v[8:9]
	v_cvt_pk_bf16_f32 v128, v128, v129
	v_cvt_pk_bf16_f32 v129, v130, v131
	v_cvt_pk_bf16_f32 v131, v134, v135
	v_add_co_u32_e32 v134, vcc, s0, v132
	v_cvt_pk_bf16_f32 v130, v156, v157
	s_nop 0
	v_addc_co_u32_e32 v135, vcc, 0, v133, vcc
	global_store_dwordx4 v[134:135], v[128:131], off
	v_pk_mul_f32 v[134:135], v[66:67], v[2:3]
	v_pk_mul_f32 v[156:157], v[64:65], v[0:1]
	v_pk_mul_f32 v[130:131], v[70:71], v[6:7]
	v_pk_mul_f32 v[128:129], v[68:69], v[4:5]
	v_add_co_u32_e32 v132, vcc, 0x58000, v132
	v_cvt_pk_bf16_f32 v128, v128, v129
	v_cvt_pk_bf16_f32 v129, v130, v131
	v_cvt_pk_bf16_f32 v130, v156, v157
	v_cvt_pk_bf16_f32 v131, v134, v135
	v_addc_co_u32_e32 v133, vcc, 0, v133, vcc
	global_store_dwordx4 v[132:133], v[128:131], off

; #define PG8_STAGE(bufoff, gbase, voff) do { _Pragma("unroll") for (int _i = 0; _i < 2; ++_i) \
;         __builtin_amdgcn_global_load_lds((const unsigned*)((const char*)(gbase) + (voff)[_i]), (PG8_LAS unsigned*)(lds + (bufoff) + ldsw + _i * 8192), 16, 0, 0); } while (0)
; #define PG8_WAIT_V(n) asm volatile("s_waitcnt vmcnt(" #n ")" ::: "memory")
; #define PG8_BAR __builtin_amdgcn_s_barrier()
; template <class Epi, class Sched>
; __device__ __forceinline__ void gemm_phase(PG8_LAS unsigned char* lds, const Gemm g, const Sched& S, const Epi& E) {
;     const int tid = threadIdx.x, wid = __builtin_amdgcn_readfirstlane(tid >> 6), lane = tid & 63, wr = wid >> 2, wc = wid & 3, fr = lane & 15, fq = lane >> 4;
;     const int K = g.K, nt = K / BK;
;     unsigned voffA[2], voffB[2];
; #pragma unroll
;     for (int i = 0; i < 2; ++i) { int R, C; stage_rc(tid * 16 + i * 8192, R, C); const int Rb = Epi::PERM ? ((R & ~31) + perm32(R & 31)) : R;
;         voffA[i] = (unsigned)(R * K + C) * 2u; voffB[i] = (unsigned)(Rb * K + C) * 2u; }
;     const size_t kstep = (size_t)(BK * 2);
;     const size_t hstep = (size_t)HALF * K * 2;
;     const size_t tstep = 2 * hstep;
;     const unsigned ldsw = (unsigned)wid * 1024u;
;     const int aoff = lds_byte(wr * 64 + fr, fq * 8), boff = lds_byte(wc * 32 + fr, fq * 8);
;     ...
;     PG8_STAGE(PG8_SB(0, 0), cB, voffB); PG8_STAGE(PG8_SA(0, 0), cA, voffA); PG8_STAGE(PG8_SB(0, 1), cB + hstep, voffB); PG8_STAGE(PG8_SA(0, 1), cA + hstep, voffA);
;     if (wr == 1) PG8_BAR;
;     PG8_WAIT_V(4); PG8_BAR;
;     PG8_STAGE(PG8_SB(1, 0), cB + kstep, voffB); PG8_STAGE(PG8_SA(1, 0), cA + kstep, voffA); PG8_STAGE(PG8_SB(1, 1), cB + hstep + kstep, voffB);
;     PG8_WAIT_V(6); PG8_BAR;
.LBB0_658:
	s_add_u32 s0, s58, 0xfc86000
	s_addc_u32 s1, s59, 0
	s_lshl_b32 s4, s4, 5
	s_and_b32 s10, s4, 0x60
	s_mov_b64 s[4:5], 0x80
	s_add_i32 m0, s29, 0x18000
	v_lshl_add_u64 v[6:7], v[6:7], 0, s[4:5]
	s_lshl_b32 s8, s3, 13
	s_lshl_b32 s11, s10, 7
	s_waitcnt vmcnt(2)
	s_barrier
	global_load_lds_dwordx4 v[6:7], off
	v_lshl_add_u64 v[4:5], v[4:5], 0, s[4:5]
	s_add_i32 m0, s29, 0x1a000
	s_add_i32 s50, s29, 0x8000
	s_add_i32 s51, s29, 0xa000
	global_load_lds_dwordx4 v[4:5], off
	v_lshl_add_u64 v[2:3], v[2:3], 0, s[4:5]
	s_mov_b32 m0, s50
	s_add_u32 s6, s34, 0x80080
	global_load_lds_dwordx4 v[2:3], off
	v_lshl_add_u64 v[0:1], v[0:1], 0, s[4:5]
	s_mov_b32 m0, s51
	s_addc_u32 s7, s35, 0
	global_load_lds_dwordx4 v[0:1], off
	s_add_i32 m0, s29, 0x1c000
	v_lshl_add_u64 v[0:1], s[6:7], 0, v[146:147]
	global_load_lds_dwordx4 v[0:1], off
	v_lshl_add_u64 v[0:1], s[6:7], 0, v[150:151]
	s_add_i32 m0, s29, 0x1e000
	s_sext_i32_i8 s69, s2
	global_load_lds_dwordx4 v[0:1], off
	v_and_b32_e32 v0, 15, v242
	v_lshlrev_b32_e32 v1, 1, v11
	v_lshlrev_b32_e32 v2, 2, v242
	v_lshlrev_b32_e32 v3, 6, v242
	s_movk_i32 s2, 0x3c0
	v_lshl_or_b32 v166, s3, 6, v0
	v_lshl_or_b32 v0, v0, 6, v1
	v_and_b32_e32 v2, 32, v2
	v_and_or_b32 v1, v3, s2, v1
	v_bitop3_b32 v167, s11, v1, v2 bitop3:0xf6
	v_lshlrev_b32_e32 v1, 9, v242
	v_bitop3_b32 v0, v0, s8, v2 bitop3:0xde
	v_and_b32_e32 v1, 0x70000, v1
	v_lshlrev_b32_e32 v2, 12, v10
	v_or3_b32 v1, v8, v1, v2
	v_add_u32_e32 v152, v1, v9
	v_lshlrev_b32_e32 v1, 5, v12
	s_waitcnt vmcnt(6)
	v_and_b32_e32 v1, 0xf0000, v1
	v_or3_b32 v1, v8, v1, v2
	s_add_i32 s66, 0, 0x10000
	s_add_i32 s67, 0, 0x14000
	s_ashr_i32 s64, s62, 31
	s_mov_b32 s65, s62
	v_or_b32_e32 v168, s10, v11
	v_mov_b32_e32 v153, v147
	v_add_u32_e32 v154, v1, v9
	v_mov_b32_e32 v155, v147
	v_mov_b64_e32 v[156:157], 0x400
	v_mov_b64_e32 v[158:159], 0x3ff
	v_add_u32_e32 v169, s66, v167
	v_add_u32_e32 v170, 0, v0
	v_add_u32_e32 v171, s67, v167
	s_mov_b64 s[6:7], 0x6a04000
	s_mov_b32 s68, 0x6a04000
	s_mov_b32 s8, 0x3f9837f0
	s_barrier

; #define PG8_STAGE(bufoff, gbase, voff) do { _Pragma("unroll") for (int _i = 0; _i < 2; ++_i) \
;         __builtin_amdgcn_global_load_lds((const unsigned*)((const char*)(gbase) + (voff)[_i]), (PG8_LAS unsigned*)(lds + (bufoff) + ldsw + _i * 8192), 16, 0, 0); } while (0)
; #define PG8_LDA(dst, b, h) do { _Pragma("unroll") for (int m = 0; m < 4; ++m) _Pragma("unroll") for (int k = 0; k < 2; ++k) dst[m][k] = *(const PG8_LAS bf16x8*)(lds + PG8_SA(b, h) + aoff + m * 2048 + k * 1024); } while (0)
; #define PG8_LDB(dst, b, h) do { _Pragma("unroll") for (int n = 0; n < 2; ++n) _Pragma("unroll") for (int k = 0; k < 2; ++k) dst[n][k] = *(const PG8_LAS bf16x8*)(lds + PG8_SB(b, h) + boff + n * 2048 + k * 1024); } while (0)
; #define PG8_MMA(ai, bj, At, Bt) do { __builtin_amdgcn_s_setprio(1); _Pragma("unroll") for (int m = 0; m < 4; ++m) _Pragma("unroll") for (int n = 0; n < 2; ++n) _Pragma("unroll") for (int k = 0; k < 2; ++k) \
;         acc[ai][bj][m][n] = __builtin_amdgcn_mfma_f32_16x16x32_bf16(Bt[n][k], At[m][k], acc[ai][bj][m][n], 0, 0, 0); __builtin_amdgcn_s_setprio(0); } while (0)
; #define PG8_WAIT_L(n) asm volatile("s_waitcnt lgkmcnt(" #n ")" ::: "memory")
; #define PG8_BAR __builtin_amdgcn_s_barrier()
; #define PG8_SCHED __builtin_amdgcn_sched_barrier(0)
; template <class Epi, class Sched>
; __device__ __forceinline__ void gemm_phase(PG8_LAS unsigned char* lds, const Gemm g, const Sched& S, const Epi& E) {
;     ...
;             const bool last = (t == nt - 2);
;             const char* a1 = cA + (size_t)(t + 1) * kstep;
;             const char* a2 = last ? nA : cA + (size_t)(t + 2) * kstep; const char* b2 = last ? nB : cB + (size_t)(t + 2) * kstep;
;             const char* a3 = a2 + kstep; const char* b3 = b2 + kstep;
;             if (last && has_next) S.a_ready(nxt);
;             PG8_LDB(B0, 0, 0); PG8_SCHED; PG8_LDA(At, 0, 0); PG8_STAGE(PG8_SA(1, 1), a1 + hstep, voffA);
;             PG8_WAIT_L(8); PG8_BAR; PG8_WAIT_L(0); PG8_MMA(0, 0, At, B0); PG8_BAR; PG8_SCHED;
;             PG8_LDB(B1, 0, 1); PG8_STAGE(PG8_SB(0, 0), b2, voffB);
;             PG8_BAR; PG8_WAIT_L(0); PG8_MMA(0, 1, At, B1); PG8_BAR;
;             PG8_LDA(At, 0, 1); PG8_STAGE(PG8_SA(0, 0), a2, voffA);
;             PG8_BAR; PG8_WAIT_L(0); PG8_MMA(1, 0, At, B0); PG8_BAR; PG8_SCHED;
;             PG8_STAGE(PG8_SB(0, 1), b2 + hstep, voffB);
.LBB0_666:
	ds_read_b128 v[128:131], v169
	ds_read_b128 v[132:135], v169 offset:1024
	ds_read_b128 v[136:139], v169 offset:2048
	ds_read_b128 v[140:143], v169 offset:3072
	ds_read_b128 v[160:163], v170
	ds_read_b128 v[172:175], v170 offset:1024
	ds_read_b128 v[176:179], v170 offset:2048
	ds_read_b128 v[180:183], v170 offset:3072
	ds_read_b128 v[184:187], v170 offset:4096
	ds_read_b128 v[188:191], v170 offset:5120
	ds_read_b128 v[192:195], v170 offset:6144
	ds_read_b128 v[196:199], v170 offset:7168
	ds_read_b128 v[200:203], v171
	ds_read_b128 v[204:207], v171 offset:1024
	ds_read_b128 v[208:211], v171 offset:2048
	ds_read_b128 v[212:215], v171 offset:3072
	s_add_u32 s10, s30, 0xfff80080
	s_addc_u32 s11, s31, -1
	s_cmp_eq_u32 s74, 28
	s_cselect_b32 s39, s19, s11
	s_cselect_b32 s38, s70, s10
	s_cselect_b32 s35, s17, s73
	s_cselect_b32 s34, s71, s72
	v_lshl_add_u64 v[164:165], s[30:31], 0, v[152:153]
	s_add_i32 m0, s29, 0xc000
	s_nop 0
	global_load_lds_dwordx4 v[164:165], off
	v_lshl_add_u64 v[164:165], s[30:31], 0, v[154:155]
	s_add_i32 m0, s29, 0xe000
	s_nop 0
	global_load_lds_dwordx4 v[164:165], off
	s_waitcnt vmcnt(8)
	s_waitcnt lgkmcnt(0)
	s_barrier
	s_setprio 1
	v_mfma_f32_16x16x32_bf16 v[120:123], v[128:131], v[160:163], v[120:123]
	v_mfma_f32_16x16x32_bf16 v[124:127], v[136:139], v[160:163], v[124:127]
	v_mfma_f32_16x16x32_bf16 v[112:115], v[128:131], v[176:179], v[112:115]
	v_mfma_f32_16x16x32_bf16 v[116:119], v[136:139], v[176:179], v[116:119]
	v_mfma_f32_16x16x32_bf16 v[96:99], v[128:131], v[184:187], v[96:99]
	v_mfma_f32_16x16x32_bf16 v[88:91], v[136:139], v[184:187], v[88:91]
	v_mfma_f32_16x16x32_bf16 v[80:83], v[128:131], v[192:195], v[80:83]
	v_mfma_f32_16x16x32_bf16 v[72:75], v[136:139], v[192:195], v[72:75]
	v_mfma_f32_16x16x32_bf16 v[120:123], v[132:135], v[172:175], v[120:123]
	v_mfma_f32_16x16x32_bf16 v[124:127], v[140:143], v[172:175], v[124:127]
	v_mfma_f32_16x16x32_bf16 v[112:115], v[132:135], v[180:183], v[112:115]
	v_mfma_f32_16x16x32_bf16 v[116:119], v[140:143], v[180:183], v[116:119]
	v_mfma_f32_16x16x32_bf16 v[96:99], v[132:135], v[188:191], v[96:99]
	v_mfma_f32_16x16x32_bf16 v[88:91], v[140:143], v[188:191], v[88:91]
	v_mfma_f32_16x16x32_bf16 v[80:83], v[132:135], v[196:199], v[80:83]
	v_mfma_f32_16x16x32_bf16 v[72:75], v[140:143], v[196:199], v[72:75]
	v_mfma_f32_16x16x32_bf16 v[108:111], v[200:203], v[160:163], v[108:111]
	v_mfma_f32_16x16x32_bf16 v[104:107], v[208:211], v[160:163], v[104:107]
	v_mfma_f32_16x16x32_bf16 v[100:103], v[200:203], v[176:179], v[100:103]
	v_mfma_f32_16x16x32_bf16 v[92:95], v[208:211], v[176:179], v[92:95]
	v_mfma_f32_16x16x32_bf16 v[84:87], v[200:203], v[184:187], v[84:87]
	v_mfma_f32_16x16x32_bf16 v[76:79], v[208:211], v[184:187], v[76:79]
	v_mfma_f32_16x16x32_bf16 v[68:71], v[200:203], v[192:195], v[68:71]
	v_mfma_f32_16x16x32_bf16 v[64:67], v[208:211], v[192:195], v[64:67]
	v_mfma_f32_16x16x32_bf16 v[108:111], v[204:207], v[172:175], v[108:111]
	v_mfma_f32_16x16x32_bf16 v[104:107], v[212:215], v[172:175], v[104:107]
	v_mfma_f32_16x16x32_bf16 v[100:103], v[204:207], v[180:183], v[100:103]
	v_mfma_f32_16x16x32_bf16 v[92:95], v[212:215], v[180:183], v[92:95]
	v_mfma_f32_16x16x32_bf16 v[84:87], v[204:207], v[188:191], v[84:87]
	v_mfma_f32_16x16x32_bf16 v[76:79], v[212:215], v[188:191], v[76:79]
	v_mfma_f32_16x16x32_bf16 v[68:71], v[204:207], v[196:199], v[68:71]
	v_mfma_f32_16x16x32_bf16 v[64:67], v[212:215], v[196:199], v[64:67]
	s_setprio 0
	s_barrier
	ds_read_b128 v[160:163], v170 offset:16384
	ds_read_b128 v[172:175], v170 offset:17408
	ds_read_b128 v[176:179], v170 offset:18432
	ds_read_b128 v[180:183], v170 offset:19456
	ds_read_b128 v[184:187], v170 offset:20480
	ds_read_b128 v[188:191], v170 offset:21504
	ds_read_b128 v[192:195], v170 offset:22528
	ds_read_b128 v[196:199], v170 offset:23552
	s_add_i32 s10, s66, s45
	v_lshl_add_u64 v[164:165], s[34:35], 0, v[146:147]
	s_mov_b32 m0, s10
	s_nop 0
	global_load_lds_dwordx4 v[164:165], off
	v_lshl_add_u64 v[216:217], s[34:35], 0, v[150:151]
	s_add_i32 m0, s10, 0x2000
	s_nop 0
	global_load_lds_dwordx4 v[216:217], off
	s_mov_b32 m0, s29
	v_lshl_add_u64 v[218:219], s[38:39], 0, v[144:145]
	global_load_lds_dwordx4 v[218:219], off
	v_lshl_add_u64 v[220:221], s[38:39], 0, v[148:149]
	s_mov_b32 m0, s46
	s_nop 0
	global_load_lds_dwordx4 v[220:221], off
	s_add_u32 s10, s34, 0x80000
	s_addc_u32 s11, s35, 0
	s_add_i32 s33, s67, s45
	v_lshl_add_u64 v[246:247], s[10:11], 0, v[146:147]
	s_mov_b32 m0, s33
	s_nop 0
	global_load_lds_dwordx4 v[246:247], off
	v_lshl_add_u64 v[246:247], s[10:11], 0, v[150:151]
	s_add_i32 m0, s33, 0x2000
	s_nop 0
	global_load_lds_dwordx4 v[246:247], off
	s_waitcnt vmcnt(8)
	s_waitcnt lgkmcnt(0)
	s_barrier
; #define PG8_STAGE(bufoff, gbase, voff) do { _Pragma("unroll") for (int _i = 0; _i < 2; ++_i) \
;         __builtin_amdgcn_global_load_lds((const unsigned*)((const char*)(gbase) + (voff)[_i]), (PG8_LAS unsigned*)(lds + (bufoff) + ldsw + _i * 8192), 16, 0, 0); } while (0)
; #define PG8_LDA(dst, b, h) do { _Pragma("unroll") for (int m = 0; m < 4; ++m) _Pragma("unroll") for (int k = 0; k < 2; ++k) dst[m][k] = *(const PG8_LAS bf16x8*)(lds + PG8_SA(b, h) + aoff + m * 2048 + k * 1024); } while (0)
; #define PG8_LDB(dst, b, h) do { _Pragma("unroll") for (int n = 0; n < 2; ++n) _Pragma("unroll") for (int k = 0; k < 2; ++k) dst[n][k] = *(const PG8_LAS bf16x8*)(lds + PG8_SB(b, h) + boff + n * 2048 + k * 1024); } while (0)
; #define PG8_MMA(ai, bj, At, Bt) do { __builtin_amdgcn_s_setprio(1); _Pragma("unroll") for (int m = 0; m < 4; ++m) _Pragma("unroll") for (int n = 0; n < 2; ++n) _Pragma("unroll") for (int k = 0; k < 2; ++k) \
;         acc[ai][bj][m][n] = __builtin_amdgcn_mfma_f32_16x16x32_bf16(Bt[n][k], At[m][k], acc[ai][bj][m][n], 0, 0, 0); __builtin_amdgcn_s_setprio(0); } while (0)
; #define PG8_WAIT_V(n) asm volatile("s_waitcnt vmcnt(" #n ")" ::: "memory")
; #define PG8_WAIT_L(n) asm volatile("s_waitcnt lgkmcnt(" #n ")" ::: "memory")
; #define PG8_BAR __builtin_amdgcn_s_barrier()
; #define PG8_SCHED __builtin_amdgcn_sched_barrier(0)
; template <class Epi, class Sched>
; __device__ __forceinline__ void gemm_phase(PG8_LAS unsigned char* lds, const Gemm g, const Sched& S, const Epi& E) {
;     ...
;             PG8_BAR; PG8_WAIT_L(0); PG8_MMA(1, 0, At, B0); PG8_BAR; PG8_SCHED;
;             PG8_STAGE(PG8_SB(0, 1), b2 + hstep, voffB);
;             PG8_WAIT_V(6); PG8_BAR; PG8_MMA(1, 1, At, B1); PG8_BAR;
;             PG8_LDB(B0, 1, 0); PG8_SCHED; PG8_LDA(At, 1, 0); PG8_STAGE(PG8_SA(0, 1), a2 + hstep, voffA);
;             PG8_WAIT_L(8); PG8_BAR; PG8_WAIT_L(0); PG8_MMA(0, 0, At, B0); PG8_BAR; PG8_SCHED;
;             PG8_LDB(B1, 1, 1); PG8_STAGE(PG8_SB(1, 0), b3, voffB);
;             PG8_BAR; PG8_WAIT_L(0); PG8_MMA(0, 1, At, B1); PG8_BAR;
	s_setprio 1
	v_mfma_f32_16x16x32_bf16 v[60:63], v[128:131], v[160:163], v[60:63]
	v_mfma_f32_16x16x32_bf16 v[56:59], v[136:139], v[160:163], v[56:59]
	v_mfma_f32_16x16x32_bf16 v[48:51], v[128:131], v[176:179], v[48:51]
	v_mfma_f32_16x16x32_bf16 v[40:43], v[136:139], v[176:179], v[40:43]
	v_mfma_f32_16x16x32_bf16 v[32:35], v[128:131], v[184:187], v[32:35]
	v_mfma_f32_16x16x32_bf16 v[24:27], v[136:139], v[184:187], v[24:27]
	v_mfma_f32_16x16x32_bf16 v[16:19], v[128:131], v[192:195], v[16:19]
	v_mfma_f32_16x16x32_bf16 v[8:11], v[136:139], v[192:195], v[8:11]
	v_mfma_f32_16x16x32_bf16 v[60:63], v[132:135], v[172:175], v[60:63]
	v_mfma_f32_16x16x32_bf16 v[56:59], v[140:143], v[172:175], v[56:59]
	v_mfma_f32_16x16x32_bf16 v[48:51], v[132:135], v[180:183], v[48:51]
	v_mfma_f32_16x16x32_bf16 v[40:43], v[140:143], v[180:183], v[40:43]
	v_mfma_f32_16x16x32_bf16 v[32:35], v[132:135], v[188:191], v[32:35]
	v_mfma_f32_16x16x32_bf16 v[24:27], v[140:143], v[188:191], v[24:27]
	v_mfma_f32_16x16x32_bf16 v[16:19], v[132:135], v[196:199], v[16:19]
	v_mfma_f32_16x16x32_bf16 v[8:11], v[140:143], v[196:199], v[8:11]
	v_mfma_f32_16x16x32_bf16 v[52:55], v[200:203], v[160:163], v[52:55]
	v_mfma_f32_16x16x32_bf16 v[44:47], v[208:211], v[160:163], v[44:47]
	v_mfma_f32_16x16x32_bf16 v[36:39], v[200:203], v[176:179], v[36:39]
	v_mfma_f32_16x16x32_bf16 v[28:31], v[208:211], v[176:179], v[28:31]
	v_mfma_f32_16x16x32_bf16 v[20:23], v[200:203], v[184:187], v[20:23]
	v_mfma_f32_16x16x32_bf16 v[12:15], v[208:211], v[184:187], v[12:15]
	v_mfma_f32_16x16x32_bf16 v[4:7], v[200:203], v[192:195], v[4:7]
	v_mfma_f32_16x16x32_bf16 v[0:3], v[208:211], v[192:195], v[0:3]
	v_mfma_f32_16x16x32_bf16 v[52:55], v[204:207], v[172:175], v[52:55]
	v_mfma_f32_16x16x32_bf16 v[44:47], v[212:215], v[172:175], v[44:47]
	v_mfma_f32_16x16x32_bf16 v[36:39], v[204:207], v[180:183], v[36:39]
	v_mfma_f32_16x16x32_bf16 v[28:31], v[212:215], v[180:183], v[28:31]
	v_mfma_f32_16x16x32_bf16 v[20:23], v[204:207], v[188:191], v[20:23]
	v_mfma_f32_16x16x32_bf16 v[12:15], v[212:215], v[188:191], v[12:15]
	v_mfma_f32_16x16x32_bf16 v[4:7], v[204:207], v[196:199], v[4:7]
	v_mfma_f32_16x16x32_bf16 v[0:3], v[212:215], v[196:199], v[0:3]
	s_setprio 0
	s_add_i32 s33, 0, 0x18000
	s_barrier
	ds_read_b128 v[128:131], v169 offset:32768
	ds_read_b128 v[132:135], v169 offset:33792
	ds_read_b128 v[136:139], v169 offset:34816
	ds_read_b128 v[140:143], v169 offset:35840
	ds_read_b128 v[160:163], v170 offset:32768
	ds_read_b128 v[172:175], v170 offset:33792
	ds_read_b128 v[176:179], v170 offset:34816
	ds_read_b128 v[180:183], v170 offset:35840
	ds_read_b128 v[184:187], v170 offset:36864
	ds_read_b128 v[188:191], v170 offset:37888
	ds_read_b128 v[192:195], v170 offset:38912
	ds_read_b128 v[196:199], v170 offset:39936
	ds_read_b128 v[200:203], v171 offset:32768
	ds_read_b128 v[204:207], v171 offset:33792
	ds_read_b128 v[208:211], v171 offset:34816
	ds_read_b128 v[212:215], v171 offset:35840
	s_add_u32 s10, s38, 0x80000
	s_addc_u32 s11, s39, 0
	s_mov_b32 m0, s47
	v_lshl_add_u64 v[246:247], s[10:11], 0, v[144:145]
	global_load_lds_dwordx4 v[246:247], off
	v_lshl_add_u64 v[246:247], s[10:11], 0, v[148:149]
	s_mov_b32 m0, s48
	s_nop 0
	global_load_lds_dwordx4 v[246:247], off
	s_waitcnt vmcnt(8)
	s_waitcnt lgkmcnt(0)
	s_barrier
	s_setprio 1
	v_mfma_f32_16x16x32_bf16 v[120:123], v[128:131], v[160:163], v[120:123]
	v_mfma_f32_16x16x32_bf16 v[124:127], v[136:139], v[160:163], v[124:127]
	v_mfma_f32_16x16x32_bf16 v[112:115], v[128:131], v[176:179], v[112:115]
	v_mfma_f32_16x16x32_bf16 v[116:119], v[136:139], v[176:179], v[116:119]
	v_mfma_f32_16x16x32_bf16 v[96:99], v[128:131], v[184:187], v[96:99]
	v_mfma_f32_16x16x32_bf16 v[88:91], v[136:139], v[184:187], v[88:91]
	v_mfma_f32_16x16x32_bf16 v[80:83], v[128:131], v[192:195], v[80:83]
	v_mfma_f32_16x16x32_bf16 v[72:75], v[136:139], v[192:195], v[72:75]
	v_mfma_f32_16x16x32_bf16 v[120:123], v[132:135], v[172:175], v[120:123]
	v_mfma_f32_16x16x32_bf16 v[124:127], v[140:143], v[172:175], v[124:127]
	v_mfma_f32_16x16x32_bf16 v[112:115], v[132:135], v[180:183], v[112:115]
	v_mfma_f32_16x16x32_bf16 v[116:119], v[140:143], v[180:183], v[116:119]
	v_mfma_f32_16x16x32_bf16 v[96:99], v[132:135], v[188:191], v[96:99]
	v_mfma_f32_16x16x32_bf16 v[88:91], v[140:143], v[188:191], v[88:91]
	v_mfma_f32_16x16x32_bf16 v[80:83], v[132:135], v[196:199], v[80:83]
	v_mfma_f32_16x16x32_bf16 v[72:75], v[140:143], v[196:199], v[72:75]
	v_mfma_f32_16x16x32_bf16 v[108:111], v[200:203], v[160:163], v[108:111]
	v_mfma_f32_16x16x32_bf16 v[104:107], v[208:211], v[160:163], v[104:107]
	v_mfma_f32_16x16x32_bf16 v[100:103], v[200:203], v[176:179], v[100:103]
	v_mfma_f32_16x16x32_bf16 v[92:95], v[208:211], v[176:179], v[92:95]
	v_mfma_f32_16x16x32_bf16 v[84:87], v[200:203], v[184:187], v[84:87]
	v_mfma_f32_16x16x32_bf16 v[76:79], v[208:211], v[184:187], v[76:79]
	v_mfma_f32_16x16x32_bf16 v[68:71], v[200:203], v[192:195], v[68:71]
	v_mfma_f32_16x16x32_bf16 v[64:67], v[208:211], v[192:195], v[64:67]
	v_mfma_f32_16x16x32_bf16 v[108:111], v[204:207], v[172:175], v[108:111]
	v_mfma_f32_16x16x32_bf16 v[104:107], v[212:215], v[172:175], v[104:107]
	v_mfma_f32_16x16x32_bf16 v[100:103], v[204:207], v[180:183], v[100:103]
	v_mfma_f32_16x16x32_bf16 v[92:95], v[212:215], v[180:183], v[92:95]
	v_mfma_f32_16x16x32_bf16 v[84:87], v[204:207], v[188:191], v[84:87]
	v_mfma_f32_16x16x32_bf16 v[76:79], v[212:215], v[188:191], v[76:79]
	v_mfma_f32_16x16x32_bf16 v[68:71], v[204:207], v[196:199], v[68:71]
	v_mfma_f32_16x16x32_bf16 v[64:67], v[212:215], v[196:199], v[64:67]
	s_setprio 0
	s_barrier
; #define PG8_STAGE(bufoff, gbase, voff) do { _Pragma("unroll") for (int _i = 0; _i < 2; ++_i) \
;         __builtin_amdgcn_global_load_lds((const unsigned*)((const char*)(gbase) + (voff)[_i]), (PG8_LAS unsigned*)(lds + (bufoff) + ldsw + _i * 8192), 16, 0, 0); } while (0)
; #define PG8_LDA(dst, b, h) do { _Pragma("unroll") for (int m = 0; m < 4; ++m) _Pragma("unroll") for (int k = 0; k < 2; ++k) dst[m][k] = *(const PG8_LAS bf16x8*)(lds + PG8_SA(b, h) + aoff + m * 2048 + k * 1024); } while (0)
; #define PG8_MMA(ai, bj, At, Bt) do { __builtin_amdgcn_s_setprio(1); _Pragma("unroll") for (int m = 0; m < 4; ++m) _Pragma("unroll") for (int n = 0; n < 2; ++n) _Pragma("unroll") for (int k = 0; k < 2; ++k) \
;         acc[ai][bj][m][n] = __builtin_amdgcn_mfma_f32_16x16x32_bf16(Bt[n][k], At[m][k], acc[ai][bj][m][n], 0, 0, 0); __builtin_amdgcn_s_setprio(0); } while (0)
; #define PG8_WAIT_V(n) asm volatile("s_waitcnt vmcnt(" #n ")" ::: "memory")
; #define PG8_WAIT_L(n) asm volatile("s_waitcnt lgkmcnt(" #n ")" ::: "memory")
; template <class Epi, class Sched>
; __device__ __forceinline__ void gemm_phase(PG8_LAS unsigned char* lds, const Gemm g, const Sched& S, const Epi& E) {
;     ...
;             PG8_LDA(At, 1, 1); PG8_STAGE(PG8_SA(1, 0), a3, voffA);
;             PG8_BAR; PG8_WAIT_L(0); PG8_MMA(1, 0, At, B0); PG8_BAR; PG8_SCHED;
;             PG8_STAGE(PG8_SB(1, 1), b3 + hstep, voffB);
;             PG8_WAIT_V(6); PG8_BAR; PG8_MMA(1, 1, At, B1); PG8_BAR;
;         }
;     __device__ __forceinline__ void operator()(const AccT& acc, const pg8::Unit& u, int wr, int wc, int fr, int fq) const {
;         const int row0 = u.pm * 256 + wr * 64 + fr, col0 = u.pn * 256 + wc * 32 + 8 * fq;
;         const float* ga = mod + (u.pm >= 64 ? 12288 : 0) + 2 * 2048;
;         f32x4 gv[2][2];
; #pragma unroll
;         for (int bj = 0; bj < 2; ++bj)
; #pragma unroll
;             for (int n = 0; n < 2; ++n) gv[bj][n] = *(const f32x4*)(ga + col0 + bj * 128 + n * 4);
; #pragma unroll
;         for (int ai = 0; ai < 2; ++ai) {
;             f32x4 xa[4][2], xb[4][2];
; #pragma unroll
;             for (int m = 0; m < 4; ++m) { const size_t off = (size_t)(row0 + ai * 128 + m * 16) * D + col0;
; #pragma unroll
;                 for (int bj = 0; bj < 2; ++bj) { xa[m][bj] = *(const f32x4*)(x + off + bj * 128); xb[m][bj] = *(const f32x4*)(x + off + bj * 128 + 4); } }
	ds_read_b128 v[160:163], v170 offset:49152
	ds_read_b128 v[172:175], v170 offset:50176
	ds_read_b128 v[176:179], v170 offset:51200
	ds_read_b128 v[180:183], v170 offset:52224
	ds_read_b128 v[184:187], v170 offset:53248
	ds_read_b128 v[188:191], v170 offset:54272
	ds_read_b128 v[192:195], v170 offset:55296
	ds_read_b128 v[196:199], v170 offset:56320
	s_add_i32 s38, 0, 0x1c000
	s_add_i32 s10, s33, s45
	v_lshl_add_u64 v[164:165], v[164:165], 0, s[4:5]
	s_mov_b32 m0, s10
	s_nop 0
	global_load_lds_dwordx4 v[164:165], off
	v_lshl_add_u64 v[164:165], v[216:217], 0, s[4:5]
	s_add_i32 m0, s10, 0x2000
	s_nop 0
	global_load_lds_dwordx4 v[164:165], off
	s_mov_b32 m0, s50
	v_lshl_add_u64 v[164:165], v[218:219], 0, s[4:5]
	global_load_lds_dwordx4 v[164:165], off
	v_lshl_add_u64 v[164:165], v[220:221], 0, s[4:5]
	s_mov_b32 m0, s51
	s_nop 0
	global_load_lds_dwordx4 v[164:165], off
	s_add_u32 s10, s34, 0x80080
	s_addc_u32 s11, s35, 0
	s_add_i32 s33, s38, s45
	v_lshl_add_u64 v[246:247], s[10:11], 0, v[146:147]
	s_mov_b32 m0, s33
	s_nop 0
	global_load_lds_dwordx4 v[246:247], off
	v_lshl_add_u64 v[246:247], s[10:11], 0, v[150:151]
	s_add_i32 m0, s33, 0x2000
	s_nop 0
	global_load_lds_dwordx4 v[246:247], off
	s_waitcnt vmcnt(8)
	s_waitcnt lgkmcnt(0)
	s_barrier
	s_setprio 1
	v_mfma_f32_16x16x32_bf16 v[60:63], v[128:131], v[160:163], v[60:63]
	v_mfma_f32_16x16x32_bf16 v[56:59], v[136:139], v[160:163], v[56:59]
	v_mfma_f32_16x16x32_bf16 v[48:51], v[128:131], v[176:179], v[48:51]
	v_mfma_f32_16x16x32_bf16 v[40:43], v[136:139], v[176:179], v[40:43]
	v_mfma_f32_16x16x32_bf16 v[32:35], v[128:131], v[184:187], v[32:35]
	v_mfma_f32_16x16x32_bf16 v[24:27], v[136:139], v[184:187], v[24:27]
	v_mfma_f32_16x16x32_bf16 v[16:19], v[128:131], v[192:195], v[16:19]
	v_mfma_f32_16x16x32_bf16 v[8:11], v[136:139], v[192:195], v[8:11]
	v_mfma_f32_16x16x32_bf16 v[60:63], v[132:135], v[172:175], v[60:63]
	v_mfma_f32_16x16x32_bf16 v[56:59], v[140:143], v[172:175], v[56:59]
	v_mfma_f32_16x16x32_bf16 v[48:51], v[132:135], v[180:183], v[48:51]
	v_mfma_f32_16x16x32_bf16 v[40:43], v[140:143], v[180:183], v[40:43]
	v_mfma_f32_16x16x32_bf16 v[32:35], v[132:135], v[188:191], v[32:35]
	v_mfma_f32_16x16x32_bf16 v[24:27], v[140:143], v[188:191], v[24:27]
	v_mfma_f32_16x16x32_bf16 v[16:19], v[132:135], v[196:199], v[16:19]
	v_mfma_f32_16x16x32_bf16 v[8:11], v[140:143], v[196:199], v[8:11]
	v_mfma_f32_16x16x32_bf16 v[52:55], v[200:203], v[160:163], v[52:55]
	v_mfma_f32_16x16x32_bf16 v[44:47], v[208:211], v[160:163], v[44:47]
	v_mfma_f32_16x16x32_bf16 v[36:39], v[200:203], v[176:179], v[36:39]
	v_mfma_f32_16x16x32_bf16 v[28:31], v[208:211], v[176:179], v[28:31]
	v_mfma_f32_16x16x32_bf16 v[20:23], v[200:203], v[184:187], v[20:23]
	v_mfma_f32_16x16x32_bf16 v[12:15], v[208:211], v[184:187], v[12:15]
	v_mfma_f32_16x16x32_bf16 v[4:7], v[200:203], v[192:195], v[4:7]
	v_mfma_f32_16x16x32_bf16 v[0:3], v[208:211], v[192:195], v[0:3]
	v_mfma_f32_16x16x32_bf16 v[52:55], v[204:207], v[172:175], v[52:55]
	v_mfma_f32_16x16x32_bf16 v[44:47], v[212:215], v[172:175], v[44:47]
	v_mfma_f32_16x16x32_bf16 v[36:39], v[204:207], v[180:183], v[36:39]
	v_mfma_f32_16x16x32_bf16 v[28:31], v[212:215], v[180:183], v[28:31]
	v_mfma_f32_16x16x32_bf16 v[20:23], v[204:207], v[188:191], v[20:23]
	v_mfma_f32_16x16x32_bf16 v[12:15], v[212:215], v[188:191], v[12:15]
	v_mfma_f32_16x16x32_bf16 v[4:7], v[204:207], v[196:199], v[4:7]
	v_mfma_f32_16x16x32_bf16 v[0:3], v[212:215], v[196:199], v[0:3]
	s_setprio 0
	s_add_i32 s74, s74, 2
	s_add_u32 s30, s30, 0x100
	s_addc_u32 s31, s31, 0
	s_add_u32 s72, s72, 0x100
	s_addc_u32 s73, s73, 0
	s_cmp_gt_u32 s74, 29
	s_barrier
	s_cbranch_scc0 .LBB0_666
	v_lshl_or_b32 v160, s69, 8, v168
	s_cmp_gt_i32 s28, 63
	v_ashrrev_i32_e32 v161, 31, v160
	v_lshl_add_u32 v164, s28, 8, v166
	s_cselect_b32 s10, 0xc000, 0
	v_lshlrev_b64 v[128:129], 2, v[160:161]
	v_ashrrev_i32_e32 v165, 31, v164
	s_add_u32 s10, s58, s10
	v_lshl_add_u64 v[162:163], s[36:37], 0, v[128:129]
	v_lshlrev_b64 v[130:131], 13, v[164:165]
	v_or_b32_e32 v220, 16, v164
	s_addc_u32 s11, s59, 0
	v_lshl_add_u64 v[130:131], v[162:163], 0, v[130:131]
	v_ashrrev_i32_e32 v221, 31, v220
	global_load_dwordx4 v[172:175], v[130:131], off offset:16
	global_load_dwordx4 v[176:179], v[130:131], off
	global_load_dwordx4 v[180:183], v[130:131], off offset:528
	global_load_dwordx4 v[184:187], v[130:131], off offset:512
	v_lshlrev_b64 v[130:131], 13, v[220:221]
	v_lshl_add_u64 v[128:129], s[10:11], 0, v[128:129]
	v_lshl_add_u64 v[200:201], v[162:163], 0, v[130:131]
	v_lshl_add_u64 v[130:131], v[128:129], 0, s[6:7]
	global_load_dwordx4 v[188:191], v[200:201], off offset:16
	global_load_dwordx4 v[192:195], v[200:201], off
	global_load_dwordx4 v[136:139], v[130:131], off offset:16
	global_load_dwordx4 v[132:135], v[130:131], off offset:512
	v_add_co_u32_e32 v128, vcc, s68, v128
	v_or_b32_e32 v236, 32, v164
	s_nop 0
	v_addc_co_u32_e32 v129, vcc, 0, v129, vcc
	global_load_dwordx4 v[140:143], v[128:129], off
	s_nop 0
	global_load_dwordx4 v[128:131], v[130:131], off offset:528
	s_nop 0
	global_load_dwordx4 v[196:199], v[200:201], off offset:512
	s_nop 0
	global_load_dwordx4 v[200:203], v[200:201], off offset:528
	v_ashrrev_i32_e32 v237, 31, v236
	v_lshlrev_b64 v[204:205], 13, v[236:237]
	v_lshl_add_u64 v[216:217], v[162:163], 0, v[204:205]
	global_load_dwordx4 v[204:207], v[216:217], off
	global_load_dwordx4 v[208:211], v[216:217], off offset:16
	global_load_dwordx4 v[212:215], v[216:217], off offset:528
	s_nop 0
	global_load_dwordx4 v[216:219], v[216:217], off offset:512
	v_or_b32_e32 v238, 48, v164
	v_ashrrev_i32_e32 v239, 31, v238
	v_lshlrev_b64 v[222:223], 12, v[164:165]
	v_lshlrev_b64 v[224:225], 13, v[238:239]
	v_lshlrev_b64 v[160:161], 1, v[160:161]
	v_lshl_add_u64 v[222:223], s[0:1], 0, v[222:223]
	v_lshl_add_u64 v[232:233], v[162:163], 0, v[224:225]
	v_lshlrev_b64 v[240:241], 12, v[220:221]
	v_lshl_add_u64 v[244:245], v[222:223], 0, v[160:161]
	global_load_dwordx4 v[220:223], v[232:233], off offset:16
	global_load_dwordx4 v[224:227], v[232:233], off
	global_load_dwordx4 v[228:231], v[232:233], off offset:528
	s_nop 0
	global_load_dwordx4 v[232:235], v[232:233], off offset:512
	s_and_b64 vcc, exec, s[2:3]
	s_mov_b32 s69, s16
	s_mov_b32 s28, s18
	s_mov_b64 s[34:35], s[26:27]
	s_mov_b64 s[30:31], s[20:21]
	s_waitcnt vmcnt(0)
;     __device__ __forceinline__ void operator()(const AccT& acc, const pg8::Unit& u, int wr, int wc, int fr, int fq) const {
;     ...
;             for (int m = 0; m < 4; ++m) { const size_t off = (size_t)(row0 + ai * 128 + m * 16) * D + col0;
; #pragma unroll
;                 for (int bj = 0; bj < 2; ++bj) {
;                     const f32x4 a = ALPHA * xa[m][bj] + gv[bj][0] * acc[ai][bj][m][0], b = ALPHA * xb[m][bj] + gv[bj][1] * acc[ai][bj][m][1];
;                     u32x4 w; w.x = pk_h2(a[0], a[1]); w.y = pk_h2(a[2], a[3]); w.z = pk_h2(b[0], b[1]); w.w = pk_h2(b[2], b[3]);
;                     *(u32x4*)(U1 + off + bj * 128) = w; } }
	v_pk_mul_f32 v[174:175], v[174:175], s[8:9] op_sel_hi:[1,0]
	v_pk_mul_f32 v[178:179], v[178:179], s[8:9] op_sel_hi:[1,0]
	v_pk_mul_f32 v[176:177], v[176:177], s[8:9] op_sel_hi:[1,0]
	v_pk_mul_f32 v[172:173], v[172:173], s[8:9] op_sel_hi:[1,0]
	v_pk_mul_f32 v[186:187], v[186:187], s[8:9] op_sel_hi:[1,0]
	v_pk_mul_f32 v[184:185], v[184:185], s[8:9] op_sel_hi:[1,0]
	v_pk_mul_f32 v[182:183], v[182:183], s[8:9] op_sel_hi:[1,0]
	v_pk_mul_f32 v[180:181], v[180:181], s[8:9] op_sel_hi:[1,0]
	v_pk_mul_f32 v[194:195], v[194:195], s[8:9] op_sel_hi:[1,0]
	v_pk_fma_f32 v[126:127], v[126:127], v[138:139], v[174:175]
	v_pk_fma_f32 v[124:125], v[124:125], v[136:137], v[172:173]
	v_pk_mul_f32 v[192:193], v[192:193], s[8:9] op_sel_hi:[1,0]
	v_pk_mul_f32 v[190:191], v[190:191], s[8:9] op_sel_hi:[1,0]
	v_pk_fma_f32 v[122:123], v[122:123], v[142:143], v[178:179]
	v_pk_fma_f32 v[120:121], v[120:121], v[140:141], v[176:177]
	v_pk_mul_f32 v[188:189], v[188:189], s[8:9] op_sel_hi:[1,0]
	v_pk_fma_f32 v[172:173], v[110:111], v[134:135], v[186:187]
	v_pk_fma_f32 v[110:111], v[108:109], v[132:133], v[184:185]
	v_cvt_pk_f16_f32 v108, v124, v125
	v_cvt_pk_f16_f32 v109, v126, v127
	v_pk_fma_f32 v[124:125], v[106:107], v[130:131], v[182:183]
	v_pk_fma_f32 v[104:105], v[104:105], v[128:129], v[180:181]
	v_cvt_pk_f16_f32 v106, v120, v121
	v_cvt_pk_f16_f32 v107, v122, v123
	v_pk_fma_f32 v[118:119], v[118:119], v[138:139], v[190:191]
	v_pk_fma_f32 v[116:117], v[116:117], v[136:137], v[188:189]
	v_cvt_pk_f16_f32 v110, v110, v111
	v_cvt_pk_f16_f32 v111, v172, v173
	v_pk_fma_f32 v[114:115], v[114:115], v[142:143], v[194:195]
	v_pk_fma_f32 v[126:127], v[112:113], v[140:141], v[192:193]
	v_cvt_pk_f16_f32 v112, v104, v105
	v_cvt_pk_f16_f32 v113, v124, v125
	global_store_dwordx4 v[244:245], v[106:109], off
	global_store_dwordx4 v[244:245], v[110:113], off offset:256
	v_cvt_pk_f16_f32 v104, v126, v127
	v_lshl_add_u64 v[108:109], s[0:1], 0, v[240:241]
	v_cvt_pk_f16_f32 v105, v114, v115
	v_cvt_pk_f16_f32 v106, v116, v117
	v_cvt_pk_f16_f32 v107, v118, v119
	v_lshl_add_u64 v[108:109], v[108:109], 0, v[160:161]
	global_store_dwordx4 v[108:109], v[104:107], off
	v_add_u32_e32 v172, 0x80, v164
	v_ashrrev_i32_e32 v173, 31, v172
	v_pk_mul_f32 v[104:105], v[198:199], s[8:9] op_sel_hi:[1,0]
	v_pk_mul_f32 v[106:107], v[196:197], s[8:9] op_sel_hi:[1,0]
	v_pk_fma_f32 v[102:103], v[102:103], v[134:135], v[104:105]
	v_pk_fma_f32 v[100:101], v[100:101], v[132:133], v[106:107]
	v_pk_mul_f32 v[104:105], v[202:203], s[8:9] op_sel_hi:[1,0]
	v_pk_mul_f32 v[106:107], v[200:201], s[8:9] op_sel_hi:[1,0]
	v_pk_fma_f32 v[104:105], v[94:95], v[130:131], v[104:105]
	v_pk_fma_f32 v[94:95], v[92:93], v[128:129], v[106:107]
	v_cvt_pk_f16_f32 v92, v100, v101
	v_cvt_pk_f16_f32 v93, v102, v103
	v_cvt_pk_f16_f32 v94, v94, v95
	v_cvt_pk_f16_f32 v95, v104, v105
	global_store_dwordx4 v[108:109], v[92:95], off offset:256
	v_pk_mul_f32 v[100:101], v[204:205], s[8:9] op_sel_hi:[1,0]
	v_add_u32_e32 v174, 0x90, v164
	v_pk_mul_f32 v[94:95], v[206:207], s[8:9] op_sel_hi:[1,0]
	v_lshlrev_b64 v[92:93], 12, v[236:237]
	v_pk_fma_f32 v[94:95], v[98:99], v[142:143], v[94:95]
	v_pk_fma_f32 v[96:97], v[96:97], v[140:141], v[100:101]
	v_pk_mul_f32 v[98:99], v[210:211], s[8:9] op_sel_hi:[1,0]
	v_pk_mul_f32 v[100:101], v[208:209], s[8:9] op_sel_hi:[1,0]
	v_pk_fma_f32 v[98:99], v[90:91], v[138:139], v[98:99]
	v_pk_fma_f32 v[90:91], v[88:89], v[136:137], v[100:101]
	v_lshl_add_u64 v[92:93], s[0:1], 0, v[92:93]
	v_cvt_pk_f16_f32 v88, v96, v97
	v_cvt_pk_f16_f32 v89, v94, v95
	v_cvt_pk_f16_f32 v90, v90, v91
	v_cvt_pk_f16_f32 v91, v98, v99
	v_lshl_add_u64 v[92:93], v[92:93], 0, v[160:161]
	global_store_dwordx4 v[92:93], v[88:91], off
	v_ashrrev_i32_e32 v175, 31, v174
	v_add_u32_e32 v176, 0xa0, v164
	v_pk_mul_f32 v[88:89], v[218:219], s[8:9] op_sel_hi:[1,0]
	v_pk_mul_f32 v[90:91], v[216:217], s[8:9] op_sel_hi:[1,0]
	v_pk_fma_f32 v[86:87], v[86:87], v[134:135], v[88:89]
	v_pk_fma_f32 v[84:85], v[84:85], v[132:133], v[90:91]
	v_pk_mul_f32 v[88:89], v[214:215], s[8:9] op_sel_hi:[1,0]
	v_pk_mul_f32 v[90:91], v[212:213], s[8:9] op_sel_hi:[1,0]
	v_pk_fma_f32 v[88:89], v[78:79], v[130:131], v[88:89]
	v_pk_fma_f32 v[78:79], v[76:77], v[128:129], v[90:91]
	v_cvt_pk_f16_f32 v76, v84, v85
	v_cvt_pk_f16_f32 v77, v86, v87
	v_cvt_pk_f16_f32 v78, v78, v79
	v_cvt_pk_f16_f32 v79, v88, v89
	global_store_dwordx4 v[92:93], v[76:79], off offset:256
	v_pk_mul_f32 v[84:85], v[224:225], s[8:9] op_sel_hi:[1,0]
	v_ashrrev_i32_e32 v177, 31, v176
	v_pk_mul_f32 v[78:79], v[226:227], s[8:9] op_sel_hi:[1,0]
	v_lshlrev_b64 v[76:77], 12, v[238:239]
	v_pk_fma_f32 v[78:79], v[82:83], v[142:143], v[78:79]
	v_pk_fma_f32 v[80:81], v[80:81], v[140:141], v[84:85]
	v_pk_mul_f32 v[82:83], v[222:223], s[8:9] op_sel_hi:[1,0]
	v_pk_mul_f32 v[84:85], v[220:221], s[8:9] op_sel_hi:[1,0]
	v_pk_fma_f32 v[82:83], v[74:75], v[138:139], v[82:83]
	v_pk_fma_f32 v[74:75], v[72:73], v[136:137], v[84:85]
	v_lshl_add_u64 v[76:77], s[0:1], 0, v[76:77]
	v_cvt_pk_f16_f32 v72, v80, v81
	v_cvt_pk_f16_f32 v73, v78, v79
	v_cvt_pk_f16_f32 v74, v74, v75
	v_cvt_pk_f16_f32 v75, v82, v83
	v_lshl_add_u64 v[76:77], v[76:77], 0, v[160:161]
	global_store_dwordx4 v[76:77], v[72:75], off
	v_lshlrev_b64 v[80:81], 13, v[174:175]
	v_lshl_add_u64 v[92:93], v[162:163], 0, v[80:81]
	v_pk_mul_f32 v[72:73], v[234:235], s[8:9] op_sel_hi:[1,0]
	v_pk_mul_f32 v[74:75], v[232:233], s[8:9] op_sel_hi:[1,0]
	v_pk_fma_f32 v[70:71], v[70:71], v[134:135], v[72:73]
	v_pk_fma_f32 v[68:69], v[68:69], v[132:133], v[74:75]
	v_pk_mul_f32 v[72:73], v[230:231], s[8:9] op_sel_hi:[1,0]
	v_pk_mul_f32 v[74:75], v[228:229], s[8:9] op_sel_hi:[1,0]
;     __device__ __forceinline__ void operator()(const AccT& acc, const pg8::Unit& u, int wr, int wc, int fr, int fq) const {
;     ...
;             for (int m = 0; m < 4; ++m) { const size_t off = (size_t)(row0 + ai * 128 + m * 16) * D + col0;
; #pragma unroll
;                 for (int bj = 0; bj < 2; ++bj) { xa[m][bj] = *(const f32x4*)(x + off + bj * 128); xb[m][bj] = *(const f32x4*)(x + off + bj * 128 + 4); } }
; #pragma unroll
;             for (int m = 0; m < 4; ++m) { const size_t off = (size_t)(row0 + ai * 128 + m * 16) * D + col0;
; #pragma unroll
;                 for (int bj = 0; bj < 2; ++bj) {
;                     const f32x4 a = ALPHA * xa[m][bj] + gv[bj][0] * acc[ai][bj][m][0], b = ALPHA * xb[m][bj] + gv[bj][1] * acc[ai][bj][m][1];
;                     u32x4 w; w.x = pk_h2(a[0], a[1]); w.y = pk_h2(a[2], a[3]); w.z = pk_h2(b[0], b[1]); w.w = pk_h2(b[2], b[3]);
;                     *(u32x4*)(U1 + off + bj * 128) = w; } }
	v_pk_fma_f32 v[72:73], v[66:67], v[130:131], v[72:73]
	v_pk_fma_f32 v[66:67], v[64:65], v[128:129], v[74:75]
	v_cvt_pk_f16_f32 v64, v68, v69
	v_cvt_pk_f16_f32 v65, v70, v71
	v_cvt_pk_f16_f32 v66, v66, v67
	v_cvt_pk_f16_f32 v67, v72, v73
	global_store_dwordx4 v[76:77], v[64:67], off offset:256
	v_lshlrev_b64 v[96:97], 13, v[176:177]
	v_lshl_add_u64 v[108:109], v[162:163], 0, v[96:97]
	v_lshlrev_b64 v[64:65], 13, v[172:173]
	v_lshl_add_u64 v[76:77], v[162:163], 0, v[64:65]
	global_load_dwordx4 v[64:67], v[76:77], off
	global_load_dwordx4 v[68:71], v[76:77], off offset:16
	global_load_dwordx4 v[72:75], v[76:77], off offset:512
	s_nop 0
	global_load_dwordx4 v[76:79], v[76:77], off offset:528
	s_nop 0
	global_load_dwordx4 v[80:83], v[92:93], off
	global_load_dwordx4 v[84:87], v[92:93], off offset:16
	global_load_dwordx4 v[88:91], v[92:93], off offset:512
	s_nop 0
	global_load_dwordx4 v[92:95], v[92:93], off offset:528
	s_nop 0
	global_load_dwordx4 v[96:99], v[108:109], off
	global_load_dwordx4 v[100:103], v[108:109], off offset:16
	global_load_dwordx4 v[104:107], v[108:109], off offset:528
	s_nop 0
	global_load_dwordx4 v[108:111], v[108:109], off offset:512
	v_add_u32_e32 v164, 0xb0, v164
	v_ashrrev_i32_e32 v165, 31, v164
	v_lshlrev_b64 v[112:113], 13, v[164:165]
	v_lshl_add_u64 v[124:125], v[162:163], 0, v[112:113]
	global_load_dwordx4 v[112:115], v[124:125], off offset:16
	global_load_dwordx4 v[116:119], v[124:125], off
	global_load_dwordx4 v[120:123], v[124:125], off offset:528
	s_nop 0
	global_load_dwordx4 v[124:127], v[124:125], off offset:512
	v_lshlrev_b64 v[162:163], 12, v[172:173]
	s_waitcnt vmcnt(0)
; #define PG8_WAIT_V(n) asm volatile("s_waitcnt vmcnt(" #n ")" ::: "memory")
; #define PG8_BAR __builtin_amdgcn_s_barrier()
; template <class Epi, class Sched>
; __device__ __forceinline__ void gemm_phase(PG8_LAS unsigned char* lds, const Gemm g, const Sched& S, const Epi& E) {
;     ...
;         if (!has_next) break;
; #pragma unroll
;         for (int a = 0; a < 2; ++a)
; #pragma unroll
;             for (int b = 0; b < 2; ++b)
; #pragma unroll
;                 for (int m = 0; m < 4; ++m)
; #pragma unroll
;                     for (int n = 0; n < 2; ++n) acc[a][b][m][n] = (f32x4){0.f, 0.f, 0.f, 0.f};
;         cur = nxt; cA = nA; cB = nB; ++ui;
;     }
;     PG8_WAIT_V(0);
;     if (wr == 0) PG8_BAR;
;     __device__ __forceinline__ void operator()(const AccT& acc, const pg8::Unit& u, int wr, int wc, int fr, int fq) const {
;     ...
;             for (int m = 0; m < 4; ++m) { const size_t off = (size_t)(row0 + ai * 128 + m * 16) * D + col0;
; #pragma unroll
;                 for (int bj = 0; bj < 2; ++bj) {
;                     const f32x4 a = ALPHA * xa[m][bj] + gv[bj][0] * acc[ai][bj][m][0], b = ALPHA * xb[m][bj] + gv[bj][1] * acc[ai][bj][m][1];
;                     u32x4 w; w.x = pk_h2(a[0], a[1]); w.y = pk_h2(a[2], a[3]); w.z = pk_h2(b[0], b[1]); w.w = pk_h2(b[2], b[3]);
;                     *(u32x4*)(U1 + off + bj * 128) = w; } }
	v_pk_mul_f32 v[66:67], v[66:67], s[8:9] op_sel_hi:[1,0]
	v_pk_mul_f32 v[64:65], v[64:65], s[8:9] op_sel_hi:[1,0]
	v_pk_fma_f32 v[62:63], v[62:63], v[142:143], v[66:67]
	v_pk_fma_f32 v[60:61], v[60:61], v[140:141], v[64:65]
	v_pk_mul_f32 v[64:65], v[70:71], s[8:9] op_sel_hi:[1,0]
	v_pk_mul_f32 v[66:67], v[68:69], s[8:9] op_sel_hi:[1,0]
	v_pk_fma_f32 v[64:65], v[58:59], v[138:139], v[64:65]
	v_pk_fma_f32 v[58:59], v[56:57], v[136:137], v[66:67]
	v_cvt_pk_f16_f32 v56, v60, v61
	v_lshl_add_u64 v[60:61], s[0:1], 0, v[162:163]
	v_cvt_pk_f16_f32 v57, v62, v63
	v_cvt_pk_f16_f32 v58, v58, v59
	v_cvt_pk_f16_f32 v59, v64, v65
	v_lshl_add_u64 v[60:61], v[60:61], 0, v[160:161]
	global_store_dwordx4 v[60:61], v[56:59], off
	s_nop 1
	v_pk_mul_f32 v[56:57], v[74:75], s[8:9] op_sel_hi:[1,0]
	v_pk_mul_f32 v[58:59], v[72:73], s[8:9] op_sel_hi:[1,0]
	v_pk_fma_f32 v[54:55], v[54:55], v[134:135], v[56:57]
	v_pk_fma_f32 v[52:53], v[52:53], v[132:133], v[58:59]
	v_pk_mul_f32 v[56:57], v[78:79], s[8:9] op_sel_hi:[1,0]
	v_pk_mul_f32 v[58:59], v[76:77], s[8:9] op_sel_hi:[1,0]
	v_pk_fma_f32 v[56:57], v[46:47], v[130:131], v[56:57]
	v_pk_fma_f32 v[46:47], v[44:45], v[128:129], v[58:59]
	v_cvt_pk_f16_f32 v44, v52, v53
	v_cvt_pk_f16_f32 v45, v54, v55
	v_cvt_pk_f16_f32 v46, v46, v47
	v_cvt_pk_f16_f32 v47, v56, v57
	global_store_dwordx4 v[60:61], v[44:47], off offset:256
	v_pk_mul_f32 v[52:53], v[80:81], s[8:9] op_sel_hi:[1,0]
	s_nop 0
	v_pk_mul_f32 v[46:47], v[82:83], s[8:9] op_sel_hi:[1,0]
	v_lshlrev_b64 v[44:45], 12, v[174:175]
	v_pk_fma_f32 v[46:47], v[50:51], v[142:143], v[46:47]
	v_pk_fma_f32 v[48:49], v[48:49], v[140:141], v[52:53]
	v_pk_mul_f32 v[50:51], v[86:87], s[8:9] op_sel_hi:[1,0]
	v_pk_mul_f32 v[52:53], v[84:85], s[8:9] op_sel_hi:[1,0]
	v_pk_fma_f32 v[50:51], v[42:43], v[138:139], v[50:51]
	v_pk_fma_f32 v[42:43], v[40:41], v[136:137], v[52:53]
	v_lshl_add_u64 v[44:45], s[0:1], 0, v[44:45]
	v_cvt_pk_f16_f32 v40, v48, v49
	v_cvt_pk_f16_f32 v41, v46, v47
	v_cvt_pk_f16_f32 v42, v42, v43
	v_cvt_pk_f16_f32 v43, v50, v51
	v_lshl_add_u64 v[44:45], v[44:45], 0, v[160:161]
	global_store_dwordx4 v[44:45], v[40:43], off
	s_nop 1
	v_pk_mul_f32 v[40:41], v[90:91], s[8:9] op_sel_hi:[1,0]
	v_pk_mul_f32 v[42:43], v[88:89], s[8:9] op_sel_hi:[1,0]
	v_pk_fma_f32 v[38:39], v[38:39], v[134:135], v[40:41]
	v_pk_fma_f32 v[36:37], v[36:37], v[132:133], v[42:43]
	v_pk_mul_f32 v[40:41], v[94:95], s[8:9] op_sel_hi:[1,0]
	v_pk_mul_f32 v[42:43], v[92:93], s[8:9] op_sel_hi:[1,0]
	v_pk_fma_f32 v[40:41], v[30:31], v[130:131], v[40:41]
	v_pk_fma_f32 v[30:31], v[28:29], v[128:129], v[42:43]
	v_cvt_pk_f16_f32 v28, v36, v37
	v_cvt_pk_f16_f32 v29, v38, v39
	v_cvt_pk_f16_f32 v30, v30, v31
	v_cvt_pk_f16_f32 v31, v40, v41
	global_store_dwordx4 v[44:45], v[28:31], off offset:256
	v_pk_mul_f32 v[36:37], v[96:97], s[8:9] op_sel_hi:[1,0]
	s_nop 0
	v_pk_mul_f32 v[30:31], v[98:99], s[8:9] op_sel_hi:[1,0]
	v_lshlrev_b64 v[28:29], 12, v[176:177]
	v_pk_fma_f32 v[30:31], v[34:35], v[142:143], v[30:31]
	v_pk_fma_f32 v[32:33], v[32:33], v[140:141], v[36:37]
	v_pk_mul_f32 v[34:35], v[102:103], s[8:9] op_sel_hi:[1,0]
	v_pk_mul_f32 v[36:37], v[100:101], s[8:9] op_sel_hi:[1,0]
	v_pk_fma_f32 v[34:35], v[26:27], v[138:139], v[34:35]
	v_pk_fma_f32 v[26:27], v[24:25], v[136:137], v[36:37]
	v_lshl_add_u64 v[28:29], s[0:1], 0, v[28:29]
	v_cvt_pk_f16_f32 v24, v32, v33
	v_cvt_pk_f16_f32 v25, v30, v31
	v_cvt_pk_f16_f32 v26, v26, v27
	v_cvt_pk_f16_f32 v27, v34, v35
	v_lshl_add_u64 v[28:29], v[28:29], 0, v[160:161]
	global_store_dwordx4 v[28:29], v[24:27], off
	s_nop 1
	v_pk_mul_f32 v[24:25], v[110:111], s[8:9] op_sel_hi:[1,0]
	v_pk_mul_f32 v[26:27], v[108:109], s[8:9] op_sel_hi:[1,0]
	v_pk_fma_f32 v[22:23], v[22:23], v[134:135], v[24:25]
	v_pk_fma_f32 v[20:21], v[20:21], v[132:133], v[26:27]
	v_pk_mul_f32 v[24:25], v[106:107], s[8:9] op_sel_hi:[1,0]
	v_pk_mul_f32 v[26:27], v[104:105], s[8:9] op_sel_hi:[1,0]
	v_pk_fma_f32 v[24:25], v[14:15], v[130:131], v[24:25]
	v_pk_fma_f32 v[14:15], v[12:13], v[128:129], v[26:27]
	v_cvt_pk_f16_f32 v12, v20, v21
	v_cvt_pk_f16_f32 v13, v22, v23
	v_cvt_pk_f16_f32 v14, v14, v15
	v_cvt_pk_f16_f32 v15, v24, v25
	global_store_dwordx4 v[28:29], v[12:15], off offset:256
	v_pk_mul_f32 v[20:21], v[116:117], s[8:9] op_sel_hi:[1,0]
	s_nop 0
	v_pk_mul_f32 v[14:15], v[118:119], s[8:9] op_sel_hi:[1,0]
	v_lshlrev_b64 v[12:13], 12, v[164:165]
	v_pk_fma_f32 v[14:15], v[18:19], v[142:143], v[14:15]
	v_pk_fma_f32 v[16:17], v[16:17], v[140:141], v[20:21]
	v_pk_mul_f32 v[18:19], v[114:115], s[8:9] op_sel_hi:[1,0]
	v_pk_mul_f32 v[20:21], v[112:113], s[8:9] op_sel_hi:[1,0]
	v_pk_fma_f32 v[18:19], v[10:11], v[138:139], v[18:19]
	v_pk_fma_f32 v[10:11], v[8:9], v[136:137], v[20:21]
	v_lshl_add_u64 v[12:13], s[0:1], 0, v[12:13]
	v_cvt_pk_f16_f32 v8, v16, v17
	v_cvt_pk_f16_f32 v9, v14, v15
	v_cvt_pk_f16_f32 v10, v10, v11
	v_cvt_pk_f16_f32 v11, v18, v19
	v_lshl_add_u64 v[12:13], v[12:13], 0, v[160:161]
	global_store_dwordx4 v[12:13], v[8:11], off
	s_nop 1
	v_pk_mul_f32 v[8:9], v[126:127], s[8:9] op_sel_hi:[1,0]
	v_pk_mul_f32 v[10:11], v[124:125], s[8:9] op_sel_hi:[1,0]
	v_pk_fma_f32 v[6:7], v[6:7], v[134:135], v[8:9]
	v_pk_fma_f32 v[4:5], v[4:5], v[132:133], v[10:11]
	v_pk_mul_f32 v[8:9], v[122:123], s[8:9] op_sel_hi:[1,0]
	v_pk_mul_f32 v[10:11], v[120:121], s[8:9] op_sel_hi:[1,0]
	v_pk_fma_f32 v[8:9], v[2:3], v[130:131], v[8:9]
	v_pk_fma_f32 v[2:3], v[0:1], v[128:129], v[10:11]
	v_cvt_pk_f16_f32 v0, v4, v5
	v_cvt_pk_f16_f32 v1, v6, v7
	v_cvt_pk_f16_f32 v2, v2, v3
	v_cvt_pk_f16_f32 v3, v8, v9
	global_store_dwordx4 v[12:13], v[0:3], off offset:256
	s_cbranch_vccz .LBB0_659
	s_waitcnt vmcnt(0)
	s_cmpk_gt_u32 s9, 0xff
	s_cbranch_scc1 .LBB0_670
	s_barrier

; #define PG8_STAGE(bufoff, gbase, voff) do { _Pragma("unroll") for (int _i = 0; _i < 2; ++_i) \
;         __builtin_amdgcn_global_load_lds((const unsigned*)((const char*)(gbase) + (voff)[_i]), (PG8_LAS unsigned*)(lds + (bufoff) + ldsw + _i * 8192), 16, 0, 0); } while (0)
; #define PG8_WAIT_V(n) asm volatile("s_waitcnt vmcnt(" #n ")" ::: "memory")
; #define PG8_BAR __builtin_amdgcn_s_barrier()
; template <class Epi, class Sched>
; __device__ __forceinline__ void gemm_phase(PG8_LAS unsigned char* lds, const Gemm g, const Sched& S, const Epi& E) {
;     const int tid = threadIdx.x, wid = __builtin_amdgcn_readfirstlane(tid >> 6), lane = tid & 63, wr = wid >> 2, wc = wid & 3, fr = lane & 15, fq = lane >> 4;
;     const int K = g.K, nt = K / BK;
;     unsigned voffA[2], voffB[2];
; #pragma unroll
;     for (int i = 0; i < 2; ++i) { int R, C; stage_rc(tid * 16 + i * 8192, R, C); const int Rb = Epi::PERM ? ((R & ~31) + perm32(R & 31)) : R;
;         voffA[i] = (unsigned)(R * K + C) * 2u; voffB[i] = (unsigned)(Rb * K + C) * 2u; }
;     const size_t kstep = (size_t)(BK * 2);
;     const size_t hstep = (size_t)HALF * K * 2;
;     const size_t tstep = 2 * hstep;
;     const unsigned ldsw = (unsigned)wid * 1024u;
;     const int aoff = lds_byte(wr * 64 + fr, fq * 8), boff = lds_byte(wc * 32 + fr, fq * 8);
;     ...
;     PG8_STAGE(PG8_SB(0, 0), cB, voffB); PG8_STAGE(PG8_SA(0, 0), cA, voffA); PG8_STAGE(PG8_SB(0, 1), cB + hstep, voffB); PG8_STAGE(PG8_SA(0, 1), cA + hstep, voffA);
;     if (wr == 1) PG8_BAR;
;     PG8_WAIT_V(4); PG8_BAR;
;     PG8_STAGE(PG8_SB(1, 0), cB + kstep, voffB); PG8_STAGE(PG8_SA(1, 0), cA + kstep, voffA); PG8_STAGE(PG8_SB(1, 1), cB + hstep + kstep, voffB);
;     PG8_WAIT_V(6); PG8_BAR;
.LBB0_799:
	s_add_u32 s0, s58, 0x1fd86000
	s_addc_u32 s1, s59, 0
	s_lshl_b32 s4, s4, 5
	s_and_b32 s9, s4, 0x60
	s_mov_b64 s[4:5], 0x80
	s_add_i32 m0, s21, 0x18000
	v_lshl_add_u64 v[6:7], v[6:7], 0, s[4:5]
	s_lshl_b32 s8, s3, 13
	s_lshl_b32 s10, s9, 7
	s_waitcnt vmcnt(2)
	s_barrier
	global_load_lds_dwordx4 v[6:7], off
	v_lshl_add_u64 v[4:5], v[4:5], 0, s[4:5]
	s_add_i32 m0, s21, 0x1a000
	s_add_i32 s46, s21, 0x8000
	s_add_i32 s47, s21, 0xa000
	global_load_lds_dwordx4 v[4:5], off
	v_lshl_add_u64 v[2:3], v[2:3], 0, s[4:5]
	s_mov_b32 m0, s46
	s_add_u32 s6, s28, 0x80080
	global_load_lds_dwordx4 v[2:3], off
	v_lshl_add_u64 v[0:1], v[0:1], 0, s[4:5]
	s_mov_b32 m0, s47
	s_addc_u32 s7, s29, 0
	global_load_lds_dwordx4 v[0:1], off
	s_add_i32 m0, s21, 0x1c000
	v_lshl_add_u64 v[0:1], s[6:7], 0, v[132:133]
	global_load_lds_dwordx4 v[0:1], off
	v_lshl_add_u64 v[0:1], s[6:7], 0, v[128:129]
	s_add_i32 m0, s21, 0x1e000
	s_sext_i32_i16 s65, s2
	global_load_lds_dwordx4 v[0:1], off
	v_and_b32_e32 v0, 15, v242
	v_lshlrev_b32_e32 v1, 1, v11
	v_lshlrev_b32_e32 v2, 2, v242
	v_lshlrev_b32_e32 v3, 6, v242
	s_movk_i32 s2, 0x3c0
	v_lshl_or_b32 v144, s3, 6, v0
	v_lshl_or_b32 v0, v0, 6, v1
	v_and_b32_e32 v2, 32, v2
	v_and_or_b32 v1, v3, s2, v1
	v_bitop3_b32 v145, s10, v1, v2 bitop3:0xf6
	v_lshlrev_b32_e32 v1, 9, v242
	v_bitop3_b32 v0, v0, s8, v2 bitop3:0xde
	v_and_b32_e32 v1, 0x70000, v1
	v_lshlrev_b32_e32 v2, 12, v12
	v_or3_b32 v1, v9, v1, v2
	v_add_u32_e32 v136, v1, v10
	v_lshlrev_b32_e32 v1, 5, v8
	s_waitcnt vmcnt(6)
	v_and_b32_e32 v1, 0xf0000, v1
	v_or3_b32 v1, v9, v1, v2
	s_add_i32 s50, 0, 0x10000
	s_add_i32 s51, 0, 0x14000
	s_ashr_i32 s48, s62, 31
	s_mov_b32 s49, s62
	v_or_b32_e32 v146, s9, v11
	v_mov_b32_e32 v137, v133
	v_add_u32_e32 v138, v1, v10
	v_mov_b32_e32 v139, v133
	v_mov_b64_e32 v[140:141], 0x1600
	v_mov_b64_e32 v[142:143], 0x15ff
	v_add_u32_e32 v147, s50, v145
	v_add_u32_e32 v148, 0, v0
	v_add_u32_e32 v149, s51, v145
	s_movk_i32 s64, 0x2c00
	s_barrier

; #define PG8_STAGE(bufoff, gbase, voff) do { _Pragma("unroll") for (int _i = 0; _i < 2; ++_i) \
;         __builtin_amdgcn_global_load_lds((const unsigned*)((const char*)(gbase) + (voff)[_i]), (PG8_LAS unsigned*)(lds + (bufoff) + ldsw + _i * 8192), 16, 0, 0); } while (0)
; #define PG8_LDA(dst, b, h) do { _Pragma("unroll") for (int m = 0; m < 4; ++m) _Pragma("unroll") for (int k = 0; k < 2; ++k) dst[m][k] = *(const PG8_LAS bf16x8*)(lds + PG8_SA(b, h) + aoff + m * 2048 + k * 1024); } while (0)
; #define PG8_LDB(dst, b, h) do { _Pragma("unroll") for (int n = 0; n < 2; ++n) _Pragma("unroll") for (int k = 0; k < 2; ++k) dst[n][k] = *(const PG8_LAS bf16x8*)(lds + PG8_SB(b, h) + boff + n * 2048 + k * 1024); } while (0)
; #define PG8_MMA(ai, bj, At, Bt) do { __builtin_amdgcn_s_setprio(1); _Pragma("unroll") for (int m = 0; m < 4; ++m) _Pragma("unroll") for (int n = 0; n < 2; ++n) _Pragma("unroll") for (int k = 0; k < 2; ++k) \
;         acc[ai][bj][m][n] = __builtin_amdgcn_mfma_f32_16x16x32_bf16(Bt[n][k], At[m][k], acc[ai][bj][m][n], 0, 0, 0); __builtin_amdgcn_s_setprio(0); } while (0)
; #define PG8_WAIT_L(n) asm volatile("s_waitcnt lgkmcnt(" #n ")" ::: "memory")
; #define PG8_BAR __builtin_amdgcn_s_barrier()
; #define PG8_SCHED __builtin_amdgcn_sched_barrier(0)
; template <class Epi, class Sched>
; __device__ __forceinline__ void gemm_phase(PG8_LAS unsigned char* lds, const Gemm g, const Sched& S, const Epi& E) {
;     ...
;             const bool last = (t == nt - 2);
;             const char* a1 = cA + (size_t)(t + 1) * kstep;
;             const char* a2 = last ? nA : cA + (size_t)(t + 2) * kstep; const char* b2 = last ? nB : cB + (size_t)(t + 2) * kstep;
;             const char* a3 = a2 + kstep; const char* b3 = b2 + kstep;
;             if (last && has_next) S.a_ready(nxt);
;             PG8_LDB(B0, 0, 0); PG8_SCHED; PG8_LDA(At, 0, 0); PG8_STAGE(PG8_SA(1, 1), a1 + hstep, voffA);
;             PG8_WAIT_L(8); PG8_BAR; PG8_WAIT_L(0); PG8_MMA(0, 0, At, B0); PG8_BAR; PG8_SCHED;
;             PG8_LDB(B1, 0, 1); PG8_STAGE(PG8_SB(0, 0), b2, voffB);
;             PG8_BAR; PG8_WAIT_L(0); PG8_MMA(0, 1, At, B1); PG8_BAR;
;             PG8_LDA(At, 0, 1); PG8_STAGE(PG8_SA(0, 0), a2, voffA);
;             PG8_BAR; PG8_WAIT_L(0); PG8_MMA(1, 0, At, B0); PG8_BAR; PG8_SCHED;
;             PG8_STAGE(PG8_SB(0, 1), b2 + hstep, voffB);
.LBB0_803:
	ds_read_b128 v[150:153], v147
	ds_read_b128 v[154:157], v147 offset:1024
	ds_read_b128 v[158:161], v147 offset:2048
	ds_read_b128 v[162:165], v147 offset:3072
	ds_read_b128 v[166:169], v148
	ds_read_b128 v[170:173], v148 offset:1024
	ds_read_b128 v[174:177], v148 offset:2048
	ds_read_b128 v[178:181], v148 offset:3072
	ds_read_b128 v[182:185], v148 offset:4096
	ds_read_b128 v[186:189], v148 offset:5120
	ds_read_b128 v[190:193], v148 offset:6144
	ds_read_b128 v[194:197], v148 offset:7168
	ds_read_b128 v[198:201], v149
	ds_read_b128 v[202:205], v149 offset:1024
	ds_read_b128 v[206:209], v149 offset:2048
	ds_read_b128 v[210:213], v149 offset:3072
	s_add_u32 s10, s26, 0xfff80080
	s_addc_u32 s11, s27, -1
	s_cmp_eq_u32 s70, 28
	s_cselect_b32 s31, s9, s11
	s_cselect_b32 s30, s66, s10
	s_cselect_b32 s29, s7, s69
	s_cselect_b32 s28, s67, s68
	v_lshl_add_u64 v[222:223], s[26:27], 0, v[136:137]
	s_add_i32 m0, s21, 0xc000
	s_nop 0
	global_load_lds_dwordx4 v[222:223], off
	v_lshl_add_u64 v[222:223], s[26:27], 0, v[138:139]
	s_add_i32 m0, s21, 0xe000
	s_nop 0
	global_load_lds_dwordx4 v[222:223], off
	s_waitcnt vmcnt(8)
	s_waitcnt lgkmcnt(0)
	s_barrier
	s_setprio 1
	v_mfma_f32_16x16x32_bf16 v[124:127], v[150:153], v[166:169], v[124:127]
	v_mfma_f32_16x16x32_bf16 v[120:123], v[158:161], v[166:169], v[120:123]
	v_mfma_f32_16x16x32_bf16 v[108:111], v[150:153], v[174:177], v[108:111]
	v_mfma_f32_16x16x32_bf16 v[104:107], v[158:161], v[174:177], v[104:107]
	v_mfma_f32_16x16x32_bf16 v[92:95], v[150:153], v[182:185], v[92:95]
	v_mfma_f32_16x16x32_bf16 v[88:91], v[158:161], v[182:185], v[88:91]
	v_mfma_f32_16x16x32_bf16 v[76:79], v[150:153], v[190:193], v[76:79]
	v_mfma_f32_16x16x32_bf16 v[72:75], v[158:161], v[190:193], v[72:75]
	v_mfma_f32_16x16x32_bf16 v[124:127], v[154:157], v[170:173], v[124:127]
	v_mfma_f32_16x16x32_bf16 v[120:123], v[162:165], v[170:173], v[120:123]
	v_mfma_f32_16x16x32_bf16 v[108:111], v[154:157], v[178:181], v[108:111]
	v_mfma_f32_16x16x32_bf16 v[104:107], v[162:165], v[178:181], v[104:107]
	v_mfma_f32_16x16x32_bf16 v[92:95], v[154:157], v[186:189], v[92:95]
	v_mfma_f32_16x16x32_bf16 v[88:91], v[162:165], v[186:189], v[88:91]
	v_mfma_f32_16x16x32_bf16 v[76:79], v[154:157], v[194:197], v[76:79]
	v_mfma_f32_16x16x32_bf16 v[72:75], v[162:165], v[194:197], v[72:75]
	v_mfma_f32_16x16x32_bf16 v[116:119], v[198:201], v[166:169], v[116:119]
	v_mfma_f32_16x16x32_bf16 v[112:115], v[206:209], v[166:169], v[112:115]
	v_mfma_f32_16x16x32_bf16 v[100:103], v[198:201], v[174:177], v[100:103]
	v_mfma_f32_16x16x32_bf16 v[96:99], v[206:209], v[174:177], v[96:99]
	v_mfma_f32_16x16x32_bf16 v[84:87], v[198:201], v[182:185], v[84:87]
	v_mfma_f32_16x16x32_bf16 v[80:83], v[206:209], v[182:185], v[80:83]
	v_mfma_f32_16x16x32_bf16 v[68:71], v[198:201], v[190:193], v[68:71]
	v_mfma_f32_16x16x32_bf16 v[64:67], v[206:209], v[190:193], v[64:67]
	v_mfma_f32_16x16x32_bf16 v[116:119], v[202:205], v[170:173], v[116:119]
	v_mfma_f32_16x16x32_bf16 v[112:115], v[210:213], v[170:173], v[112:115]
	v_mfma_f32_16x16x32_bf16 v[100:103], v[202:205], v[178:181], v[100:103]
	v_mfma_f32_16x16x32_bf16 v[96:99], v[210:213], v[178:181], v[96:99]
	v_mfma_f32_16x16x32_bf16 v[84:87], v[202:205], v[186:189], v[84:87]
	v_mfma_f32_16x16x32_bf16 v[80:83], v[210:213], v[186:189], v[80:83]
	v_mfma_f32_16x16x32_bf16 v[68:71], v[202:205], v[194:197], v[68:71]
	v_mfma_f32_16x16x32_bf16 v[64:67], v[210:213], v[194:197], v[64:67]
	s_setprio 0
	s_barrier
	ds_read_b128 v[166:169], v148 offset:16384
	ds_read_b128 v[170:173], v148 offset:17408
	ds_read_b128 v[174:177], v148 offset:18432
	ds_read_b128 v[178:181], v148 offset:19456
	ds_read_b128 v[182:185], v148 offset:20480
	ds_read_b128 v[186:189], v148 offset:21504
	ds_read_b128 v[190:193], v148 offset:22528
	ds_read_b128 v[194:197], v148 offset:23552
	s_add_i32 s10, s50, s39
	v_lshl_add_u64 v[214:215], s[28:29], 0, v[132:133]
	s_mov_b32 m0, s10
	s_nop 0
	global_load_lds_dwordx4 v[214:215], off
	v_lshl_add_u64 v[216:217], s[28:29], 0, v[128:129]
	s_add_i32 m0, s10, 0x2000
	s_nop 0
	global_load_lds_dwordx4 v[216:217], off
	s_mov_b32 m0, s21
	v_lshl_add_u64 v[218:219], s[30:31], 0, v[134:135]
	global_load_lds_dwordx4 v[218:219], off
	v_lshl_add_u64 v[220:221], s[30:31], 0, v[130:131]
	s_mov_b32 m0, s42
	s_nop 0
	global_load_lds_dwordx4 v[220:221], off
	s_add_u32 s10, s28, 0x80000
	s_addc_u32 s11, s29, 0
	s_add_i32 s33, s51, s39
	v_lshl_add_u64 v[222:223], s[10:11], 0, v[132:133]
	s_mov_b32 m0, s33
	s_nop 0
	global_load_lds_dwordx4 v[222:223], off
	v_lshl_add_u64 v[222:223], s[10:11], 0, v[128:129]
	s_add_i32 m0, s33, 0x2000
	s_nop 0
	global_load_lds_dwordx4 v[222:223], off
	s_waitcnt vmcnt(8)
	s_waitcnt lgkmcnt(0)
	s_barrier
; #define PG8_STAGE(bufoff, gbase, voff) do { _Pragma("unroll") for (int _i = 0; _i < 2; ++_i) \
;         __builtin_amdgcn_global_load_lds((const unsigned*)((const char*)(gbase) + (voff)[_i]), (PG8_LAS unsigned*)(lds + (bufoff) + ldsw + _i * 8192), 16, 0, 0); } while (0)
; #define PG8_LDA(dst, b, h) do { _Pragma("unroll") for (int m = 0; m < 4; ++m) _Pragma("unroll") for (int k = 0; k < 2; ++k) dst[m][k] = *(const PG8_LAS bf16x8*)(lds + PG8_SA(b, h) + aoff + m * 2048 + k * 1024); } while (0)
; #define PG8_LDB(dst, b, h) do { _Pragma("unroll") for (int n = 0; n < 2; ++n) _Pragma("unroll") for (int k = 0; k < 2; ++k) dst[n][k] = *(const PG8_LAS bf16x8*)(lds + PG8_SB(b, h) + boff + n * 2048 + k * 1024); } while (0)
; #define PG8_MMA(ai, bj, At, Bt) do { __builtin_amdgcn_s_setprio(1); _Pragma("unroll") for (int m = 0; m < 4; ++m) _Pragma("unroll") for (int n = 0; n < 2; ++n) _Pragma("unroll") for (int k = 0; k < 2; ++k) \
;         acc[ai][bj][m][n] = __builtin_amdgcn_mfma_f32_16x16x32_bf16(Bt[n][k], At[m][k], acc[ai][bj][m][n], 0, 0, 0); __builtin_amdgcn_s_setprio(0); } while (0)
; #define PG8_WAIT_V(n) asm volatile("s_waitcnt vmcnt(" #n ")" ::: "memory")
; #define PG8_WAIT_L(n) asm volatile("s_waitcnt lgkmcnt(" #n ")" ::: "memory")
; #define PG8_BAR __builtin_amdgcn_s_barrier()
; #define PG8_SCHED __builtin_amdgcn_sched_barrier(0)
; template <class Epi, class Sched>
; __device__ __forceinline__ void gemm_phase(PG8_LAS unsigned char* lds, const Gemm g, const Sched& S, const Epi& E) {
;     ...
;             PG8_BAR; PG8_WAIT_L(0); PG8_MMA(1, 0, At, B0); PG8_BAR; PG8_SCHED;
;             PG8_STAGE(PG8_SB(0, 1), b2 + hstep, voffB);
;             PG8_WAIT_V(6); PG8_BAR; PG8_MMA(1, 1, At, B1); PG8_BAR;
;             PG8_LDB(B0, 1, 0); PG8_SCHED; PG8_LDA(At, 1, 0); PG8_STAGE(PG8_SA(0, 1), a2 + hstep, voffA);
;             PG8_WAIT_L(8); PG8_BAR; PG8_WAIT_L(0); PG8_MMA(0, 0, At, B0); PG8_BAR; PG8_SCHED;
;             PG8_LDB(B1, 1, 1); PG8_STAGE(PG8_SB(1, 0), b3, voffB);
;             PG8_BAR; PG8_WAIT_L(0); PG8_MMA(0, 1, At, B1); PG8_BAR;
	s_setprio 1
	v_mfma_f32_16x16x32_bf16 v[60:63], v[150:153], v[166:169], v[60:63]
	v_mfma_f32_16x16x32_bf16 v[56:59], v[158:161], v[166:169], v[56:59]
	v_mfma_f32_16x16x32_bf16 v[44:47], v[150:153], v[174:177], v[44:47]
	v_mfma_f32_16x16x32_bf16 v[40:43], v[158:161], v[174:177], v[40:43]
	v_mfma_f32_16x16x32_bf16 v[28:31], v[150:153], v[182:185], v[28:31]
	v_mfma_f32_16x16x32_bf16 v[24:27], v[158:161], v[182:185], v[24:27]
	v_mfma_f32_16x16x32_bf16 v[12:15], v[150:153], v[190:193], v[12:15]
	v_mfma_f32_16x16x32_bf16 v[8:11], v[158:161], v[190:193], v[8:11]
	v_mfma_f32_16x16x32_bf16 v[60:63], v[154:157], v[170:173], v[60:63]
	v_mfma_f32_16x16x32_bf16 v[56:59], v[162:165], v[170:173], v[56:59]
	v_mfma_f32_16x16x32_bf16 v[44:47], v[154:157], v[178:181], v[44:47]
	v_mfma_f32_16x16x32_bf16 v[40:43], v[162:165], v[178:181], v[40:43]
	v_mfma_f32_16x16x32_bf16 v[28:31], v[154:157], v[186:189], v[28:31]
	v_mfma_f32_16x16x32_bf16 v[24:27], v[162:165], v[186:189], v[24:27]
	v_mfma_f32_16x16x32_bf16 v[12:15], v[154:157], v[194:197], v[12:15]
	v_mfma_f32_16x16x32_bf16 v[8:11], v[162:165], v[194:197], v[8:11]
	v_mfma_f32_16x16x32_bf16 v[52:55], v[198:201], v[166:169], v[52:55]
	v_mfma_f32_16x16x32_bf16 v[48:51], v[206:209], v[166:169], v[48:51]
	v_mfma_f32_16x16x32_bf16 v[36:39], v[198:201], v[174:177], v[36:39]
	v_mfma_f32_16x16x32_bf16 v[32:35], v[206:209], v[174:177], v[32:35]
	v_mfma_f32_16x16x32_bf16 v[20:23], v[198:201], v[182:185], v[20:23]
	v_mfma_f32_16x16x32_bf16 v[16:19], v[206:209], v[182:185], v[16:19]
	v_mfma_f32_16x16x32_bf16 v[4:7], v[198:201], v[190:193], v[4:7]
	v_mfma_f32_16x16x32_bf16 v[0:3], v[206:209], v[190:193], v[0:3]
	v_mfma_f32_16x16x32_bf16 v[52:55], v[202:205], v[170:173], v[52:55]
	v_mfma_f32_16x16x32_bf16 v[48:51], v[210:213], v[170:173], v[48:51]
	v_mfma_f32_16x16x32_bf16 v[36:39], v[202:205], v[178:181], v[36:39]
	v_mfma_f32_16x16x32_bf16 v[32:35], v[210:213], v[178:181], v[32:35]
	v_mfma_f32_16x16x32_bf16 v[20:23], v[202:205], v[186:189], v[20:23]
	v_mfma_f32_16x16x32_bf16 v[16:19], v[210:213], v[186:189], v[16:19]
	v_mfma_f32_16x16x32_bf16 v[4:7], v[202:205], v[194:197], v[4:7]
	v_mfma_f32_16x16x32_bf16 v[0:3], v[210:213], v[194:197], v[0:3]
	s_setprio 0
	s_add_i32 s33, 0, 0x18000
	s_barrier
	ds_read_b128 v[150:153], v147 offset:32768
	ds_read_b128 v[154:157], v147 offset:33792
	ds_read_b128 v[158:161], v147 offset:34816
	ds_read_b128 v[162:165], v147 offset:35840
	ds_read_b128 v[166:169], v148 offset:32768
	ds_read_b128 v[170:173], v148 offset:33792
	ds_read_b128 v[174:177], v148 offset:34816
	ds_read_b128 v[178:181], v148 offset:35840
	ds_read_b128 v[182:185], v148 offset:36864
	ds_read_b128 v[186:189], v148 offset:37888
	ds_read_b128 v[190:193], v148 offset:38912
	ds_read_b128 v[194:197], v148 offset:39936
	ds_read_b128 v[198:201], v149 offset:32768
	ds_read_b128 v[202:205], v149 offset:33792
	ds_read_b128 v[206:209], v149 offset:34816
	ds_read_b128 v[210:213], v149 offset:35840
	s_add_u32 s10, s30, 0x80000
	s_addc_u32 s11, s31, 0
	s_mov_b32 m0, s43
	v_lshl_add_u64 v[222:223], s[10:11], 0, v[134:135]
	global_load_lds_dwordx4 v[222:223], off
	v_lshl_add_u64 v[222:223], s[10:11], 0, v[130:131]
	s_mov_b32 m0, s44
	s_nop 0
	global_load_lds_dwordx4 v[222:223], off
	s_waitcnt vmcnt(8)
	s_waitcnt lgkmcnt(0)
	s_barrier
	s_setprio 1
	v_mfma_f32_16x16x32_bf16 v[124:127], v[150:153], v[166:169], v[124:127]
	v_mfma_f32_16x16x32_bf16 v[120:123], v[158:161], v[166:169], v[120:123]
	v_mfma_f32_16x16x32_bf16 v[108:111], v[150:153], v[174:177], v[108:111]
	v_mfma_f32_16x16x32_bf16 v[104:107], v[158:161], v[174:177], v[104:107]
	v_mfma_f32_16x16x32_bf16 v[92:95], v[150:153], v[182:185], v[92:95]
	v_mfma_f32_16x16x32_bf16 v[88:91], v[158:161], v[182:185], v[88:91]
	v_mfma_f32_16x16x32_bf16 v[76:79], v[150:153], v[190:193], v[76:79]
	v_mfma_f32_16x16x32_bf16 v[72:75], v[158:161], v[190:193], v[72:75]
	v_mfma_f32_16x16x32_bf16 v[124:127], v[154:157], v[170:173], v[124:127]
	v_mfma_f32_16x16x32_bf16 v[120:123], v[162:165], v[170:173], v[120:123]
	v_mfma_f32_16x16x32_bf16 v[108:111], v[154:157], v[178:181], v[108:111]
	v_mfma_f32_16x16x32_bf16 v[104:107], v[162:165], v[178:181], v[104:107]
	v_mfma_f32_16x16x32_bf16 v[92:95], v[154:157], v[186:189], v[92:95]
	v_mfma_f32_16x16x32_bf16 v[88:91], v[162:165], v[186:189], v[88:91]
	v_mfma_f32_16x16x32_bf16 v[76:79], v[154:157], v[194:197], v[76:79]
	v_mfma_f32_16x16x32_bf16 v[72:75], v[162:165], v[194:197], v[72:75]
	v_mfma_f32_16x16x32_bf16 v[116:119], v[198:201], v[166:169], v[116:119]
	v_mfma_f32_16x16x32_bf16 v[112:115], v[206:209], v[166:169], v[112:115]
	v_mfma_f32_16x16x32_bf16 v[100:103], v[198:201], v[174:177], v[100:103]
	v_mfma_f32_16x16x32_bf16 v[96:99], v[206:209], v[174:177], v[96:99]
	v_mfma_f32_16x16x32_bf16 v[84:87], v[198:201], v[182:185], v[84:87]
	v_mfma_f32_16x16x32_bf16 v[80:83], v[206:209], v[182:185], v[80:83]
	v_mfma_f32_16x16x32_bf16 v[68:71], v[198:201], v[190:193], v[68:71]
	v_mfma_f32_16x16x32_bf16 v[64:67], v[206:209], v[190:193], v[64:67]
	v_mfma_f32_16x16x32_bf16 v[116:119], v[202:205], v[170:173], v[116:119]
	v_mfma_f32_16x16x32_bf16 v[112:115], v[210:213], v[170:173], v[112:115]
	v_mfma_f32_16x16x32_bf16 v[100:103], v[202:205], v[178:181], v[100:103]
	v_mfma_f32_16x16x32_bf16 v[96:99], v[210:213], v[178:181], v[96:99]
	v_mfma_f32_16x16x32_bf16 v[84:87], v[202:205], v[186:189], v[84:87]
	v_mfma_f32_16x16x32_bf16 v[80:83], v[210:213], v[186:189], v[80:83]
	v_mfma_f32_16x16x32_bf16 v[68:71], v[202:205], v[194:197], v[68:71]
	v_mfma_f32_16x16x32_bf16 v[64:67], v[210:213], v[194:197], v[64:67]
	s_setprio 0
	s_barrier
; __device__ __forceinline__ unsigned cvt_pk_bf16(float lo, float hi) { const bf16v2_t v = __builtin_convertvector((f32x2){lo, hi}, bf16v2_t); return __builtin_bit_cast(unsigned, v); }
; __device__ __forceinline__ float silu_f(float v) { return v * __builtin_amdgcn_rcpf(1.0f + __expf(-v)); }
; #define PG8_STAGE(bufoff, gbase, voff) do { _Pragma("unroll") for (int _i = 0; _i < 2; ++_i) \
;         __builtin_amdgcn_global_load_lds((const unsigned*)((const char*)(gbase) + (voff)[_i]), (PG8_LAS unsigned*)(lds + (bufoff) + ldsw + _i * 8192), 16, 0, 0); } while (0)
; #define PG8_LDA(dst, b, h) do { _Pragma("unroll") for (int m = 0; m < 4; ++m) _Pragma("unroll") for (int k = 0; k < 2; ++k) dst[m][k] = *(const PG8_LAS bf16x8*)(lds + PG8_SA(b, h) + aoff + m * 2048 + k * 1024); } while (0)
; #define PG8_WAIT_V(n) asm volatile("s_waitcnt vmcnt(" #n ")" ::: "memory")
; #define PG8_WAIT_L(n) asm volatile("s_waitcnt lgkmcnt(" #n ")" ::: "memory")
; #define PG8_BAR __builtin_amdgcn_s_barrier()
; #define PG8_SCHED __builtin_amdgcn_sched_barrier(0)
; template <class Epi, class Sched>
; __device__ __forceinline__ void gemm_phase(PG8_LAS unsigned char* lds, const Gemm g, const Sched& S, const Epi& E) {
;     ...
;             PG8_LDA(At, 1, 1); PG8_STAGE(PG8_SA(1, 0), a3, voffA);
;             PG8_BAR; PG8_WAIT_L(0); PG8_MMA(1, 0, At, B0); PG8_BAR; PG8_SCHED;
;             PG8_STAGE(PG8_SB(1, 1), b3 + hstep, voffB);
;             PG8_WAIT_V(6); PG8_BAR; PG8_MMA(1, 1, At, B1); PG8_BAR;
;         }
;     __device__ __forceinline__ void operator()(const AccT& acc, const pg8::Unit& u, int wr, int wc, int fr, int fq) const {
;         const int row0 = u.pm * 256 + wr * 64 + fr, col = u.pn * 128 + wc * 32 + 8 * fq;
; #pragma unroll
;         for (int ai = 0; ai < 2; ++ai)
; #pragma unroll
;             for (int m = 0; m < 4; ++m) {
;                 f32x4 a = acc[ai][0][m][0], b = acc[ai][0][m][1];
; #pragma unroll
;                 for (int j = 0; j < 4; ++j) { a[j] = silu_f(a[j]) * acc[ai][1][m][0][j]; b[j] = silu_f(b[j]) * acc[ai][1][m][1][j]; }
;                 u32x4 w; w.x = cvt_pk_bf16(a[0], a[1]); w.y = cvt_pk_bf16(a[2], a[3]); w.z = cvt_pk_bf16(b[0], b[1]); w.w = cvt_pk_bf16(b[2], b[3]);
;                 *(u32x4*)(HID + (size_t)(row0 + ai * 128 + m * 16) * DFF + col) = w;
	ds_read_b128 v[166:169], v148 offset:49152
	ds_read_b128 v[170:173], v148 offset:50176
	ds_read_b128 v[174:177], v148 offset:51200
	ds_read_b128 v[178:181], v148 offset:52224
	ds_read_b128 v[182:185], v148 offset:53248
	ds_read_b128 v[186:189], v148 offset:54272
	ds_read_b128 v[190:193], v148 offset:55296
	ds_read_b128 v[194:197], v148 offset:56320
	s_add_i32 s30, 0, 0x1c000
	s_add_i32 s10, s33, s39
	v_lshl_add_u64 v[214:215], v[214:215], 0, s[4:5]
	s_mov_b32 m0, s10
	s_nop 0
	global_load_lds_dwordx4 v[214:215], off
	v_lshl_add_u64 v[214:215], v[216:217], 0, s[4:5]
	s_add_i32 m0, s10, 0x2000
	s_nop 0
	global_load_lds_dwordx4 v[214:215], off
	s_mov_b32 m0, s46
	v_lshl_add_u64 v[214:215], v[218:219], 0, s[4:5]
	global_load_lds_dwordx4 v[214:215], off
	v_lshl_add_u64 v[214:215], v[220:221], 0, s[4:5]
	s_mov_b32 m0, s47
	s_nop 0
	global_load_lds_dwordx4 v[214:215], off
	s_add_u32 s10, s28, 0x80080
	s_addc_u32 s11, s29, 0
	s_add_i32 s28, s30, s39
	v_lshl_add_u64 v[222:223], s[10:11], 0, v[132:133]
	s_mov_b32 m0, s28
	s_nop 0
	global_load_lds_dwordx4 v[222:223], off
	v_lshl_add_u64 v[222:223], s[10:11], 0, v[128:129]
	s_add_i32 m0, s28, 0x2000
	s_nop 0
	global_load_lds_dwordx4 v[222:223], off
	s_waitcnt vmcnt(8)
	s_waitcnt lgkmcnt(0)
	s_barrier
	s_setprio 1
	v_mfma_f32_16x16x32_bf16 v[60:63], v[150:153], v[166:169], v[60:63]
	v_mfma_f32_16x16x32_bf16 v[56:59], v[158:161], v[166:169], v[56:59]
	v_mfma_f32_16x16x32_bf16 v[44:47], v[150:153], v[174:177], v[44:47]
	v_mfma_f32_16x16x32_bf16 v[40:43], v[158:161], v[174:177], v[40:43]
	v_mfma_f32_16x16x32_bf16 v[28:31], v[150:153], v[182:185], v[28:31]
	v_mfma_f32_16x16x32_bf16 v[24:27], v[158:161], v[182:185], v[24:27]
	v_mfma_f32_16x16x32_bf16 v[12:15], v[150:153], v[190:193], v[12:15]
	v_mfma_f32_16x16x32_bf16 v[8:11], v[158:161], v[190:193], v[8:11]
	v_mfma_f32_16x16x32_bf16 v[60:63], v[154:157], v[170:173], v[60:63]
	v_mfma_f32_16x16x32_bf16 v[56:59], v[162:165], v[170:173], v[56:59]
	v_mfma_f32_16x16x32_bf16 v[44:47], v[154:157], v[178:181], v[44:47]
	v_mfma_f32_16x16x32_bf16 v[40:43], v[162:165], v[178:181], v[40:43]
	v_mfma_f32_16x16x32_bf16 v[28:31], v[154:157], v[186:189], v[28:31]
	v_mfma_f32_16x16x32_bf16 v[24:27], v[162:165], v[186:189], v[24:27]
	v_mfma_f32_16x16x32_bf16 v[12:15], v[154:157], v[194:197], v[12:15]
	v_mfma_f32_16x16x32_bf16 v[8:11], v[162:165], v[194:197], v[8:11]
	v_mfma_f32_16x16x32_bf16 v[52:55], v[198:201], v[166:169], v[52:55]
	v_mfma_f32_16x16x32_bf16 v[48:51], v[206:209], v[166:169], v[48:51]
	v_mfma_f32_16x16x32_bf16 v[36:39], v[198:201], v[174:177], v[36:39]
	v_mfma_f32_16x16x32_bf16 v[32:35], v[206:209], v[174:177], v[32:35]
	v_mfma_f32_16x16x32_bf16 v[20:23], v[198:201], v[182:185], v[20:23]
	v_mfma_f32_16x16x32_bf16 v[16:19], v[206:209], v[182:185], v[16:19]
	v_mfma_f32_16x16x32_bf16 v[4:7], v[198:201], v[190:193], v[4:7]
	v_mfma_f32_16x16x32_bf16 v[0:3], v[206:209], v[190:193], v[0:3]
	v_mfma_f32_16x16x32_bf16 v[52:55], v[202:205], v[170:173], v[52:55]
	v_mfma_f32_16x16x32_bf16 v[48:51], v[210:213], v[170:173], v[48:51]
	v_mfma_f32_16x16x32_bf16 v[36:39], v[202:205], v[178:181], v[36:39]
	v_mfma_f32_16x16x32_bf16 v[32:35], v[210:213], v[178:181], v[32:35]
	v_mfma_f32_16x16x32_bf16 v[20:23], v[202:205], v[186:189], v[20:23]
	v_mfma_f32_16x16x32_bf16 v[16:19], v[210:213], v[186:189], v[16:19]
	v_mfma_f32_16x16x32_bf16 v[4:7], v[202:205], v[194:197], v[4:7]
	v_mfma_f32_16x16x32_bf16 v[0:3], v[210:213], v[194:197], v[0:3]
	s_setprio 0
	s_add_i32 s70, s70, 2
	s_add_u32 s26, s26, 0x100
	s_addc_u32 s27, s27, 0
	s_add_u32 s68, s68, 0x100
	s_addc_u32 s69, s69, 0
	s_cmp_gt_u32 s70, 29
	s_barrier
	s_cbranch_scc0 .LBB0_803
	v_mul_f32_e32 v151, 0xbfb8aa3b, v124
	v_mul_f32_e32 v154, 0xbfb8aa3b, v120
	v_exp_f32_e32 v151, v151
	v_exp_f32_e32 v155, v154
	v_mul_f32_e32 v154, 0xbfb8aa3b, v125
	v_exp_f32_e32 v156, v154
	v_add_f32_e32 v151, 1.0, v151
	v_rcp_f32_e32 v154, v151
	v_add_f32_e32 v151, 1.0, v155
	v_add_f32_e32 v155, 1.0, v156
	v_rcp_f32_e32 v155, v155
	v_mul_f32_e32 v156, 0xbfb8aa3b, v121
	v_exp_f32_e32 v157, v156
	v_rcp_f32_e32 v156, v151
	v_pk_mul_f32 v[124:125], v[124:125], v[154:155]
	v_mul_f32_e32 v151, 0xbfb8aa3b, v127
	v_pk_mul_f32 v[116:117], v[124:125], v[116:117]
	v_add_f32_e32 v124, 1.0, v157
	v_mul_f32_e32 v125, 0xbfb8aa3b, v122
	v_rcp_f32_e32 v157, v124
	v_mul_f32_e32 v124, 0xbfb8aa3b, v126
	v_exp_f32_e32 v125, v125
	v_exp_f32_e32 v124, v124
	v_exp_f32_e32 v151, v151
	v_mul_f32_e32 v154, 0xbfb8aa3b, v123
	v_exp_f32_e32 v155, v154
	v_add_f32_e32 v125, 1.0, v125
	v_add_f32_e32 v124, 1.0, v124
	v_rcp_f32_e32 v154, v125
	v_add_f32_e32 v125, 1.0, v151
	v_rcp_f32_e32 v124, v124
	v_rcp_f32_e32 v125, v125
	v_add_f32_e32 v151, 1.0, v155
	v_rcp_f32_e32 v155, v151
	v_pk_mul_f32 v[120:121], v[120:121], v[156:157]
	v_lshl_or_b32 v152, s65, 7, v146
	v_pk_mul_f32 v[112:113], v[120:121], v[112:113]
	v_pk_mul_f32 v[120:121], v[126:127], v[124:125]
	v_lshl_add_u32 v150, s20, 8, v144
	v_pk_mul_f32 v[118:119], v[120:121], v[118:119]
	v_pk_mul_f32 v[120:121], v[122:123], v[154:155]
	v_ashrrev_i32_e32 v153, 31, v152
	v_pk_mul_f32 v[114:115], v[120:121], v[114:115]
	v_cvt_pk_bf16_f32 v116, v116, v117
	v_cvt_pk_bf16_f32 v117, v118, v119
	v_cvt_pk_bf16_f32 v118, v112, v113
	v_mov_b64_e32 v[112:113], s[0:1]
	v_cvt_pk_bf16_f32 v119, v114, v115
	v_mad_i64_i32 v[120:121], s[10:11], v150, s64, v[112:113]
	v_lshlrev_b64 v[114:115], 1, v[152:153]
	v_lshl_add_u64 v[120:121], v[120:121], 0, v[114:115]
	global_store_dwordx4 v[120:121], v[116:119], off
	s_and_b64 vcc, exec, s[2:3]
	s_mov_b32 s65, s6
	v_mul_f32_e32 v116, 0xbfb8aa3b, v108
	v_mul_f32_e32 v117, 0xbfb8aa3b, v104
; __device__ __forceinline__ unsigned cvt_pk_bf16(float lo, float hi) { const bf16v2_t v = __builtin_convertvector((f32x2){lo, hi}, bf16v2_t); return __builtin_bit_cast(unsigned, v); }
; __device__ __forceinline__ float silu_f(float v) { return v * __builtin_amdgcn_rcpf(1.0f + __expf(-v)); }
;     __device__ __forceinline__ void operator()(const AccT& acc, const pg8::Unit& u, int wr, int wc, int fr, int fq) const {
;     ...
;         for (int ai = 0; ai < 2; ++ai)
; #pragma unroll
;             for (int m = 0; m < 4; ++m) {
;                 f32x4 a = acc[ai][0][m][0], b = acc[ai][0][m][1];
; #pragma unroll
;                 for (int j = 0; j < 4; ++j) { a[j] = silu_f(a[j]) * acc[ai][1][m][0][j]; b[j] = silu_f(b[j]) * acc[ai][1][m][1][j]; }
;                 u32x4 w; w.x = cvt_pk_bf16(a[0], a[1]); w.y = cvt_pk_bf16(a[2], a[3]); w.z = cvt_pk_bf16(b[0], b[1]); w.w = cvt_pk_bf16(b[2], b[3]);
;                 *(u32x4*)(HID + (size_t)(row0 + ai * 128 + m * 16) * DFF + col) = w;
	v_mul_f32_e32 v118, 0xbfb8aa3b, v109
	v_exp_f32_e32 v116, v116
	v_exp_f32_e32 v117, v117
	v_exp_f32_e32 v118, v118
	s_mov_b32 s20, s8
	v_add_f32_e32 v116, 1.0, v116
	v_add_f32_e32 v119, 1.0, v117
	v_add_f32_e32 v117, 1.0, v118
	v_rcp_f32_e32 v116, v116
	v_rcp_f32_e32 v117, v117
	v_mul_f32_e32 v118, 0xbfb8aa3b, v105
	v_exp_f32_e32 v120, v118
	v_rcp_f32_e32 v118, v119
	v_pk_mul_f32 v[108:109], v[108:109], v[116:117]
	v_mul_f32_e32 v116, 0xbfb8aa3b, v111
	v_pk_mul_f32 v[100:101], v[108:109], v[100:101]
	v_add_f32_e32 v108, 1.0, v120
	v_rcp_f32_e32 v119, v108
	v_mul_f32_e32 v109, 0xbfb8aa3b, v106
	v_mul_f32_e32 v108, 0xbfb8aa3b, v110
	v_exp_f32_e32 v109, v109
	v_exp_f32_e32 v108, v108
	v_exp_f32_e32 v117, v116
	v_mul_f32_e32 v116, 0xbfb8aa3b, v107
	v_pk_mul_f32 v[104:105], v[104:105], v[118:119]
	v_exp_f32_e32 v118, v116
	v_add_f32_e32 v109, 1.0, v109
	v_add_f32_e32 v108, 1.0, v108
	v_rcp_f32_e32 v116, v109
	v_add_f32_e32 v109, 1.0, v117
	v_rcp_f32_e32 v108, v108
	v_rcp_f32_e32 v109, v109
	v_add_f32_e32 v117, 1.0, v118
	v_rcp_f32_e32 v117, v117
	v_pk_mul_f32 v[104:105], v[104:105], v[96:97]
	v_pk_mul_f32 v[96:97], v[110:111], v[108:109]
	s_mov_b64 s[28:29], s[18:19]
	v_pk_mul_f32 v[102:103], v[96:97], v[102:103]
	v_pk_mul_f32 v[96:97], v[106:107], v[116:117]
	s_mov_b64 s[26:27], s[16:17]
	v_pk_mul_f32 v[106:107], v[96:97], v[98:99]
	v_cvt_pk_bf16_f32 v96, v100, v101
	v_or_b32_e32 v100, 16, v150
	v_mad_i64_i32 v[100:101], s[10:11], v100, s64, v[112:113]
	v_cvt_pk_bf16_f32 v97, v102, v103
	v_cvt_pk_bf16_f32 v98, v104, v105
	v_cvt_pk_bf16_f32 v99, v106, v107
	v_lshl_add_u64 v[100:101], v[100:101], 0, v[114:115]
	global_store_dwordx4 v[100:101], v[96:99], off
	s_nop 1
	v_mul_f32_e32 v96, 0xbfb8aa3b, v92
	v_mul_f32_e32 v97, 0xbfb8aa3b, v88
	v_mul_f32_e32 v98, 0xbfb8aa3b, v93
	v_exp_f32_e32 v96, v96
	v_exp_f32_e32 v97, v97
	v_exp_f32_e32 v98, v98
	v_add_f32_e32 v96, 1.0, v96
	v_add_f32_e32 v99, 1.0, v97
	v_add_f32_e32 v97, 1.0, v98
	v_rcp_f32_e32 v96, v96
	v_rcp_f32_e32 v97, v97
	v_mul_f32_e32 v98, 0xbfb8aa3b, v89
	v_exp_f32_e32 v100, v98
	v_rcp_f32_e32 v98, v99
	v_pk_mul_f32 v[92:93], v[92:93], v[96:97]
	v_mul_f32_e32 v96, 0xbfb8aa3b, v95
	v_pk_mul_f32 v[84:85], v[92:93], v[84:85]
	v_add_f32_e32 v92, 1.0, v100
	v_rcp_f32_e32 v99, v92
	v_mul_f32_e32 v93, 0xbfb8aa3b, v90
	v_mul_f32_e32 v92, 0xbfb8aa3b, v94
	v_exp_f32_e32 v93, v93
	v_exp_f32_e32 v92, v92
	v_exp_f32_e32 v97, v96
	v_mul_f32_e32 v96, 0xbfb8aa3b, v91
	v_pk_mul_f32 v[88:89], v[88:89], v[98:99]
	v_exp_f32_e32 v98, v96
	v_add_f32_e32 v93, 1.0, v93
	v_add_f32_e32 v92, 1.0, v92
	v_rcp_f32_e32 v96, v93
	v_add_f32_e32 v93, 1.0, v97
	v_rcp_f32_e32 v92, v92
	v_rcp_f32_e32 v93, v93
	v_add_f32_e32 v97, 1.0, v98
	v_rcp_f32_e32 v97, v97
	v_pk_mul_f32 v[88:89], v[88:89], v[80:81]
	v_pk_mul_f32 v[80:81], v[94:95], v[92:93]
	s_nop 0
	v_pk_mul_f32 v[86:87], v[80:81], v[86:87]
	v_pk_mul_f32 v[80:81], v[90:91], v[96:97]
	s_nop 0
	v_pk_mul_f32 v[90:91], v[80:81], v[82:83]
	v_cvt_pk_bf16_f32 v80, v84, v85
	v_or_b32_e32 v84, 32, v150
	v_mad_i64_i32 v[84:85], s[10:11], v84, s64, v[112:113]
	v_cvt_pk_bf16_f32 v81, v86, v87
	v_cvt_pk_bf16_f32 v82, v88, v89
	v_cvt_pk_bf16_f32 v83, v90, v91
	v_lshl_add_u64 v[84:85], v[84:85], 0, v[114:115]
	global_store_dwordx4 v[84:85], v[80:83], off
	s_nop 1
	v_mul_f32_e32 v80, 0xbfb8aa3b, v76
	v_mul_f32_e32 v81, 0xbfb8aa3b, v72
	v_mul_f32_e32 v82, 0xbfb8aa3b, v77
	v_exp_f32_e32 v80, v80
	v_exp_f32_e32 v81, v81
	v_exp_f32_e32 v82, v82
	v_add_f32_e32 v80, 1.0, v80
	v_add_f32_e32 v83, 1.0, v81
	v_add_f32_e32 v81, 1.0, v82
	v_rcp_f32_e32 v80, v80
	v_rcp_f32_e32 v81, v81
	v_mul_f32_e32 v82, 0xbfb8aa3b, v73
	v_exp_f32_e32 v84, v82
	v_rcp_f32_e32 v82, v83
	v_pk_mul_f32 v[76:77], v[76:77], v[80:81]
	v_mul_f32_e32 v80, 0xbfb8aa3b, v79
	v_pk_mul_f32 v[68:69], v[76:77], v[68:69]
	v_add_f32_e32 v76, 1.0, v84
	v_rcp_f32_e32 v83, v76
	v_mul_f32_e32 v77, 0xbfb8aa3b, v74
	v_mul_f32_e32 v76, 0xbfb8aa3b, v78
	v_exp_f32_e32 v77, v77
	v_exp_f32_e32 v76, v76
	v_exp_f32_e32 v81, v80
	v_mul_f32_e32 v80, 0xbfb8aa3b, v75
	v_pk_mul_f32 v[72:73], v[72:73], v[82:83]
	v_exp_f32_e32 v82, v80
	v_add_f32_e32 v77, 1.0, v77
	v_add_f32_e32 v76, 1.0, v76
	v_rcp_f32_e32 v80, v77
	v_add_f32_e32 v77, 1.0, v81
	v_rcp_f32_e32 v76, v76
	v_rcp_f32_e32 v77, v77
	v_add_f32_e32 v81, 1.0, v82
	v_rcp_f32_e32 v81, v81
	v_pk_mul_f32 v[72:73], v[72:73], v[64:65]
	v_pk_mul_f32 v[64:65], v[78:79], v[76:77]
	s_nop 0
	v_pk_mul_f32 v[70:71], v[64:65], v[70:71]
	v_pk_mul_f32 v[64:65], v[74:75], v[80:81]
	s_nop 0
	v_pk_mul_f32 v[74:75], v[64:65], v[66:67]
	v_cvt_pk_bf16_f32 v64, v68, v69
	v_or_b32_e32 v68, 48, v150
	v_mad_i64_i32 v[68:69], s[10:11], v68, s64, v[112:113]
	v_cvt_pk_bf16_f32 v65, v70, v71
	v_cvt_pk_bf16_f32 v66, v72, v73
	v_cvt_pk_bf16_f32 v67, v74, v75
	v_lshl_add_u64 v[68:69], v[68:69], 0, v[114:115]
	global_store_dwordx4 v[68:69], v[64:67], off
	v_add_u32_e32 v68, 0x80, v150
	s_nop 0
	v_mul_f32_e32 v64, 0xbfb8aa3b, v60
	v_mul_f32_e32 v65, 0xbfb8aa3b, v56
	v_mul_f32_e32 v66, 0xbfb8aa3b, v61
	v_exp_f32_e32 v64, v64
	v_exp_f32_e32 v65, v65
	v_exp_f32_e32 v66, v66
	v_add_f32_e32 v64, 1.0, v64
	v_add_f32_e32 v67, 1.0, v65
	v_add_f32_e32 v65, 1.0, v66
	v_rcp_f32_e32 v64, v64
	v_rcp_f32_e32 v65, v65
	v_mul_f32_e32 v66, 0xbfb8aa3b, v57
	v_exp_f32_e32 v69, v66
	v_rcp_f32_e32 v66, v67
	v_pk_mul_f32 v[60:61], v[60:61], v[64:65]
	v_mul_f32_e32 v64, 0xbfb8aa3b, v63
	v_pk_mul_f32 v[52:53], v[60:61], v[52:53]
	v_add_f32_e32 v60, 1.0, v69
	v_rcp_f32_e32 v67, v60
	v_mul_f32_e32 v61, 0xbfb8aa3b, v58
	v_mul_f32_e32 v60, 0xbfb8aa3b, v62
	v_exp_f32_e32 v61, v61
	v_exp_f32_e32 v60, v60
	v_exp_f32_e32 v65, v64
	v_mul_f32_e32 v64, 0xbfb8aa3b, v59
; __device__ __forceinline__ unsigned cvt_pk_bf16(float lo, float hi) { const bf16v2_t v = __builtin_convertvector((f32x2){lo, hi}, bf16v2_t); return __builtin_bit_cast(unsigned, v); }
; __device__ __forceinline__ float silu_f(float v) { return v * __builtin_amdgcn_rcpf(1.0f + __expf(-v)); }
; #define PG8_WAIT_V(n) asm volatile("s_waitcnt vmcnt(" #n ")" ::: "memory")
; #define PG8_BAR __builtin_amdgcn_s_barrier()
; template <class Epi, class Sched>
; __device__ __forceinline__ void gemm_phase(PG8_LAS unsigned char* lds, const Gemm g, const Sched& S, const Epi& E) {
;     ...
;         if (!has_next) break;
; #pragma unroll
;         for (int a = 0; a < 2; ++a)
; #pragma unroll
;             for (int b = 0; b < 2; ++b)
; #pragma unroll
;                 for (int m = 0; m < 4; ++m)
; #pragma unroll
;                     for (int n = 0; n < 2; ++n) acc[a][b][m][n] = (f32x4){0.f, 0.f, 0.f, 0.f};
;         cur = nxt; cA = nA; cB = nB; ++ui;
;     }
;     PG8_WAIT_V(0);
;     if (wr == 0) PG8_BAR;
;     PG8_BAR;
;     __device__ __forceinline__ void operator()(const AccT& acc, const pg8::Unit& u, int wr, int wc, int fr, int fq) const {
;     ...
;         for (int ai = 0; ai < 2; ++ai)
; #pragma unroll
;             for (int m = 0; m < 4; ++m) {
;                 f32x4 a = acc[ai][0][m][0], b = acc[ai][0][m][1];
; #pragma unroll
;                 for (int j = 0; j < 4; ++j) { a[j] = silu_f(a[j]) * acc[ai][1][m][0][j]; b[j] = silu_f(b[j]) * acc[ai][1][m][1][j]; }
;                 u32x4 w; w.x = cvt_pk_bf16(a[0], a[1]); w.y = cvt_pk_bf16(a[2], a[3]); w.z = cvt_pk_bf16(b[0], b[1]); w.w = cvt_pk_bf16(b[2], b[3]);
;                 *(u32x4*)(HID + (size_t)(row0 + ai * 128 + m * 16) * DFF + col) = w;
	v_pk_mul_f32 v[56:57], v[56:57], v[66:67]
	v_exp_f32_e32 v66, v64
	v_add_f32_e32 v61, 1.0, v61
	v_add_f32_e32 v60, 1.0, v60
	v_rcp_f32_e32 v64, v61
	v_add_f32_e32 v61, 1.0, v65
	v_rcp_f32_e32 v60, v60
	v_rcp_f32_e32 v61, v61
	v_add_f32_e32 v65, 1.0, v66
	v_rcp_f32_e32 v65, v65
	v_pk_mul_f32 v[56:57], v[56:57], v[48:49]
	v_pk_mul_f32 v[48:49], v[62:63], v[60:61]
	s_nop 0
	v_pk_mul_f32 v[54:55], v[48:49], v[54:55]
	v_pk_mul_f32 v[48:49], v[58:59], v[64:65]
	s_nop 0
	v_pk_mul_f32 v[58:59], v[48:49], v[50:51]
	v_cvt_pk_bf16_f32 v48, v52, v53
	v_mad_i64_i32 v[52:53], s[10:11], v68, s64, v[112:113]
	v_cvt_pk_bf16_f32 v49, v54, v55
	v_cvt_pk_bf16_f32 v50, v56, v57
	v_cvt_pk_bf16_f32 v51, v58, v59
	v_lshl_add_u64 v[52:53], v[52:53], 0, v[114:115]
	global_store_dwordx4 v[52:53], v[48:51], off
	s_nop 1
	v_mul_f32_e32 v48, 0xbfb8aa3b, v44
	v_mul_f32_e32 v49, 0xbfb8aa3b, v40
	v_mul_f32_e32 v50, 0xbfb8aa3b, v45
	v_exp_f32_e32 v48, v48
	v_exp_f32_e32 v49, v49
	v_exp_f32_e32 v50, v50
	v_add_f32_e32 v48, 1.0, v48
	v_add_f32_e32 v51, 1.0, v49
	v_add_f32_e32 v49, 1.0, v50
	v_rcp_f32_e32 v48, v48
	v_rcp_f32_e32 v49, v49
	v_mul_f32_e32 v50, 0xbfb8aa3b, v41
	v_exp_f32_e32 v52, v50
	v_rcp_f32_e32 v50, v51
	v_pk_mul_f32 v[44:45], v[44:45], v[48:49]
	v_mul_f32_e32 v48, 0xbfb8aa3b, v47
	v_pk_mul_f32 v[36:37], v[44:45], v[36:37]
	v_add_f32_e32 v44, 1.0, v52
	v_rcp_f32_e32 v51, v44
	v_mul_f32_e32 v45, 0xbfb8aa3b, v42
	v_mul_f32_e32 v44, 0xbfb8aa3b, v46
	v_exp_f32_e32 v45, v45
	v_exp_f32_e32 v44, v44
	v_exp_f32_e32 v49, v48
	v_mul_f32_e32 v48, 0xbfb8aa3b, v43
	v_pk_mul_f32 v[40:41], v[40:41], v[50:51]
	v_exp_f32_e32 v50, v48
	v_add_f32_e32 v45, 1.0, v45
	v_add_f32_e32 v44, 1.0, v44
	v_rcp_f32_e32 v48, v45
	v_add_f32_e32 v45, 1.0, v49
	v_rcp_f32_e32 v44, v44
	v_rcp_f32_e32 v45, v45
	v_add_f32_e32 v49, 1.0, v50
	v_rcp_f32_e32 v49, v49
	v_pk_mul_f32 v[40:41], v[40:41], v[32:33]
	v_pk_mul_f32 v[32:33], v[46:47], v[44:45]
	s_nop 0
	v_pk_mul_f32 v[38:39], v[32:33], v[38:39]
	v_pk_mul_f32 v[32:33], v[42:43], v[48:49]
	s_nop 0
	v_pk_mul_f32 v[42:43], v[32:33], v[34:35]
	v_cvt_pk_bf16_f32 v32, v36, v37
	v_add_u32_e32 v36, 0x90, v150
	v_mad_i64_i32 v[36:37], s[10:11], v36, s64, v[112:113]
	v_cvt_pk_bf16_f32 v33, v38, v39
	v_cvt_pk_bf16_f32 v34, v40, v41
	v_cvt_pk_bf16_f32 v35, v42, v43
	v_lshl_add_u64 v[36:37], v[36:37], 0, v[114:115]
	global_store_dwordx4 v[36:37], v[32:35], off
	s_nop 1
	v_mul_f32_e32 v32, 0xbfb8aa3b, v28
	v_mul_f32_e32 v33, 0xbfb8aa3b, v24
	v_mul_f32_e32 v34, 0xbfb8aa3b, v29
	v_exp_f32_e32 v32, v32
	v_exp_f32_e32 v33, v33
	v_exp_f32_e32 v34, v34
	v_add_f32_e32 v32, 1.0, v32
	v_add_f32_e32 v35, 1.0, v33
	v_add_f32_e32 v33, 1.0, v34
	v_rcp_f32_e32 v32, v32
	v_rcp_f32_e32 v33, v33
	v_mul_f32_e32 v34, 0xbfb8aa3b, v25
	v_exp_f32_e32 v36, v34
	v_rcp_f32_e32 v34, v35
	v_pk_mul_f32 v[28:29], v[28:29], v[32:33]
	v_mul_f32_e32 v32, 0xbfb8aa3b, v31
	v_pk_mul_f32 v[20:21], v[28:29], v[20:21]
	v_add_f32_e32 v28, 1.0, v36
	v_rcp_f32_e32 v35, v28
	v_mul_f32_e32 v29, 0xbfb8aa3b, v26
	v_mul_f32_e32 v28, 0xbfb8aa3b, v30
	v_exp_f32_e32 v29, v29
	v_exp_f32_e32 v28, v28
	v_exp_f32_e32 v33, v32
	v_mul_f32_e32 v32, 0xbfb8aa3b, v27
	v_pk_mul_f32 v[24:25], v[24:25], v[34:35]
	v_exp_f32_e32 v34, v32
	v_add_f32_e32 v29, 1.0, v29
	v_add_f32_e32 v28, 1.0, v28
	v_rcp_f32_e32 v32, v29
	v_add_f32_e32 v29, 1.0, v33
	v_rcp_f32_e32 v28, v28
	v_rcp_f32_e32 v29, v29
	v_add_f32_e32 v33, 1.0, v34
	v_rcp_f32_e32 v33, v33
	v_pk_mul_f32 v[24:25], v[24:25], v[16:17]
	v_pk_mul_f32 v[16:17], v[30:31], v[28:29]
	s_nop 0
	v_pk_mul_f32 v[22:23], v[16:17], v[22:23]
	v_pk_mul_f32 v[16:17], v[26:27], v[32:33]
	s_nop 0
	v_pk_mul_f32 v[26:27], v[16:17], v[18:19]
	v_cvt_pk_bf16_f32 v16, v20, v21
	v_add_u32_e32 v20, 0xa0, v150
	v_mad_i64_i32 v[20:21], s[10:11], v20, s64, v[112:113]
	v_cvt_pk_bf16_f32 v17, v22, v23
	v_cvt_pk_bf16_f32 v18, v24, v25
	v_cvt_pk_bf16_f32 v19, v26, v27
	v_lshl_add_u64 v[20:21], v[20:21], 0, v[114:115]
	global_store_dwordx4 v[20:21], v[16:19], off
	s_nop 1
	v_mul_f32_e32 v16, 0xbfb8aa3b, v12
	v_mul_f32_e32 v17, 0xbfb8aa3b, v8
	v_mul_f32_e32 v18, 0xbfb8aa3b, v13
	v_exp_f32_e32 v16, v16
	v_exp_f32_e32 v17, v17
	v_exp_f32_e32 v18, v18
	v_add_f32_e32 v16, 1.0, v16
	v_add_f32_e32 v19, 1.0, v17
	v_add_f32_e32 v17, 1.0, v18
	v_rcp_f32_e32 v16, v16
	v_rcp_f32_e32 v17, v17
	v_mul_f32_e32 v18, 0xbfb8aa3b, v9
	v_exp_f32_e32 v20, v18
	v_rcp_f32_e32 v18, v19
	v_pk_mul_f32 v[12:13], v[12:13], v[16:17]
	v_mul_f32_e32 v16, 0xbfb8aa3b, v15
	v_pk_mul_f32 v[4:5], v[12:13], v[4:5]
	v_add_f32_e32 v12, 1.0, v20
	v_rcp_f32_e32 v19, v12
	v_mul_f32_e32 v13, 0xbfb8aa3b, v10
	v_mul_f32_e32 v12, 0xbfb8aa3b, v14
	v_exp_f32_e32 v13, v13
	v_exp_f32_e32 v12, v12
	v_exp_f32_e32 v17, v16
	v_mul_f32_e32 v16, 0xbfb8aa3b, v11
	v_pk_mul_f32 v[8:9], v[8:9], v[18:19]
	v_exp_f32_e32 v18, v16
	v_add_f32_e32 v13, 1.0, v13
	v_add_f32_e32 v12, 1.0, v12
	v_rcp_f32_e32 v16, v13
	v_add_f32_e32 v13, 1.0, v17
	v_rcp_f32_e32 v12, v12
	v_rcp_f32_e32 v13, v13
	v_add_f32_e32 v17, 1.0, v18
	v_rcp_f32_e32 v17, v17
	v_pk_mul_f32 v[8:9], v[8:9], v[0:1]
	v_pk_mul_f32 v[0:1], v[14:15], v[12:13]
	s_nop 0
	v_pk_mul_f32 v[6:7], v[0:1], v[6:7]
	v_pk_mul_f32 v[0:1], v[10:11], v[16:17]
	s_nop 0
	v_pk_mul_f32 v[10:11], v[0:1], v[2:3]
	v_cvt_pk_bf16_f32 v0, v4, v5
	v_add_u32_e32 v4, 0xb0, v150
	v_mad_i64_i32 v[4:5], s[10:11], v4, s64, v[112:113]
	v_cvt_pk_bf16_f32 v1, v6, v7
	v_cvt_pk_bf16_f32 v2, v8, v9
	v_cvt_pk_bf16_f32 v3, v10, v11
	v_lshl_add_u64 v[4:5], v[4:5], 0, v[114:115]
	global_store_dwordx4 v[4:5], v[0:3], off
	s_cbranch_vccz .LBB0_800
	s_waitcnt vmcnt(0)
	s_cmpk_gt_u32 s34, 0xff
	s_cbranch_scc1 .LBB0_807
	s_barrier

; #define PG8_STAGE(bufoff, gbase, voff) do { _Pragma("unroll") for (int _i = 0; _i < 2; ++_i) \
;         __builtin_amdgcn_global_load_lds((const unsigned*)((const char*)(gbase) + (voff)[_i]), (PG8_LAS unsigned*)(lds + (bufoff) + ldsw + _i * 8192), 16, 0, 0); } while (0)
; #define PG8_WAIT_V(n) asm volatile("s_waitcnt vmcnt(" #n ")" ::: "memory")
; #define PG8_BAR __builtin_amdgcn_s_barrier()
; template <class Epi, class Sched>
; __device__ __forceinline__ void gemm_phase(PG8_LAS unsigned char* lds, const Gemm g, const Sched& S, const Epi& E) {
;     const int tid = threadIdx.x, wid = __builtin_amdgcn_readfirstlane(tid >> 6), lane = tid & 63, wr = wid >> 2, wc = wid & 3, fr = lane & 15, fq = lane >> 4;
;     const int K = g.K, nt = K / BK;
;     unsigned voffA[2], voffB[2];
; #pragma unroll
;     for (int i = 0; i < 2; ++i) { int R, C; stage_rc(tid * 16 + i * 8192, R, C); const int Rb = Epi::PERM ? ((R & ~31) + perm32(R & 31)) : R;
;         voffA[i] = (unsigned)(R * K + C) * 2u; voffB[i] = (unsigned)(Rb * K + C) * 2u; }
;     const size_t kstep = (size_t)(BK * 2);
;     const size_t hstep = (size_t)HALF * K * 2;
;     const size_t tstep = 2 * hstep;
;     const unsigned ldsw = (unsigned)wid * 1024u;
;     const int aoff = lds_byte(wr * 64 + fr, fq * 8), boff = lds_byte(wc * 32 + fr, fq * 8);
;     ...
;     PG8_STAGE(PG8_SB(0, 0), cB, voffB); PG8_STAGE(PG8_SA(0, 0), cA, voffA); PG8_STAGE(PG8_SB(0, 1), cB + hstep, voffB); PG8_STAGE(PG8_SA(0, 1), cA + hstep, voffA);
;     if (wr == 1) PG8_BAR;
;     PG8_WAIT_V(4); PG8_BAR;
;     PG8_STAGE(PG8_SB(1, 0), cB + kstep, voffB); PG8_STAGE(PG8_SA(1, 0), cA + kstep, voffA); PG8_STAGE(PG8_SB(1, 1), cB + hstep + kstep, voffB);
;     PG8_WAIT_V(6); PG8_BAR;
.LBB0_870:
	s_add_u32 s6, s58, 0xfc86000
	s_addc_u32 s7, s59, 0
	s_add_u32 s8, s58, 0x6a26000
	s_addc_u32 s9, s59, 0
	s_add_u32 s16, s58, 0x7a86000
	s_addc_u32 s17, s59, 0
	s_lshl_b32 s2, s2, 5
	s_mov_b64 s[18:19], 0x80
	s_and_b32 s5, s2, 0x60
	s_add_i32 m0, s40, 0x18000
	v_lshl_add_u64 v[6:7], v[6:7], 0, s[18:19]
	s_lshl_b32 s4, s0, 13
	s_lshl_b32 s10, s5, 7
	s_waitcnt vmcnt(2)
	s_barrier
	global_load_lds_dwordx4 v[6:7], off
	v_lshl_add_u64 v[4:5], v[4:5], 0, s[18:19]
	s_add_i32 m0, s40, 0x1a000
	s_add_i32 s45, s40, 0x8000
	s_add_i32 s46, s40, 0xa000
	global_load_lds_dwordx4 v[4:5], off
	v_lshl_add_u64 v[2:3], v[2:3], 0, s[18:19]
	s_mov_b32 m0, s45
	s_add_u32 s2, s28, 0x160080
	global_load_lds_dwordx4 v[2:3], off
	v_lshl_add_u64 v[0:1], v[0:1], 0, s[18:19]
	s_mov_b32 m0, s46
	s_addc_u32 s3, s29, 0
	global_load_lds_dwordx4 v[0:1], off
	s_add_i32 m0, s40, 0x1c000
	v_lshl_add_u64 v[0:1], s[2:3], 0, v[178:179]
	global_load_lds_dwordx4 v[0:1], off
	v_lshl_add_u64 v[0:1], s[2:3], 0, v[182:183]
	s_add_i32 m0, s40, 0x1e000
	v_lshlrev_b32_e32 v2, 2, v242
	global_load_lds_dwordx4 v[0:1], off
	v_and_b32_e32 v0, 15, v242
	v_lshl_or_b32 v244, s0, 6, v0
	v_lshlrev_b32_e32 v1, 1, v10
	v_lshlrev_b32_e32 v3, 6, v242
	s_movk_i32 s0, 0x3c0
	v_lshl_or_b32 v0, v0, 6, v1
	v_and_b32_e32 v2, 32, v2
	v_and_or_b32 v1, v3, s0, v1
	v_bitop3_b32 v245, s10, v1, v2 bitop3:0xf6
	s_waitcnt vmcnt(6)
	v_add_u16_e32 v1, v8, v9
	v_bitop3_b32 v0, v0, s4, v2 bitop3:0xde
	v_lshrrev_b16_e32 v1, 1, v1
	s_add_i32 s49, 0, 0x10000
	s_add_i32 s50, 0, 0x14000
	s_sext_i32_i8 s66, s1
	s_ashr_i32 s47, s62, 31
	s_mov_b32 s48, s62
	v_or_b32_e32 v246, s5, v10
	v_add_lshl_u32 v184, v11, v1, 1
	v_mov_b32_e32 v185, v179
	v_add_lshl_u32 v186, v12, v1, 1
	v_mov_b32_e32 v187, v179
	v_add_u32_e32 v247, s49, v245
	v_add_u32_e32 v248, 0, v0
	v_add_u32_e32 v249, s50, v245
	s_mov_b32 s20, 0x3f9837f0
	s_barrier

; #define PG8_STAGE(bufoff, gbase, voff) do { _Pragma("unroll") for (int _i = 0; _i < 2; ++_i) \
;         __builtin_amdgcn_global_load_lds((const unsigned*)((const char*)(gbase) + (voff)[_i]), (PG8_LAS unsigned*)(lds + (bufoff) + ldsw + _i * 8192), 16, 0, 0); } while (0)
; #define PG8_LDA(dst, b, h) do { _Pragma("unroll") for (int m = 0; m < 4; ++m) _Pragma("unroll") for (int k = 0; k < 2; ++k) dst[m][k] = *(const PG8_LAS bf16x8*)(lds + PG8_SA(b, h) + aoff + m * 2048 + k * 1024); } while (0)
; #define PG8_LDB(dst, b, h) do { _Pragma("unroll") for (int n = 0; n < 2; ++n) _Pragma("unroll") for (int k = 0; k < 2; ++k) dst[n][k] = *(const PG8_LAS bf16x8*)(lds + PG8_SB(b, h) + boff + n * 2048 + k * 1024); } while (0)
; #define PG8_MMA(ai, bj, At, Bt) do { __builtin_amdgcn_s_setprio(1); _Pragma("unroll") for (int m = 0; m < 4; ++m) _Pragma("unroll") for (int n = 0; n < 2; ++n) _Pragma("unroll") for (int k = 0; k < 2; ++k) \
;         acc[ai][bj][m][n] = __builtin_amdgcn_mfma_f32_16x16x32_bf16(Bt[n][k], At[m][k], acc[ai][bj][m][n], 0, 0, 0); __builtin_amdgcn_s_setprio(0); } while (0)
; #define PG8_WAIT_L(n) asm volatile("s_waitcnt lgkmcnt(" #n ")" ::: "memory")
; #define PG8_BAR __builtin_amdgcn_s_barrier()
; #define PG8_SCHED __builtin_amdgcn_sched_barrier(0)
; template <class Epi, class Sched>
; __device__ __forceinline__ void gemm_phase(PG8_LAS unsigned char* lds, const Gemm g, const Sched& S, const Epi& E) {
;     ...
;             const bool last = (t == nt - 2);
;             const char* a1 = cA + (size_t)(t + 1) * kstep;
;             const char* a2 = last ? nA : cA + (size_t)(t + 2) * kstep; const char* b2 = last ? nB : cB + (size_t)(t + 2) * kstep;
;             const char* a3 = a2 + kstep; const char* b3 = b2 + kstep;
;             if (last && has_next) S.a_ready(nxt);
;             PG8_LDB(B0, 0, 0); PG8_SCHED; PG8_LDA(At, 0, 0); PG8_STAGE(PG8_SA(1, 1), a1 + hstep, voffA);
;             PG8_WAIT_L(8); PG8_BAR; PG8_WAIT_L(0); PG8_MMA(0, 0, At, B0); PG8_BAR; PG8_SCHED;
;             PG8_LDB(B1, 0, 1); PG8_STAGE(PG8_SB(0, 0), b2, voffB);
;             PG8_BAR; PG8_WAIT_L(0); PG8_MMA(0, 1, At, B1); PG8_BAR;
;             PG8_LDA(At, 0, 1); PG8_STAGE(PG8_SA(0, 0), a2, voffA);
;             PG8_BAR; PG8_WAIT_L(0); PG8_MMA(1, 0, At, B0); PG8_BAR; PG8_SCHED;
;             PG8_STAGE(PG8_SB(0, 1), b2 + hstep, voffB);
.LBB0_882:
	ds_read_b128 v[108:111], v247
	ds_read_b128 v[112:115], v247 offset:1024
	ds_read_b128 v[124:127], v247 offset:2048
	ds_read_b128 v[128:131], v247 offset:3072
	ds_read_b128 v[144:147], v248
	ds_read_b128 v[148:151], v248 offset:1024
	ds_read_b128 v[152:155], v248 offset:2048
	ds_read_b128 v[156:159], v248 offset:3072
	ds_read_b128 v[160:163], v248 offset:4096
	ds_read_b128 v[164:167], v248 offset:5120
	ds_read_b128 v[168:171], v248 offset:6144
	ds_read_b128 v[172:175], v248 offset:7168
	ds_read_b128 v[188:191], v249
	ds_read_b128 v[192:195], v249 offset:1024
	ds_read_b128 v[196:199], v249 offset:2048
	ds_read_b128 v[200:203], v249 offset:3072
	s_add_u32 s10, s26, 0xffea0080
	s_addc_u32 s11, s27, -1
	s_cmpk_eq_i32 s69, 0x54
	s_cselect_b32 s31, s1, s11
	s_cselect_b32 s30, s0, s10
	s_cselect_b32 s29, s5, s68
	s_cselect_b32 s28, s4, s67
	v_lshl_add_u64 v[252:253], s[26:27], 0, v[184:185]
	s_add_i32 m0, s40, 0xc000
	s_nop 0
	global_load_lds_dwordx4 v[252:253], off
	v_lshl_add_u64 v[252:253], s[26:27], 0, v[186:187]
	s_add_i32 m0, s40, 0xe000
	s_nop 0
	global_load_lds_dwordx4 v[252:253], off
	s_waitcnt vmcnt(8)
	s_waitcnt lgkmcnt(0)
	s_barrier
	s_setprio 1
	v_mfma_f32_16x16x32_bf16 v[140:143], v[108:111], v[144:147], v[140:143]
	v_mfma_f32_16x16x32_bf16 v[136:139], v[124:127], v[144:147], v[136:139]
	v_mfma_f32_16x16x32_bf16 v[116:119], v[108:111], v[152:155], v[116:119]
	v_mfma_f32_16x16x32_bf16 v[104:107], v[124:127], v[152:155], v[104:107]
	v_mfma_f32_16x16x32_bf16 v[92:95], v[108:111], v[160:163], v[92:95]
	v_mfma_f32_16x16x32_bf16 v[88:91], v[124:127], v[160:163], v[88:91]
	v_mfma_f32_16x16x32_bf16 v[76:79], v[108:111], v[168:171], v[76:79]
	v_mfma_f32_16x16x32_bf16 v[72:75], v[124:127], v[168:171], v[72:75]
	v_mfma_f32_16x16x32_bf16 v[140:143], v[112:115], v[148:151], v[140:143]
	v_mfma_f32_16x16x32_bf16 v[136:139], v[128:131], v[148:151], v[136:139]
	v_mfma_f32_16x16x32_bf16 v[116:119], v[112:115], v[156:159], v[116:119]
	v_mfma_f32_16x16x32_bf16 v[104:107], v[128:131], v[156:159], v[104:107]
	v_mfma_f32_16x16x32_bf16 v[92:95], v[112:115], v[164:167], v[92:95]
	v_mfma_f32_16x16x32_bf16 v[88:91], v[128:131], v[164:167], v[88:91]
	v_mfma_f32_16x16x32_bf16 v[76:79], v[112:115], v[172:175], v[76:79]
	v_mfma_f32_16x16x32_bf16 v[72:75], v[128:131], v[172:175], v[72:75]
	v_mfma_f32_16x16x32_bf16 v[132:135], v[188:191], v[144:147], v[132:135]
	v_mfma_f32_16x16x32_bf16 v[120:123], v[196:199], v[144:147], v[120:123]
	v_mfma_f32_16x16x32_bf16 v[100:103], v[188:191], v[152:155], v[100:103]
	v_mfma_f32_16x16x32_bf16 v[96:99], v[196:199], v[152:155], v[96:99]
	v_mfma_f32_16x16x32_bf16 v[84:87], v[188:191], v[160:163], v[84:87]
	v_mfma_f32_16x16x32_bf16 v[80:83], v[196:199], v[160:163], v[80:83]
	v_mfma_f32_16x16x32_bf16 v[68:71], v[188:191], v[168:171], v[68:71]
	v_mfma_f32_16x16x32_bf16 v[64:67], v[196:199], v[168:171], v[64:67]
	v_mfma_f32_16x16x32_bf16 v[132:135], v[192:195], v[148:151], v[132:135]
	v_mfma_f32_16x16x32_bf16 v[120:123], v[200:203], v[148:151], v[120:123]
	v_mfma_f32_16x16x32_bf16 v[100:103], v[192:195], v[156:159], v[100:103]
	v_mfma_f32_16x16x32_bf16 v[96:99], v[200:203], v[156:159], v[96:99]
	v_mfma_f32_16x16x32_bf16 v[84:87], v[192:195], v[164:167], v[84:87]
	v_mfma_f32_16x16x32_bf16 v[80:83], v[200:203], v[164:167], v[80:83]
	v_mfma_f32_16x16x32_bf16 v[68:71], v[192:195], v[172:175], v[68:71]
	v_mfma_f32_16x16x32_bf16 v[64:67], v[200:203], v[172:175], v[64:67]
	s_setprio 0
	s_barrier
	ds_read_b128 v[144:147], v248 offset:16384
	ds_read_b128 v[148:151], v248 offset:17408
	ds_read_b128 v[152:155], v248 offset:18432
	ds_read_b128 v[156:159], v248 offset:19456
	ds_read_b128 v[160:163], v248 offset:20480
	ds_read_b128 v[164:167], v248 offset:21504
	ds_read_b128 v[168:171], v248 offset:22528
	ds_read_b128 v[172:175], v248 offset:23552
	s_add_i32 s10, s49, s39
	v_lshl_add_u64 v[204:205], s[28:29], 0, v[178:179]
	s_mov_b32 m0, s10
	s_nop 0
	global_load_lds_dwordx4 v[204:205], off
	v_lshl_add_u64 v[206:207], s[28:29], 0, v[182:183]
	s_add_i32 m0, s10, 0x2000
	s_nop 0
	global_load_lds_dwordx4 v[206:207], off
	s_mov_b32 m0, s40
	v_lshl_add_u64 v[208:209], s[30:31], 0, v[176:177]
	global_load_lds_dwordx4 v[208:209], off
	v_lshl_add_u64 v[210:211], s[30:31], 0, v[180:181]
	s_mov_b32 m0, s41
	s_nop 0
	global_load_lds_dwordx4 v[210:211], off
	s_add_u32 s10, s28, 0x160000
	s_addc_u32 s11, s29, 0
	s_add_i32 s33, s50, s39
	v_lshl_add_u64 v[252:253], s[10:11], 0, v[178:179]
	s_mov_b32 m0, s33
	s_nop 0
	global_load_lds_dwordx4 v[252:253], off
	v_lshl_add_u64 v[252:253], s[10:11], 0, v[182:183]
	s_add_i32 m0, s33, 0x2000
	s_nop 0
	global_load_lds_dwordx4 v[252:253], off
	s_waitcnt vmcnt(8)
	s_waitcnt lgkmcnt(0)
	s_barrier
; #define PG8_STAGE(bufoff, gbase, voff) do { _Pragma("unroll") for (int _i = 0; _i < 2; ++_i) \
;         __builtin_amdgcn_global_load_lds((const unsigned*)((const char*)(gbase) + (voff)[_i]), (PG8_LAS unsigned*)(lds + (bufoff) + ldsw + _i * 8192), 16, 0, 0); } while (0)
; #define PG8_LDA(dst, b, h) do { _Pragma("unroll") for (int m = 0; m < 4; ++m) _Pragma("unroll") for (int k = 0; k < 2; ++k) dst[m][k] = *(const PG8_LAS bf16x8*)(lds + PG8_SA(b, h) + aoff + m * 2048 + k * 1024); } while (0)
; #define PG8_LDB(dst, b, h) do { _Pragma("unroll") for (int n = 0; n < 2; ++n) _Pragma("unroll") for (int k = 0; k < 2; ++k) dst[n][k] = *(const PG8_LAS bf16x8*)(lds + PG8_SB(b, h) + boff + n * 2048 + k * 1024); } while (0)
; #define PG8_MMA(ai, bj, At, Bt) do { __builtin_amdgcn_s_setprio(1); _Pragma("unroll") for (int m = 0; m < 4; ++m) _Pragma("unroll") for (int n = 0; n < 2; ++n) _Pragma("unroll") for (int k = 0; k < 2; ++k) \
;         acc[ai][bj][m][n] = __builtin_amdgcn_mfma_f32_16x16x32_bf16(Bt[n][k], At[m][k], acc[ai][bj][m][n], 0, 0, 0); __builtin_amdgcn_s_setprio(0); } while (0)
; #define PG8_WAIT_V(n) asm volatile("s_waitcnt vmcnt(" #n ")" ::: "memory")
; #define PG8_WAIT_L(n) asm volatile("s_waitcnt lgkmcnt(" #n ")" ::: "memory")
; #define PG8_BAR __builtin_amdgcn_s_barrier()
; #define PG8_SCHED __builtin_amdgcn_sched_barrier(0)
; template <class Epi, class Sched>
; __device__ __forceinline__ void gemm_phase(PG8_LAS unsigned char* lds, const Gemm g, const Sched& S, const Epi& E) {
;     ...
;             PG8_BAR; PG8_WAIT_L(0); PG8_MMA(1, 0, At, B0); PG8_BAR; PG8_SCHED;
;             PG8_STAGE(PG8_SB(0, 1), b2 + hstep, voffB);
;             PG8_WAIT_V(6); PG8_BAR; PG8_MMA(1, 1, At, B1); PG8_BAR;
;             PG8_LDB(B0, 1, 0); PG8_SCHED; PG8_LDA(At, 1, 0); PG8_STAGE(PG8_SA(0, 1), a2 + hstep, voffA);
;             PG8_WAIT_L(8); PG8_BAR; PG8_WAIT_L(0); PG8_MMA(0, 0, At, B0); PG8_BAR; PG8_SCHED;
;             PG8_LDB(B1, 1, 1); PG8_STAGE(PG8_SB(1, 0), b3, voffB);
;             PG8_BAR; PG8_WAIT_L(0); PG8_MMA(0, 1, At, B1); PG8_BAR;
	s_setprio 1
	v_mfma_f32_16x16x32_bf16 v[60:63], v[108:111], v[144:147], v[60:63]
	v_mfma_f32_16x16x32_bf16 v[56:59], v[124:127], v[144:147], v[56:59]
	v_mfma_f32_16x16x32_bf16 v[44:47], v[108:111], v[152:155], v[44:47]
	v_mfma_f32_16x16x32_bf16 v[40:43], v[124:127], v[152:155], v[40:43]
	v_mfma_f32_16x16x32_bf16 v[28:31], v[108:111], v[160:163], v[28:31]
	v_mfma_f32_16x16x32_bf16 v[24:27], v[124:127], v[160:163], v[24:27]
	v_mfma_f32_16x16x32_bf16 v[12:15], v[108:111], v[168:171], v[12:15]
	v_mfma_f32_16x16x32_bf16 v[8:11], v[124:127], v[168:171], v[8:11]
	v_mfma_f32_16x16x32_bf16 v[60:63], v[112:115], v[148:151], v[60:63]
	v_mfma_f32_16x16x32_bf16 v[56:59], v[128:131], v[148:151], v[56:59]
	v_mfma_f32_16x16x32_bf16 v[44:47], v[112:115], v[156:159], v[44:47]
	v_mfma_f32_16x16x32_bf16 v[40:43], v[128:131], v[156:159], v[40:43]
	v_mfma_f32_16x16x32_bf16 v[28:31], v[112:115], v[164:167], v[28:31]
	v_mfma_f32_16x16x32_bf16 v[24:27], v[128:131], v[164:167], v[24:27]
	v_mfma_f32_16x16x32_bf16 v[12:15], v[112:115], v[172:175], v[12:15]
	v_mfma_f32_16x16x32_bf16 v[8:11], v[128:131], v[172:175], v[8:11]
	v_mfma_f32_16x16x32_bf16 v[52:55], v[188:191], v[144:147], v[52:55]
	v_mfma_f32_16x16x32_bf16 v[48:51], v[196:199], v[144:147], v[48:51]
	v_mfma_f32_16x16x32_bf16 v[36:39], v[188:191], v[152:155], v[36:39]
	v_mfma_f32_16x16x32_bf16 v[32:35], v[196:199], v[152:155], v[32:35]
	v_mfma_f32_16x16x32_bf16 v[20:23], v[188:191], v[160:163], v[20:23]
	v_mfma_f32_16x16x32_bf16 v[16:19], v[196:199], v[160:163], v[16:19]
	v_mfma_f32_16x16x32_bf16 v[4:7], v[188:191], v[168:171], v[4:7]
	v_mfma_f32_16x16x32_bf16 v[0:3], v[196:199], v[168:171], v[0:3]
	v_mfma_f32_16x16x32_bf16 v[52:55], v[192:195], v[148:151], v[52:55]
	v_mfma_f32_16x16x32_bf16 v[48:51], v[200:203], v[148:151], v[48:51]
	v_mfma_f32_16x16x32_bf16 v[36:39], v[192:195], v[156:159], v[36:39]
	v_mfma_f32_16x16x32_bf16 v[32:35], v[200:203], v[156:159], v[32:35]
	v_mfma_f32_16x16x32_bf16 v[20:23], v[192:195], v[164:167], v[20:23]
	v_mfma_f32_16x16x32_bf16 v[16:19], v[200:203], v[164:167], v[16:19]
	v_mfma_f32_16x16x32_bf16 v[4:7], v[192:195], v[172:175], v[4:7]
	v_mfma_f32_16x16x32_bf16 v[0:3], v[200:203], v[172:175], v[0:3]
	s_setprio 0
	s_add_i32 s33, 0, 0x18000
	s_barrier
	ds_read_b128 v[108:111], v247 offset:32768
	ds_read_b128 v[112:115], v247 offset:33792
	ds_read_b128 v[124:127], v247 offset:34816
	ds_read_b128 v[128:131], v247 offset:35840
	ds_read_b128 v[144:147], v248 offset:32768
	ds_read_b128 v[148:151], v248 offset:33792
	ds_read_b128 v[152:155], v248 offset:34816
	ds_read_b128 v[156:159], v248 offset:35840
	ds_read_b128 v[160:163], v248 offset:36864
	ds_read_b128 v[164:167], v248 offset:37888
	ds_read_b128 v[168:171], v248 offset:38912
	ds_read_b128 v[172:175], v248 offset:39936
	ds_read_b128 v[188:191], v249 offset:32768
	ds_read_b128 v[192:195], v249 offset:33792
	ds_read_b128 v[196:199], v249 offset:34816
	ds_read_b128 v[200:203], v249 offset:35840
	s_add_u32 s10, s30, 0x160000
	s_addc_u32 s11, s31, 0
	s_mov_b32 m0, s42
	v_lshl_add_u64 v[252:253], s[10:11], 0, v[176:177]
	global_load_lds_dwordx4 v[252:253], off
	v_lshl_add_u64 v[252:253], s[10:11], 0, v[180:181]
	s_mov_b32 m0, s43
	s_nop 0
	global_load_lds_dwordx4 v[252:253], off
	s_waitcnt vmcnt(8)
	s_waitcnt lgkmcnt(0)
	s_barrier
	s_setprio 1
	v_mfma_f32_16x16x32_bf16 v[140:143], v[108:111], v[144:147], v[140:143]
	v_mfma_f32_16x16x32_bf16 v[136:139], v[124:127], v[144:147], v[136:139]
	v_mfma_f32_16x16x32_bf16 v[116:119], v[108:111], v[152:155], v[116:119]
	v_mfma_f32_16x16x32_bf16 v[104:107], v[124:127], v[152:155], v[104:107]
	v_mfma_f32_16x16x32_bf16 v[92:95], v[108:111], v[160:163], v[92:95]
	v_mfma_f32_16x16x32_bf16 v[88:91], v[124:127], v[160:163], v[88:91]
	v_mfma_f32_16x16x32_bf16 v[76:79], v[108:111], v[168:171], v[76:79]
	v_mfma_f32_16x16x32_bf16 v[72:75], v[124:127], v[168:171], v[72:75]
	v_mfma_f32_16x16x32_bf16 v[140:143], v[112:115], v[148:151], v[140:143]
	v_mfma_f32_16x16x32_bf16 v[136:139], v[128:131], v[148:151], v[136:139]
	v_mfma_f32_16x16x32_bf16 v[116:119], v[112:115], v[156:159], v[116:119]
	v_mfma_f32_16x16x32_bf16 v[104:107], v[128:131], v[156:159], v[104:107]
	v_mfma_f32_16x16x32_bf16 v[92:95], v[112:115], v[164:167], v[92:95]
	v_mfma_f32_16x16x32_bf16 v[88:91], v[128:131], v[164:167], v[88:91]
	v_mfma_f32_16x16x32_bf16 v[76:79], v[112:115], v[172:175], v[76:79]
	v_mfma_f32_16x16x32_bf16 v[72:75], v[128:131], v[172:175], v[72:75]
	v_mfma_f32_16x16x32_bf16 v[132:135], v[188:191], v[144:147], v[132:135]
	v_mfma_f32_16x16x32_bf16 v[120:123], v[196:199], v[144:147], v[120:123]
	v_mfma_f32_16x16x32_bf16 v[100:103], v[188:191], v[152:155], v[100:103]
	v_mfma_f32_16x16x32_bf16 v[96:99], v[196:199], v[152:155], v[96:99]
	v_mfma_f32_16x16x32_bf16 v[84:87], v[188:191], v[160:163], v[84:87]
	v_mfma_f32_16x16x32_bf16 v[80:83], v[196:199], v[160:163], v[80:83]
	v_mfma_f32_16x16x32_bf16 v[68:71], v[188:191], v[168:171], v[68:71]
	v_mfma_f32_16x16x32_bf16 v[64:67], v[196:199], v[168:171], v[64:67]
	v_mfma_f32_16x16x32_bf16 v[132:135], v[192:195], v[148:151], v[132:135]
	v_mfma_f32_16x16x32_bf16 v[120:123], v[200:203], v[148:151], v[120:123]
	v_mfma_f32_16x16x32_bf16 v[100:103], v[192:195], v[156:159], v[100:103]
	v_mfma_f32_16x16x32_bf16 v[96:99], v[200:203], v[156:159], v[96:99]
	v_mfma_f32_16x16x32_bf16 v[84:87], v[192:195], v[164:167], v[84:87]
	v_mfma_f32_16x16x32_bf16 v[80:83], v[200:203], v[164:167], v[80:83]
	v_mfma_f32_16x16x32_bf16 v[68:71], v[192:195], v[172:175], v[68:71]
	v_mfma_f32_16x16x32_bf16 v[64:67], v[200:203], v[172:175], v[64:67]
	s_setprio 0
	s_barrier
; #define PG8_STAGE(bufoff, gbase, voff) do { _Pragma("unroll") for (int _i = 0; _i < 2; ++_i) \
;         __builtin_amdgcn_global_load_lds((const unsigned*)((const char*)(gbase) + (voff)[_i]), (PG8_LAS unsigned*)(lds + (bufoff) + ldsw + _i * 8192), 16, 0, 0); } while (0)
; #define PG8_LDA(dst, b, h) do { _Pragma("unroll") for (int m = 0; m < 4; ++m) _Pragma("unroll") for (int k = 0; k < 2; ++k) dst[m][k] = *(const PG8_LAS bf16x8*)(lds + PG8_SA(b, h) + aoff + m * 2048 + k * 1024); } while (0)
; #define PG8_MMA(ai, bj, At, Bt) do { __builtin_amdgcn_s_setprio(1); _Pragma("unroll") for (int m = 0; m < 4; ++m) _Pragma("unroll") for (int n = 0; n < 2; ++n) _Pragma("unroll") for (int k = 0; k < 2; ++k) \
;         acc[ai][bj][m][n] = __builtin_amdgcn_mfma_f32_16x16x32_bf16(Bt[n][k], At[m][k], acc[ai][bj][m][n], 0, 0, 0); __builtin_amdgcn_s_setprio(0); } while (0)
; template <class Epi, class Sched>
; __device__ __forceinline__ void gemm_phase(PG8_LAS unsigned char* lds, const Gemm g, const Sched& S, const Epi& E) {
;     ...
;             PG8_LDA(At, 1, 1); PG8_STAGE(PG8_SA(1, 0), a3, voffA);
;             PG8_BAR; PG8_WAIT_L(0); PG8_MMA(1, 0, At, B0); PG8_BAR; PG8_SCHED;
;             PG8_STAGE(PG8_SB(1, 1), b3 + hstep, voffB);
;             PG8_WAIT_V(6); PG8_BAR; PG8_MMA(1, 1, At, B1); PG8_BAR;
;         }
;     __device__ __forceinline__ void operator()(const AccT& acc, const pg8::Unit& u, int wr, int wc, int fr, int fq) const {
;         const int row0 = u.pm * 256 + wr * 64 + fr, col0 = u.pn * 256 + wc * 32 + 8 * fq;
;         const float* ga = mod + (u.pm >= 64 ? 12288 : 0) + 5 * 2048;
;         f32x4 gv[2][2], lg[2][2], lbv[2][2];
; #pragma unroll
;         for (int bj = 0; bj < 2; ++bj)
; #pragma unroll
;             for (int n = 0; n < 2; ++n) { const int c = col0 + bj * 128 + n * 4; gv[bj][n] = *(const f32x4*)(ga + c); lg[bj][n] = ALPHA * *(const f32x4*)(g1 + c); lbv[bj][n] = ALPHA * *(const f32x4*)(b1 + c); }
; #pragma unroll
;         for (int ai = 0; ai < 2; ++ai) {
;             u32x4 uraw[4][2]; f32x2 stv[4];
; #pragma unroll
;             for (int m = 0; m < 4; ++m) { const int row = row0 + ai * 128 + m * 16; const size_t off = (size_t)row * D + col0; stv[m] = *(const f32x2*)(stats + 2 * row);
; #pragma unroll
;                 for (int bj = 0; bj < 2; ++bj) uraw[m][bj] = *(const u32x4*)(U1 + off + bj * 128); }
	ds_read_b128 v[144:147], v248 offset:49152
	ds_read_b128 v[148:151], v248 offset:50176
	ds_read_b128 v[152:155], v248 offset:51200
	ds_read_b128 v[156:159], v248 offset:52224
	ds_read_b128 v[160:163], v248 offset:53248
	ds_read_b128 v[164:167], v248 offset:54272
	ds_read_b128 v[168:171], v248 offset:55296
	ds_read_b128 v[172:175], v248 offset:56320
	s_add_i32 s30, 0, 0x1c000
	s_add_i32 s10, s33, s39
	v_lshl_add_u64 v[204:205], v[204:205], 0, s[18:19]
	s_mov_b32 m0, s10
	s_nop 0
	global_load_lds_dwordx4 v[204:205], off
	v_lshl_add_u64 v[204:205], v[206:207], 0, s[18:19]
	s_add_i32 m0, s10, 0x2000
	s_nop 0
	global_load_lds_dwordx4 v[204:205], off
	s_mov_b32 m0, s45
	v_lshl_add_u64 v[204:205], v[208:209], 0, s[18:19]
	global_load_lds_dwordx4 v[204:205], off
	v_lshl_add_u64 v[204:205], v[210:211], 0, s[18:19]
	s_mov_b32 m0, s46
	s_nop 0
	global_load_lds_dwordx4 v[204:205], off
	s_add_u32 s10, s28, 0x160080
	s_addc_u32 s11, s29, 0
	s_add_i32 s28, s30, s39
	v_lshl_add_u64 v[252:253], s[10:11], 0, v[178:179]
	s_mov_b32 m0, s28
	s_nop 0
	global_load_lds_dwordx4 v[252:253], off
	v_lshl_add_u64 v[252:253], s[10:11], 0, v[182:183]
	s_add_i32 m0, s28, 0x2000
	s_nop 0
	global_load_lds_dwordx4 v[252:253], off
	s_waitcnt vmcnt(8)
	s_waitcnt lgkmcnt(0)
	s_barrier
	s_setprio 1
	v_mfma_f32_16x16x32_bf16 v[60:63], v[108:111], v[144:147], v[60:63]
	v_mfma_f32_16x16x32_bf16 v[56:59], v[124:127], v[144:147], v[56:59]
	v_mfma_f32_16x16x32_bf16 v[44:47], v[108:111], v[152:155], v[44:47]
	v_mfma_f32_16x16x32_bf16 v[40:43], v[124:127], v[152:155], v[40:43]
	v_mfma_f32_16x16x32_bf16 v[28:31], v[108:111], v[160:163], v[28:31]
	v_mfma_f32_16x16x32_bf16 v[24:27], v[124:127], v[160:163], v[24:27]
	v_mfma_f32_16x16x32_bf16 v[12:15], v[108:111], v[168:171], v[12:15]
	v_mfma_f32_16x16x32_bf16 v[8:11], v[124:127], v[168:171], v[8:11]
	v_mfma_f32_16x16x32_bf16 v[60:63], v[112:115], v[148:151], v[60:63]
	v_mfma_f32_16x16x32_bf16 v[56:59], v[128:131], v[148:151], v[56:59]
	v_mfma_f32_16x16x32_bf16 v[44:47], v[112:115], v[156:159], v[44:47]
	v_mfma_f32_16x16x32_bf16 v[40:43], v[128:131], v[156:159], v[40:43]
	v_mfma_f32_16x16x32_bf16 v[28:31], v[112:115], v[164:167], v[28:31]
	v_mfma_f32_16x16x32_bf16 v[24:27], v[128:131], v[164:167], v[24:27]
	v_mfma_f32_16x16x32_bf16 v[12:15], v[112:115], v[172:175], v[12:15]
	v_mfma_f32_16x16x32_bf16 v[8:11], v[128:131], v[172:175], v[8:11]
	v_mfma_f32_16x16x32_bf16 v[52:55], v[188:191], v[144:147], v[52:55]
	v_mfma_f32_16x16x32_bf16 v[48:51], v[196:199], v[144:147], v[48:51]
	v_mfma_f32_16x16x32_bf16 v[36:39], v[188:191], v[152:155], v[36:39]
	v_mfma_f32_16x16x32_bf16 v[32:35], v[196:199], v[152:155], v[32:35]
	v_mfma_f32_16x16x32_bf16 v[20:23], v[188:191], v[160:163], v[20:23]
	v_mfma_f32_16x16x32_bf16 v[16:19], v[196:199], v[160:163], v[16:19]
	v_mfma_f32_16x16x32_bf16 v[4:7], v[188:191], v[168:171], v[4:7]
	v_mfma_f32_16x16x32_bf16 v[0:3], v[196:199], v[168:171], v[0:3]
	v_mfma_f32_16x16x32_bf16 v[52:55], v[192:195], v[148:151], v[52:55]
	v_mfma_f32_16x16x32_bf16 v[48:51], v[200:203], v[148:151], v[48:51]
	v_mfma_f32_16x16x32_bf16 v[36:39], v[192:195], v[156:159], v[36:39]
	v_mfma_f32_16x16x32_bf16 v[32:35], v[200:203], v[156:159], v[32:35]
	v_mfma_f32_16x16x32_bf16 v[20:23], v[192:195], v[164:167], v[20:23]
	v_mfma_f32_16x16x32_bf16 v[16:19], v[200:203], v[164:167], v[16:19]
	v_mfma_f32_16x16x32_bf16 v[4:7], v[192:195], v[172:175], v[4:7]
	v_mfma_f32_16x16x32_bf16 v[0:3], v[200:203], v[172:175], v[0:3]
	s_setprio 0
	s_add_i32 s69, s69, 2
	s_add_u32 s26, s26, 0x100
	s_addc_u32 s27, s27, 0
	s_add_u32 s67, s67, 0x100
	s_addc_u32 s68, s68, 0
	s_cmpk_gt_u32 s69, 0x55
	s_barrier
	s_cbranch_scc0 .LBB0_882
	s_cmp_gt_i32 s65, 63
	s_cselect_b32 s10, 0xc000, 0
	s_add_u32 s10, s58, s10
	v_lshl_or_b32 v156, s66, 8, v246
	s_addc_u32 s11, s59, 0
	s_add_u32 s10, s10, 0x6a0a000
	v_ashrrev_i32_e32 v157, 31, v156
	s_addc_u32 s11, s11, 0
	v_lshlrev_b64 v[144:145], 2, v[156:157]
	v_lshl_add_u64 v[108:109], s[10:11], 0, v[144:145]
	v_lshl_add_u64 v[148:149], s[22:23], 0, v[144:145]
	global_load_dwordx4 v[112:115], v[108:109], off offset:16
	global_load_dwordx4 v[128:131], v[108:109], off
	s_nop 0
	global_load_dwordx4 v[108:111], v[148:149], off offset:16
	global_load_dwordx4 v[124:127], v[148:149], off
	v_lshl_add_u64 v[152:153], s[24:25], 0, v[144:145]
	v_lshl_add_u32 v224, s65, 8, v244
	v_lshlrev_b64 v[220:221], 1, v[156:157]
	v_ashrrev_i32_e32 v225, 31, v224
	v_lshl_add_u64 v[222:223], s[6:7], 0, v[220:221]
	v_lshlrev_b64 v[240:241], 12, v[224:225]
	s_and_b64 vcc, exec, s[2:3]
	s_mov_b32 s66, s51
	s_mov_b32 s65, s64
	s_mov_b64 s[28:29], s[4:5]
	s_mov_b64 s[26:27], s[0:1]
	s_waitcnt vmcnt(0)
	v_pk_mul_f32 v[210:211], v[108:109], s[20:21] op_sel_hi:[1,0]
	v_pk_mul_f32 v[204:205], v[126:127], s[20:21] op_sel_hi:[1,0]
	v_pk_mul_f32 v[206:207], v[124:125], s[20:21] op_sel_hi:[1,0]
	global_load_dwordx4 v[124:127], v[152:153], off offset:16
	global_load_dwordx4 v[144:147], v[152:153], off
	v_or_b32_e32 v108, 0x80, v156
	v_ashrrev_i32_e32 v109, 31, v108
	v_pk_mul_f32 v[208:209], v[110:111], s[20:21] op_sel_hi:[1,0]
	v_or_b32_e32 v156, 48, v224
	v_ashrrev_i32_e32 v157, 31, v156
	v_lshlrev_b32_e32 v158, 1, v156
	v_ashrrev_i32_e32 v159, 31, v158
	v_lshlrev_b64 v[232:233], 12, v[156:157]
	v_lshl_add_u64 v[158:159], v[158:159], 2, s[8:9]
	v_lshl_add_u64 v[156:157], v[222:223], 0, v[232:233]
	s_waitcnt vmcnt(0)
;     __device__ __forceinline__ void operator()(const AccT& acc, const pg8::Unit& u, int wr, int wc, int fr, int fq) const {
;     ...
;             u32x4 uraw[4][2]; f32x2 stv[4];
; #pragma unroll
;             for (int m = 0; m < 4; ++m) { const int row = row0 + ai * 128 + m * 16; const size_t off = (size_t)row * D + col0; stv[m] = *(const f32x2*)(stats + 2 * row);
; #pragma unroll
;                 for (int bj = 0; bj < 2; ++bj) uraw[m][bj] = *(const u32x4*)(U1 + off + bj * 128); }
; #pragma unroll
;             for (int m = 0; m < 4; ++m) { const int row = row0 + ai * 128 + m * 16; const size_t off = (size_t)row * D + col0; const f32x2 st = stv[m];
; #pragma unroll
;                 for (int bj = 0; bj < 2; ++bj) { float uf[8]; unpack_h8(uraw[m][bj], uf);
;                     const f32x4 ua = {uf[0], uf[1], uf[2], uf[3]}, ub = {uf[4], uf[5], uf[6], uf[7]};
;                     const f32x4 a = ((ua - st.x) * st.y) * lg[bj][0] + lbv[bj][0] + gv[bj][0] * acc[ai][bj][m][0], b = ((ub - st.x) * st.y) * lg[bj][1] + lbv[bj][1] + gv[bj][1] * acc[ai][bj][m][1];
;                     u32x4 w; w.x = pk_h2(a[0], a[1]); w.y = pk_h2(a[2], a[3]); w.z = pk_h2(b[0], b[1]); w.w = pk_h2(b[2], b[3]);
;                     *(u32x4*)(U2 + off + bj * 128) = w; } }
	v_pk_mul_f32 v[214:215], v[124:125], s[20:21] op_sel_hi:[1,0]
	v_lshl_add_u64 v[124:125], v[108:109], 2, s[10:11]
	v_pk_mul_f32 v[216:217], v[146:147], s[20:21] op_sel_hi:[1,0]
	v_pk_mul_f32 v[218:219], v[144:145], s[20:21] op_sel_hi:[1,0]
	v_pk_mul_f32 v[212:213], v[126:127], s[20:21] op_sel_hi:[1,0]
	global_load_dwordx4 v[108:111], v[124:125], off offset:16
	s_nop 0
	global_load_dwordx4 v[124:127], v[124:125], off
	s_nop 0
	global_load_dwordx4 v[144:147], v[148:149], off offset:528
	s_nop 0
	global_load_dwordx4 v[148:151], v[148:149], off offset:512
	s_waitcnt vmcnt(0)
	v_pk_mul_f32 v[190:191], v[144:145], s[20:21] op_sel_hi:[1,0]
	v_pk_mul_f32 v[196:197], v[150:151], s[20:21] op_sel_hi:[1,0]
	v_pk_mul_f32 v[198:199], v[148:149], s[20:21] op_sel_hi:[1,0]
	global_load_dwordx4 v[148:151], v[152:153], off offset:528
	s_nop 0
	global_load_dwordx4 v[152:155], v[152:153], off offset:512
	v_lshlrev_b32_e32 v144, 1, v224
	v_ashrrev_i32_e32 v145, 31, v144
	v_lshl_add_u64 v[144:145], v[144:145], 2, s[8:9]
	global_load_dwordx2 v[234:235], v[144:145], off
	v_lshl_add_u64 v[144:145], v[222:223], 0, v[240:241]
	global_load_dwordx4 v[172:175], v[144:145], off
	global_load_dwordx4 v[160:163], v[144:145], off offset:256
	v_or_b32_e32 v144, 16, v224
	v_pk_mul_f32 v[188:189], v[146:147], s[20:21] op_sel_hi:[1,0]
	v_ashrrev_i32_e32 v145, 31, v144
	v_lshlrev_b32_e32 v146, 1, v144
	v_ashrrev_i32_e32 v147, 31, v146
	v_lshlrev_b64 v[238:239], 12, v[144:145]
	v_lshl_add_u64 v[146:147], v[146:147], 2, s[8:9]
	v_lshl_add_u64 v[144:145], v[222:223], 0, v[238:239]
	global_load_dwordx2 v[236:237], v[146:147], off
	s_waitcnt vmcnt(0)
	v_pk_mul_f32 v[192:193], v[150:151], s[20:21] op_sel_hi:[1,0]
	v_pk_mul_f32 v[194:195], v[148:149], s[20:21] op_sel_hi:[1,0]
	global_load_dwordx4 v[164:167], v[144:145], off
	global_load_dwordx4 v[148:151], v[144:145], off offset:256
	v_or_b32_e32 v144, 32, v224
	v_ashrrev_i32_e32 v145, 31, v144
	v_lshlrev_b32_e32 v146, 1, v144
	v_ashrrev_i32_e32 v147, 31, v146
	v_lshlrev_b64 v[230:231], 12, v[144:145]
	v_lshl_add_u64 v[146:147], v[146:147], 2, s[8:9]
	v_lshl_add_u64 v[144:145], v[222:223], 0, v[230:231]
	v_pk_mul_f32 v[200:201], v[154:155], s[20:21] op_sel_hi:[1,0]
	v_pk_mul_f32 v[202:203], v[152:153], s[20:21] op_sel_hi:[1,0]
	global_load_dwordx2 v[228:229], v[146:147], off
	global_load_dwordx4 v[152:155], v[144:145], off
	s_nop 0
	global_load_dwordx4 v[144:147], v[144:145], off offset:256
	v_cvt_f32_f16_sdwa v225, v172 dst_sel:DWORD dst_unused:UNUSED_PAD src0_sel:WORD_1
	global_load_dwordx2 v[226:227], v[158:159], off
	global_load_dwordx4 v[168:171], v[156:157], off
	s_nop 0
	global_load_dwordx4 v[156:159], v[156:157], off offset:256
	v_cvt_f32_f16_e32 v172, v172
	v_cvt_f32_f16_sdwa v250, v173 dst_sel:DWORD dst_unused:UNUSED_PAD src0_sel:WORD_1
	v_cvt_f32_f16_e32 v251, v173
	v_cvt_f32_f16_sdwa v252, v174 dst_sel:DWORD dst_unused:UNUSED_PAD src0_sel:WORD_1
	v_cvt_f32_f16_e32 v253, v174
	v_cvt_f32_f16_sdwa v254, v175 dst_sel:DWORD dst_unused:UNUSED_PAD src0_sel:WORD_1
	v_cvt_f32_f16_e32 v243, v175
	v_sub_f32_e32 v172, v172, v234
	v_sub_f32_e32 v173, v225, v234
	v_sub_f32_e32 v174, v251, v234
	v_sub_f32_e32 v175, v250, v234
	v_pk_mul_f32 v[174:175], v[234:235], v[174:175] op_sel:[1,0]
	v_pk_mul_f32 v[172:173], v[234:235], v[172:173] op_sel:[1,0]
	v_pk_fma_f32 v[174:175], v[204:205], v[174:175], v[216:217]
	v_pk_fma_f32 v[172:173], v[206:207], v[172:173], v[218:219]
	v_pk_fma_f32 v[142:143], v[142:143], v[130:131], v[174:175]
	v_pk_fma_f32 v[140:141], v[140:141], v[128:129], v[172:173]
	v_sub_f32_e32 v172, v253, v234
	v_sub_f32_e32 v173, v252, v234
	v_sub_f32_e32 v174, v243, v234
	v_sub_f32_e32 v175, v254, v234
	v_pk_mul_f32 v[174:175], v[234:235], v[174:175] op_sel:[1,0]
	v_pk_mul_f32 v[172:173], v[234:235], v[172:173] op_sel:[1,0]
	v_pk_fma_f32 v[174:175], v[208:209], v[174:175], v[212:213]
	v_pk_fma_f32 v[172:173], v[210:211], v[172:173], v[214:215]
	v_pk_fma_f32 v[174:175], v[138:139], v[114:115], v[174:175]
	v_pk_fma_f32 v[138:139], v[136:137], v[112:113], v[172:173]
	v_cvt_pk_f16_f32 v136, v140, v141
	v_lshl_add_u64 v[140:141], s[16:17], 0, v[240:241]
	v_cvt_pk_f16_f32 v137, v142, v143
	v_cvt_pk_f16_f32 v138, v138, v139
	v_cvt_pk_f16_f32 v139, v174, v175
	v_lshl_add_u64 v[140:141], v[140:141], 0, v[220:221]
	global_store_dwordx4 v[140:141], v[136:139], off
	v_cvt_f32_f16_sdwa v142, v162 dst_sel:DWORD dst_unused:UNUSED_PAD src0_sel:WORD_1
	v_cvt_f32_f16_e32 v143, v162
	v_cvt_f32_f16_sdwa v137, v160 dst_sel:DWORD dst_unused:UNUSED_PAD src0_sel:WORD_1
	v_cvt_f32_f16_e32 v136, v160
	v_cvt_f32_f16_sdwa v139, v161 dst_sel:DWORD dst_unused:UNUSED_PAD src0_sel:WORD_1
	v_cvt_f32_f16_e32 v138, v161
	v_cvt_f32_f16_sdwa v160, v163 dst_sel:DWORD dst_unused:UNUSED_PAD src0_sel:WORD_1
	v_cvt_f32_f16_e32 v161, v163
	v_sub_f32_e32 v136, v136, v234
	v_sub_f32_e32 v137, v137, v234
	v_sub_f32_e32 v138, v138, v234
	v_sub_f32_e32 v139, v139, v234
	v_pk_mul_f32 v[138:139], v[234:235], v[138:139] op_sel:[1,0]
	v_pk_mul_f32 v[136:137], v[234:235], v[136:137] op_sel:[1,0]
	v_pk_fma_f32 v[138:139], v[196:197], v[138:139], v[200:201]
	v_pk_fma_f32 v[136:137], v[198:199], v[136:137], v[202:203]
	v_pk_fma_f32 v[134:135], v[134:135], v[126:127], v[138:139]
	v_pk_fma_f32 v[132:133], v[132:133], v[124:125], v[136:137]
	v_sub_f32_e32 v136, v143, v234
	v_sub_f32_e32 v137, v142, v234
	v_sub_f32_e32 v138, v161, v234
	v_sub_f32_e32 v139, v160, v234
	v_pk_mul_f32 v[138:139], v[234:235], v[138:139] op_sel:[1,0]
	v_pk_mul_f32 v[136:137], v[234:235], v[136:137] op_sel:[1,0]
	v_pk_fma_f32 v[138:139], v[188:189], v[138:139], v[192:193]
	v_pk_fma_f32 v[136:137], v[190:191], v[136:137], v[194:195]
	v_pk_fma_f32 v[138:139], v[122:123], v[110:111], v[138:139]
	v_pk_fma_f32 v[122:123], v[120:121], v[108:109], v[136:137]
	v_cvt_pk_f16_f32 v120, v132, v133
	v_cvt_pk_f16_f32 v121, v134, v135
	v_cvt_pk_f16_f32 v122, v122, v123
	v_cvt_pk_f16_f32 v123, v138, v139
	global_store_dwordx4 v[140:141], v[120:123], off offset:256
	s_waitcnt vmcnt(0)
;     __device__ __forceinline__ void operator()(const AccT& acc, const pg8::Unit& u, int wr, int wc, int fr, int fq) const {
;     ...
;             for (int m = 0; m < 4; ++m) { const int row = row0 + ai * 128 + m * 16; const size_t off = (size_t)row * D + col0; const f32x2 st = stv[m];
; #pragma unroll
;                 for (int bj = 0; bj < 2; ++bj) { float uf[8]; unpack_h8(uraw[m][bj], uf);
;                     const f32x4 ua = {uf[0], uf[1], uf[2], uf[3]}, ub = {uf[4], uf[5], uf[6], uf[7]};
;                     const f32x4 a = ((ua - st.x) * st.y) * lg[bj][0] + lbv[bj][0] + gv[bj][0] * acc[ai][bj][m][0], b = ((ub - st.x) * st.y) * lg[bj][1] + lbv[bj][1] + gv[bj][1] * acc[ai][bj][m][1];
;                     u32x4 w; w.x = pk_h2(a[0], a[1]); w.y = pk_h2(a[2], a[3]); w.z = pk_h2(b[0], b[1]); w.w = pk_h2(b[2], b[3]);
;                     *(u32x4*)(U2 + off + bj * 128) = w; } }
	v_cvt_f32_f16_sdwa v132, v166 dst_sel:DWORD dst_unused:UNUSED_PAD src0_sel:WORD_1
	v_cvt_f32_f16_e32 v133, v166
	v_cvt_f32_f16_sdwa v121, v164 dst_sel:DWORD dst_unused:UNUSED_PAD src0_sel:WORD_1
	v_cvt_f32_f16_e32 v120, v164
	v_cvt_f32_f16_sdwa v123, v165 dst_sel:DWORD dst_unused:UNUSED_PAD src0_sel:WORD_1
	v_cvt_f32_f16_e32 v122, v165
	v_cvt_f32_f16_sdwa v134, v167 dst_sel:DWORD dst_unused:UNUSED_PAD src0_sel:WORD_1
	v_cvt_f32_f16_e32 v135, v167
	v_sub_f32_e32 v120, v120, v236
	v_sub_f32_e32 v121, v121, v236
	v_sub_f32_e32 v122, v122, v236
	v_sub_f32_e32 v123, v123, v236
	v_pk_mul_f32 v[122:123], v[236:237], v[122:123] op_sel:[1,0]
	v_pk_mul_f32 v[120:121], v[236:237], v[120:121] op_sel:[1,0]
	v_pk_fma_f32 v[122:123], v[204:205], v[122:123], v[216:217]
	v_pk_fma_f32 v[120:121], v[206:207], v[120:121], v[218:219]
	v_pk_fma_f32 v[118:119], v[118:119], v[130:131], v[122:123]
	v_pk_fma_f32 v[116:117], v[116:117], v[128:129], v[120:121]
	v_sub_f32_e32 v120, v133, v236
	v_sub_f32_e32 v121, v132, v236
	v_sub_f32_e32 v122, v135, v236
	v_sub_f32_e32 v123, v134, v236
	v_pk_mul_f32 v[122:123], v[236:237], v[122:123] op_sel:[1,0]
	v_pk_mul_f32 v[120:121], v[236:237], v[120:121] op_sel:[1,0]
	v_pk_fma_f32 v[122:123], v[208:209], v[122:123], v[212:213]
	v_pk_fma_f32 v[120:121], v[210:211], v[120:121], v[214:215]
	v_pk_fma_f32 v[122:123], v[106:107], v[114:115], v[122:123]
	v_pk_fma_f32 v[106:107], v[104:105], v[112:113], v[120:121]
	v_cvt_pk_f16_f32 v104, v116, v117
	v_lshl_add_u64 v[116:117], s[16:17], 0, v[238:239]
	v_cvt_pk_f16_f32 v105, v118, v119
	v_cvt_pk_f16_f32 v106, v106, v107
	v_cvt_pk_f16_f32 v107, v122, v123
	v_lshl_add_u64 v[116:117], v[116:117], 0, v[220:221]
	global_store_dwordx4 v[116:117], v[104:107], off
	v_cvt_f32_f16_sdwa v118, v150 dst_sel:DWORD dst_unused:UNUSED_PAD src0_sel:WORD_1
	v_cvt_f32_f16_e32 v119, v150
	v_cvt_f32_f16_sdwa v105, v148 dst_sel:DWORD dst_unused:UNUSED_PAD src0_sel:WORD_1
	v_cvt_f32_f16_e32 v104, v148
	v_cvt_f32_f16_sdwa v107, v149 dst_sel:DWORD dst_unused:UNUSED_PAD src0_sel:WORD_1
	v_cvt_f32_f16_e32 v106, v149
	v_cvt_f32_f16_sdwa v120, v151 dst_sel:DWORD dst_unused:UNUSED_PAD src0_sel:WORD_1
	v_cvt_f32_f16_e32 v121, v151
	v_sub_f32_e32 v104, v104, v236
	v_sub_f32_e32 v105, v105, v236
	v_sub_f32_e32 v106, v106, v236
	v_sub_f32_e32 v107, v107, v236
	v_pk_mul_f32 v[106:107], v[236:237], v[106:107] op_sel:[1,0]
	v_pk_mul_f32 v[104:105], v[236:237], v[104:105] op_sel:[1,0]
	v_pk_fma_f32 v[106:107], v[196:197], v[106:107], v[200:201]
	v_pk_fma_f32 v[104:105], v[198:199], v[104:105], v[202:203]
	v_pk_fma_f32 v[102:103], v[102:103], v[126:127], v[106:107]
	v_pk_fma_f32 v[100:101], v[100:101], v[124:125], v[104:105]
	v_sub_f32_e32 v104, v119, v236
	v_sub_f32_e32 v105, v118, v236
	v_sub_f32_e32 v106, v121, v236
	v_sub_f32_e32 v107, v120, v236
	v_pk_mul_f32 v[106:107], v[236:237], v[106:107] op_sel:[1,0]
	v_pk_mul_f32 v[104:105], v[236:237], v[104:105] op_sel:[1,0]
	v_pk_fma_f32 v[106:107], v[188:189], v[106:107], v[192:193]
	v_pk_fma_f32 v[104:105], v[190:191], v[104:105], v[194:195]
	v_pk_fma_f32 v[106:107], v[98:99], v[110:111], v[106:107]
	v_pk_fma_f32 v[98:99], v[96:97], v[108:109], v[104:105]
	v_cvt_pk_f16_f32 v96, v100, v101
	v_cvt_pk_f16_f32 v97, v102, v103
	v_cvt_pk_f16_f32 v98, v98, v99
	v_cvt_pk_f16_f32 v99, v106, v107
	global_store_dwordx4 v[116:117], v[96:99], off offset:256
	v_cvt_f32_f16_sdwa v100, v154 dst_sel:DWORD dst_unused:UNUSED_PAD src0_sel:WORD_1
	v_cvt_f32_f16_e32 v101, v154
	v_cvt_f32_f16_sdwa v97, v152 dst_sel:DWORD dst_unused:UNUSED_PAD src0_sel:WORD_1
	v_cvt_f32_f16_e32 v96, v152
	v_cvt_f32_f16_sdwa v99, v153 dst_sel:DWORD dst_unused:UNUSED_PAD src0_sel:WORD_1
	v_cvt_f32_f16_e32 v98, v153
	v_cvt_f32_f16_sdwa v102, v155 dst_sel:DWORD dst_unused:UNUSED_PAD src0_sel:WORD_1
	v_cvt_f32_f16_e32 v103, v155
	v_sub_f32_e32 v96, v96, v228
	v_sub_f32_e32 v97, v97, v228
	v_sub_f32_e32 v98, v98, v228
	v_sub_f32_e32 v99, v99, v228
	v_pk_mul_f32 v[98:99], v[228:229], v[98:99] op_sel:[1,0]
	v_pk_mul_f32 v[96:97], v[228:229], v[96:97] op_sel:[1,0]
	v_pk_fma_f32 v[98:99], v[204:205], v[98:99], v[216:217]
	v_pk_fma_f32 v[96:97], v[206:207], v[96:97], v[218:219]
	v_pk_fma_f32 v[94:95], v[94:95], v[130:131], v[98:99]
	v_pk_fma_f32 v[92:93], v[92:93], v[128:129], v[96:97]
	v_sub_f32_e32 v96, v101, v228
	v_sub_f32_e32 v97, v100, v228
	v_sub_f32_e32 v98, v103, v228
	v_sub_f32_e32 v99, v102, v228
	v_pk_mul_f32 v[98:99], v[228:229], v[98:99] op_sel:[1,0]
	v_pk_mul_f32 v[96:97], v[228:229], v[96:97] op_sel:[1,0]
	v_pk_fma_f32 v[98:99], v[208:209], v[98:99], v[212:213]
	v_pk_fma_f32 v[96:97], v[210:211], v[96:97], v[214:215]
	v_pk_fma_f32 v[98:99], v[90:91], v[114:115], v[98:99]
	v_pk_fma_f32 v[90:91], v[88:89], v[112:113], v[96:97]
	v_cvt_pk_f16_f32 v88, v92, v93
	v_lshl_add_u64 v[92:93], s[16:17], 0, v[230:231]
	v_cvt_pk_f16_f32 v89, v94, v95
	v_cvt_pk_f16_f32 v90, v90, v91
	v_cvt_pk_f16_f32 v91, v98, v99
	v_lshl_add_u64 v[92:93], v[92:93], 0, v[220:221]
	global_store_dwordx4 v[92:93], v[88:91], off
	v_cvt_f32_f16_sdwa v94, v146 dst_sel:DWORD dst_unused:UNUSED_PAD src0_sel:WORD_1
	v_cvt_f32_f16_e32 v95, v146
	v_cvt_f32_f16_sdwa v89, v144 dst_sel:DWORD dst_unused:UNUSED_PAD src0_sel:WORD_1
	v_cvt_f32_f16_e32 v88, v144
	v_cvt_f32_f16_sdwa v91, v145 dst_sel:DWORD dst_unused:UNUSED_PAD src0_sel:WORD_1
	v_cvt_f32_f16_e32 v90, v145
	v_cvt_f32_f16_sdwa v96, v147 dst_sel:DWORD dst_unused:UNUSED_PAD src0_sel:WORD_1
	v_cvt_f32_f16_e32 v97, v147
	v_sub_f32_e32 v88, v88, v228
	v_sub_f32_e32 v89, v89, v228
	v_sub_f32_e32 v90, v90, v228
	v_sub_f32_e32 v91, v91, v228
	v_pk_mul_f32 v[90:91], v[228:229], v[90:91] op_sel:[1,0]
;     __device__ __forceinline__ void operator()(const AccT& acc, const pg8::Unit& u, int wr, int wc, int fr, int fq) const {
;     ...
;         for (int ai = 0; ai < 2; ++ai) {
;             u32x4 uraw[4][2]; f32x2 stv[4];
; #pragma unroll
;             for (int m = 0; m < 4; ++m) { const int row = row0 + ai * 128 + m * 16; const size_t off = (size_t)row * D + col0; stv[m] = *(const f32x2*)(stats + 2 * row);
; #pragma unroll
;                 for (int bj = 0; bj < 2; ++bj) uraw[m][bj] = *(const u32x4*)(U1 + off + bj * 128); }
; #pragma unroll
;             for (int m = 0; m < 4; ++m) { const int row = row0 + ai * 128 + m * 16; const size_t off = (size_t)row * D + col0; const f32x2 st = stv[m];
; #pragma unroll
;                 for (int bj = 0; bj < 2; ++bj) { float uf[8]; unpack_h8(uraw[m][bj], uf);
;                     const f32x4 ua = {uf[0], uf[1], uf[2], uf[3]}, ub = {uf[4], uf[5], uf[6], uf[7]};
;                     const f32x4 a = ((ua - st.x) * st.y) * lg[bj][0] + lbv[bj][0] + gv[bj][0] * acc[ai][bj][m][0], b = ((ub - st.x) * st.y) * lg[bj][1] + lbv[bj][1] + gv[bj][1] * acc[ai][bj][m][1];
;                     u32x4 w; w.x = pk_h2(a[0], a[1]); w.y = pk_h2(a[2], a[3]); w.z = pk_h2(b[0], b[1]); w.w = pk_h2(b[2], b[3]);
;                     *(u32x4*)(U2 + off + bj * 128) = w; } }
	v_pk_mul_f32 v[88:89], v[228:229], v[88:89] op_sel:[1,0]
	v_pk_fma_f32 v[90:91], v[196:197], v[90:91], v[200:201]
	v_pk_fma_f32 v[88:89], v[198:199], v[88:89], v[202:203]
	v_pk_fma_f32 v[86:87], v[86:87], v[126:127], v[90:91]
	v_pk_fma_f32 v[84:85], v[84:85], v[124:125], v[88:89]
	v_sub_f32_e32 v88, v95, v228
	v_sub_f32_e32 v89, v94, v228
	v_sub_f32_e32 v90, v97, v228
	v_sub_f32_e32 v91, v96, v228
	v_pk_mul_f32 v[90:91], v[228:229], v[90:91] op_sel:[1,0]
	v_pk_mul_f32 v[88:89], v[228:229], v[88:89] op_sel:[1,0]
	v_pk_fma_f32 v[90:91], v[188:189], v[90:91], v[192:193]
	v_pk_fma_f32 v[88:89], v[190:191], v[88:89], v[194:195]
	v_pk_fma_f32 v[90:91], v[82:83], v[110:111], v[90:91]
	v_pk_fma_f32 v[82:83], v[80:81], v[108:109], v[88:89]
	v_cvt_pk_f16_f32 v80, v84, v85
	v_cvt_pk_f16_f32 v81, v86, v87
	v_cvt_pk_f16_f32 v82, v82, v83
	v_cvt_pk_f16_f32 v83, v90, v91
	global_store_dwordx4 v[92:93], v[80:83], off offset:256
	v_cvt_f32_f16_sdwa v84, v170 dst_sel:DWORD dst_unused:UNUSED_PAD src0_sel:WORD_1
	v_cvt_f32_f16_e32 v85, v170
	v_cvt_f32_f16_sdwa v81, v168 dst_sel:DWORD dst_unused:UNUSED_PAD src0_sel:WORD_1
	v_cvt_f32_f16_e32 v80, v168
	v_cvt_f32_f16_sdwa v83, v169 dst_sel:DWORD dst_unused:UNUSED_PAD src0_sel:WORD_1
	v_cvt_f32_f16_e32 v82, v169
	v_cvt_f32_f16_sdwa v86, v171 dst_sel:DWORD dst_unused:UNUSED_PAD src0_sel:WORD_1
	v_cvt_f32_f16_e32 v87, v171
	v_sub_f32_e32 v80, v80, v226
	v_sub_f32_e32 v81, v81, v226
	v_sub_f32_e32 v82, v82, v226
	v_sub_f32_e32 v83, v83, v226
	v_pk_mul_f32 v[82:83], v[226:227], v[82:83] op_sel:[1,0]
	v_pk_mul_f32 v[80:81], v[226:227], v[80:81] op_sel:[1,0]
	v_pk_fma_f32 v[82:83], v[204:205], v[82:83], v[216:217]
	v_pk_fma_f32 v[80:81], v[206:207], v[80:81], v[218:219]
	v_pk_fma_f32 v[78:79], v[78:79], v[130:131], v[82:83]
	v_pk_fma_f32 v[76:77], v[76:77], v[128:129], v[80:81]
	v_sub_f32_e32 v80, v85, v226
	v_sub_f32_e32 v81, v84, v226
	v_sub_f32_e32 v82, v87, v226
	v_sub_f32_e32 v83, v86, v226
	v_pk_mul_f32 v[82:83], v[226:227], v[82:83] op_sel:[1,0]
	v_pk_mul_f32 v[80:81], v[226:227], v[80:81] op_sel:[1,0]
	v_pk_fma_f32 v[82:83], v[208:209], v[82:83], v[212:213]
	v_pk_fma_f32 v[80:81], v[210:211], v[80:81], v[214:215]
	v_pk_fma_f32 v[82:83], v[74:75], v[114:115], v[82:83]
	v_pk_fma_f32 v[74:75], v[72:73], v[112:113], v[80:81]
	v_cvt_pk_f16_f32 v72, v76, v77
	v_lshl_add_u64 v[76:77], s[16:17], 0, v[232:233]
	v_cvt_pk_f16_f32 v73, v78, v79
	v_cvt_pk_f16_f32 v74, v74, v75
	v_cvt_pk_f16_f32 v75, v82, v83
	v_lshl_add_u64 v[76:77], v[76:77], 0, v[220:221]
	global_store_dwordx4 v[76:77], v[72:75], off
	v_cvt_f32_f16_sdwa v78, v158 dst_sel:DWORD dst_unused:UNUSED_PAD src0_sel:WORD_1
	v_cvt_f32_f16_e32 v79, v158
	v_cvt_f32_f16_sdwa v73, v156 dst_sel:DWORD dst_unused:UNUSED_PAD src0_sel:WORD_1
	v_cvt_f32_f16_e32 v72, v156
	v_cvt_f32_f16_sdwa v75, v157 dst_sel:DWORD dst_unused:UNUSED_PAD src0_sel:WORD_1
	v_cvt_f32_f16_e32 v74, v157
	v_cvt_f32_f16_sdwa v80, v159 dst_sel:DWORD dst_unused:UNUSED_PAD src0_sel:WORD_1
	v_cvt_f32_f16_e32 v81, v159
	v_sub_f32_e32 v72, v72, v226
	v_sub_f32_e32 v73, v73, v226
	v_sub_f32_e32 v74, v74, v226
	v_sub_f32_e32 v75, v75, v226
	v_pk_mul_f32 v[74:75], v[226:227], v[74:75] op_sel:[1,0]
	v_pk_mul_f32 v[72:73], v[226:227], v[72:73] op_sel:[1,0]
	v_pk_fma_f32 v[74:75], v[196:197], v[74:75], v[200:201]
	v_pk_fma_f32 v[72:73], v[198:199], v[72:73], v[202:203]
	v_pk_fma_f32 v[70:71], v[70:71], v[126:127], v[74:75]
	v_pk_fma_f32 v[68:69], v[68:69], v[124:125], v[72:73]
	v_sub_f32_e32 v72, v79, v226
	v_sub_f32_e32 v73, v78, v226
	v_sub_f32_e32 v74, v81, v226
	v_sub_f32_e32 v75, v80, v226
	v_pk_mul_f32 v[74:75], v[226:227], v[74:75] op_sel:[1,0]
	v_pk_mul_f32 v[72:73], v[226:227], v[72:73] op_sel:[1,0]
	v_pk_fma_f32 v[74:75], v[188:189], v[74:75], v[192:193]
	v_pk_fma_f32 v[72:73], v[190:191], v[72:73], v[194:195]
	v_pk_fma_f32 v[74:75], v[66:67], v[110:111], v[74:75]
	v_pk_fma_f32 v[66:67], v[64:65], v[108:109], v[72:73]
	v_cvt_pk_f16_f32 v64, v68, v69
	v_cvt_pk_f16_f32 v65, v70, v71
	v_cvt_pk_f16_f32 v66, v66, v67
	v_cvt_pk_f16_f32 v67, v74, v75
	global_store_dwordx4 v[76:77], v[64:67], off offset:256
	s_nop 1
	v_add_u32_e32 v64, 0x80, v224
	v_ashrrev_i32_e32 v65, 31, v64
	v_lshlrev_b32_e32 v66, 1, v64
	v_ashrrev_i32_e32 v67, 31, v66
	v_lshlrev_b64 v[106:107], 12, v[64:65]
	v_lshl_add_u64 v[66:67], v[66:67], 2, s[8:9]
	v_lshl_add_u64 v[64:65], v[222:223], 0, v[106:107]
	global_load_dwordx2 v[104:105], v[66:67], off
	global_load_dwordx4 v[84:87], v[64:65], off
	global_load_dwordx4 v[88:91], v[64:65], off offset:256
	v_add_u32_e32 v64, 0x90, v224
	v_ashrrev_i32_e32 v65, 31, v64
	v_lshlrev_b32_e32 v66, 1, v64
	v_ashrrev_i32_e32 v67, 31, v66
	v_lshlrev_b64 v[118:119], 12, v[64:65]
	v_lshl_add_u64 v[66:67], v[66:67], 2, s[8:9]
	v_lshl_add_u64 v[64:65], v[222:223], 0, v[118:119]
	global_load_dwordx2 v[116:117], v[66:67], off
	global_load_dwordx4 v[92:95], v[64:65], off
	global_load_dwordx4 v[96:99], v[64:65], off offset:256
	v_add_u32_e32 v64, 0xa0, v224
	v_ashrrev_i32_e32 v65, 31, v64
	v_lshlrev_b32_e32 v66, 1, v64
	v_ashrrev_i32_e32 v67, 31, v66
	v_lshlrev_b64 v[82:83], 12, v[64:65]
	v_lshl_add_u64 v[66:67], v[66:67], 2, s[8:9]
	v_lshl_add_u64 v[64:65], v[222:223], 0, v[82:83]
	global_load_dwordx2 v[80:81], v[66:67], off
	global_load_dwordx4 v[100:103], v[64:65], off
	global_load_dwordx4 v[72:75], v[64:65], off offset:256
	v_add_u32_e32 v64, 0xb0, v224
	v_ashrrev_i32_e32 v65, 31, v64
	v_lshlrev_b32_e32 v66, 1, v64
	v_ashrrev_i32_e32 v67, 31, v66
	v_lshlrev_b64 v[78:79], 12, v[64:65]
	v_lshl_add_u64 v[66:67], v[66:67], 2, s[8:9]
	v_lshl_add_u64 v[64:65], v[222:223], 0, v[78:79]
	global_load_dwordx2 v[76:77], v[66:67], off
	global_load_dwordx4 v[68:71], v[64:65], off
	s_nop 0
	global_load_dwordx4 v[64:67], v[64:65], off offset:256
	s_waitcnt vmcnt(0)
;     __device__ __forceinline__ void operator()(const AccT& acc, const pg8::Unit& u, int wr, int wc, int fr, int fq) const {
;     ...
;             for (int m = 0; m < 4; ++m) { const int row = row0 + ai * 128 + m * 16; const size_t off = (size_t)row * D + col0; const f32x2 st = stv[m];
; #pragma unroll
;                 for (int bj = 0; bj < 2; ++bj) { float uf[8]; unpack_h8(uraw[m][bj], uf);
;                     const f32x4 ua = {uf[0], uf[1], uf[2], uf[3]}, ub = {uf[4], uf[5], uf[6], uf[7]};
;                     const f32x4 a = ((ua - st.x) * st.y) * lg[bj][0] + lbv[bj][0] + gv[bj][0] * acc[ai][bj][m][0], b = ((ub - st.x) * st.y) * lg[bj][1] + lbv[bj][1] + gv[bj][1] * acc[ai][bj][m][1];
;                     u32x4 w; w.x = pk_h2(a[0], a[1]); w.y = pk_h2(a[2], a[3]); w.z = pk_h2(b[0], b[1]); w.w = pk_h2(b[2], b[3]);
;                     *(u32x4*)(U2 + off + bj * 128) = w; } }
	v_cvt_f32_f16_e32 v120, v84
	v_cvt_f32_f16_sdwa v84, v84 dst_sel:DWORD dst_unused:UNUSED_PAD src0_sel:WORD_1
	v_cvt_f32_f16_e32 v121, v85
	v_cvt_f32_f16_sdwa v122, v85 dst_sel:DWORD dst_unused:UNUSED_PAD src0_sel:WORD_1
	v_cvt_f32_f16_e32 v123, v86
	v_cvt_f32_f16_sdwa v132, v86 dst_sel:DWORD dst_unused:UNUSED_PAD src0_sel:WORD_1
	v_cvt_f32_f16_e32 v133, v87
	v_cvt_f32_f16_sdwa v134, v87 dst_sel:DWORD dst_unused:UNUSED_PAD src0_sel:WORD_1
	v_sub_f32_e32 v85, v84, v104
	v_sub_f32_e32 v84, v120, v104
	v_sub_f32_e32 v87, v122, v104
	v_sub_f32_e32 v86, v121, v104
	v_pk_mul_f32 v[86:87], v[104:105], v[86:87] op_sel:[1,0]
	v_pk_mul_f32 v[84:85], v[104:105], v[84:85] op_sel:[1,0]
	v_pk_fma_f32 v[86:87], v[204:205], v[86:87], v[216:217]
	v_pk_fma_f32 v[84:85], v[206:207], v[84:85], v[218:219]
	v_pk_fma_f32 v[62:63], v[62:63], v[130:131], v[86:87]
	v_pk_fma_f32 v[60:61], v[60:61], v[128:129], v[84:85]
	v_sub_f32_e32 v85, v132, v104
	v_sub_f32_e32 v84, v123, v104
	v_sub_f32_e32 v87, v134, v104
	v_sub_f32_e32 v86, v133, v104
	v_pk_mul_f32 v[86:87], v[104:105], v[86:87] op_sel:[1,0]
	v_pk_mul_f32 v[84:85], v[104:105], v[84:85] op_sel:[1,0]
	v_pk_fma_f32 v[86:87], v[208:209], v[86:87], v[212:213]
	v_pk_fma_f32 v[84:85], v[210:211], v[84:85], v[214:215]
	v_pk_fma_f32 v[86:87], v[58:59], v[114:115], v[86:87]
	v_pk_fma_f32 v[58:59], v[56:57], v[112:113], v[84:85]
	v_cvt_pk_f16_f32 v56, v60, v61
	v_lshl_add_u64 v[60:61], s[16:17], 0, v[106:107]
	v_cvt_pk_f16_f32 v57, v62, v63
	v_cvt_pk_f16_f32 v58, v58, v59
	v_cvt_pk_f16_f32 v59, v86, v87
	v_lshl_add_u64 v[60:61], v[60:61], 0, v[220:221]
	global_store_dwordx4 v[60:61], v[56:59], off
	v_cvt_f32_f16_e32 v62, v90
	v_cvt_f32_f16_sdwa v63, v90 dst_sel:DWORD dst_unused:UNUSED_PAD src0_sel:WORD_1
	v_cvt_f32_f16_e32 v56, v88
	v_cvt_f32_f16_sdwa v57, v88 dst_sel:DWORD dst_unused:UNUSED_PAD src0_sel:WORD_1
	v_cvt_f32_f16_e32 v58, v89
	v_cvt_f32_f16_sdwa v59, v89 dst_sel:DWORD dst_unused:UNUSED_PAD src0_sel:WORD_1
	v_cvt_f32_f16_e32 v84, v91
	v_cvt_f32_f16_sdwa v85, v91 dst_sel:DWORD dst_unused:UNUSED_PAD src0_sel:WORD_1
	v_sub_f32_e32 v57, v57, v104
	v_sub_f32_e32 v56, v56, v104
	v_sub_f32_e32 v59, v59, v104
	v_sub_f32_e32 v58, v58, v104
	v_pk_mul_f32 v[58:59], v[104:105], v[58:59] op_sel:[1,0]
	v_pk_mul_f32 v[56:57], v[104:105], v[56:57] op_sel:[1,0]
	v_pk_fma_f32 v[58:59], v[196:197], v[58:59], v[200:201]
	v_pk_fma_f32 v[56:57], v[198:199], v[56:57], v[202:203]
	v_pk_fma_f32 v[54:55], v[54:55], v[126:127], v[58:59]
	v_pk_fma_f32 v[52:53], v[52:53], v[124:125], v[56:57]
	v_sub_f32_e32 v57, v63, v104
	v_sub_f32_e32 v56, v62, v104
	v_sub_f32_e32 v59, v85, v104
	v_sub_f32_e32 v58, v84, v104
	v_pk_mul_f32 v[58:59], v[104:105], v[58:59] op_sel:[1,0]
	v_pk_mul_f32 v[56:57], v[104:105], v[56:57] op_sel:[1,0]
	v_pk_fma_f32 v[58:59], v[188:189], v[58:59], v[192:193]
	v_pk_fma_f32 v[56:57], v[190:191], v[56:57], v[194:195]
	v_pk_fma_f32 v[58:59], v[50:51], v[110:111], v[58:59]
	v_pk_fma_f32 v[50:51], v[48:49], v[108:109], v[56:57]
	v_cvt_pk_f16_f32 v48, v52, v53
	v_cvt_pk_f16_f32 v49, v54, v55
	v_cvt_pk_f16_f32 v50, v50, v51
	v_cvt_pk_f16_f32 v51, v58, v59
	global_store_dwordx4 v[60:61], v[48:51], off offset:256
	v_cvt_f32_f16_e32 v52, v94
	v_cvt_f32_f16_sdwa v53, v94 dst_sel:DWORD dst_unused:UNUSED_PAD src0_sel:WORD_1
	v_cvt_f32_f16_e32 v48, v92
	v_cvt_f32_f16_sdwa v49, v92 dst_sel:DWORD dst_unused:UNUSED_PAD src0_sel:WORD_1
	v_cvt_f32_f16_e32 v50, v93
	v_cvt_f32_f16_sdwa v51, v93 dst_sel:DWORD dst_unused:UNUSED_PAD src0_sel:WORD_1
	v_cvt_f32_f16_e32 v54, v95
	v_cvt_f32_f16_sdwa v55, v95 dst_sel:DWORD dst_unused:UNUSED_PAD src0_sel:WORD_1
	v_sub_f32_e32 v49, v49, v116
	v_sub_f32_e32 v48, v48, v116
	v_sub_f32_e32 v51, v51, v116
	v_sub_f32_e32 v50, v50, v116
	v_pk_mul_f32 v[50:51], v[116:117], v[50:51] op_sel:[1,0]
	v_pk_mul_f32 v[48:49], v[116:117], v[48:49] op_sel:[1,0]
	v_pk_fma_f32 v[50:51], v[204:205], v[50:51], v[216:217]
	v_pk_fma_f32 v[48:49], v[206:207], v[48:49], v[218:219]
	v_pk_fma_f32 v[46:47], v[46:47], v[130:131], v[50:51]
	v_pk_fma_f32 v[44:45], v[44:45], v[128:129], v[48:49]
	v_sub_f32_e32 v49, v53, v116
	v_sub_f32_e32 v48, v52, v116
	v_sub_f32_e32 v51, v55, v116
	v_sub_f32_e32 v50, v54, v116
	v_pk_mul_f32 v[50:51], v[116:117], v[50:51] op_sel:[1,0]
	v_pk_mul_f32 v[48:49], v[116:117], v[48:49] op_sel:[1,0]
	v_pk_fma_f32 v[50:51], v[208:209], v[50:51], v[212:213]
	v_pk_fma_f32 v[48:49], v[210:211], v[48:49], v[214:215]
	v_pk_fma_f32 v[50:51], v[42:43], v[114:115], v[50:51]
	v_pk_fma_f32 v[42:43], v[40:41], v[112:113], v[48:49]
	v_cvt_pk_f16_f32 v40, v44, v45
	v_lshl_add_u64 v[44:45], s[16:17], 0, v[118:119]
	v_cvt_pk_f16_f32 v41, v46, v47
	v_cvt_pk_f16_f32 v42, v42, v43
	v_cvt_pk_f16_f32 v43, v50, v51
	v_lshl_add_u64 v[44:45], v[44:45], 0, v[220:221]
	global_store_dwordx4 v[44:45], v[40:43], off
	v_cvt_f32_f16_e32 v46, v98
	v_cvt_f32_f16_sdwa v47, v98 dst_sel:DWORD dst_unused:UNUSED_PAD src0_sel:WORD_1
	v_cvt_f32_f16_e32 v40, v96
	v_cvt_f32_f16_sdwa v41, v96 dst_sel:DWORD dst_unused:UNUSED_PAD src0_sel:WORD_1
	v_cvt_f32_f16_e32 v42, v97
	v_cvt_f32_f16_sdwa v43, v97 dst_sel:DWORD dst_unused:UNUSED_PAD src0_sel:WORD_1
	v_cvt_f32_f16_e32 v48, v99
	v_cvt_f32_f16_sdwa v49, v99 dst_sel:DWORD dst_unused:UNUSED_PAD src0_sel:WORD_1
	v_sub_f32_e32 v41, v41, v116
	v_sub_f32_e32 v40, v40, v116
	v_sub_f32_e32 v43, v43, v116
	v_sub_f32_e32 v42, v42, v116
	v_pk_mul_f32 v[42:43], v[116:117], v[42:43] op_sel:[1,0]
	v_pk_mul_f32 v[40:41], v[116:117], v[40:41] op_sel:[1,0]
	v_pk_fma_f32 v[42:43], v[196:197], v[42:43], v[200:201]
	v_pk_fma_f32 v[40:41], v[198:199], v[40:41], v[202:203]
	v_pk_fma_f32 v[38:39], v[38:39], v[126:127], v[42:43]
; #define PG8_WAIT_V(n) asm volatile("s_waitcnt vmcnt(" #n ")" ::: "memory")
; #define PG8_BAR __builtin_amdgcn_s_barrier()
; template <class Epi, class Sched>
; __device__ __forceinline__ void gemm_phase(PG8_LAS unsigned char* lds, const Gemm g, const Sched& S, const Epi& E) {
;     ...
;         if (!has_next) break;
; #pragma unroll
;         for (int a = 0; a < 2; ++a)
; #pragma unroll
;             for (int b = 0; b < 2; ++b)
; #pragma unroll
;                 for (int m = 0; m < 4; ++m)
; #pragma unroll
;                     for (int n = 0; n < 2; ++n) acc[a][b][m][n] = (f32x4){0.f, 0.f, 0.f, 0.f};
;         cur = nxt; cA = nA; cB = nB; ++ui;
;     }
;     PG8_WAIT_V(0);
;     if (wr == 0) PG8_BAR;
;     PG8_BAR;
;     __device__ __forceinline__ void operator()(const AccT& acc, const pg8::Unit& u, int wr, int wc, int fr, int fq) const {
;     ...
;             for (int m = 0; m < 4; ++m) { const int row = row0 + ai * 128 + m * 16; const size_t off = (size_t)row * D + col0; const f32x2 st = stv[m];
; #pragma unroll
;                 for (int bj = 0; bj < 2; ++bj) { float uf[8]; unpack_h8(uraw[m][bj], uf);
;                     const f32x4 ua = {uf[0], uf[1], uf[2], uf[3]}, ub = {uf[4], uf[5], uf[6], uf[7]};
;                     const f32x4 a = ((ua - st.x) * st.y) * lg[bj][0] + lbv[bj][0] + gv[bj][0] * acc[ai][bj][m][0], b = ((ub - st.x) * st.y) * lg[bj][1] + lbv[bj][1] + gv[bj][1] * acc[ai][bj][m][1];
;                     u32x4 w; w.x = pk_h2(a[0], a[1]); w.y = pk_h2(a[2], a[3]); w.z = pk_h2(b[0], b[1]); w.w = pk_h2(b[2], b[3]);
;                     *(u32x4*)(U2 + off + bj * 128) = w; } }
	v_pk_fma_f32 v[36:37], v[36:37], v[124:125], v[40:41]
	v_sub_f32_e32 v41, v47, v116
	v_sub_f32_e32 v40, v46, v116
	v_sub_f32_e32 v43, v49, v116
	v_sub_f32_e32 v42, v48, v116
	v_pk_mul_f32 v[42:43], v[116:117], v[42:43] op_sel:[1,0]
	v_pk_mul_f32 v[40:41], v[116:117], v[40:41] op_sel:[1,0]
	v_pk_fma_f32 v[42:43], v[188:189], v[42:43], v[192:193]
	v_pk_fma_f32 v[40:41], v[190:191], v[40:41], v[194:195]
	v_pk_fma_f32 v[42:43], v[34:35], v[110:111], v[42:43]
	v_pk_fma_f32 v[34:35], v[32:33], v[108:109], v[40:41]
	v_cvt_pk_f16_f32 v32, v36, v37
	v_cvt_pk_f16_f32 v33, v38, v39
	v_cvt_pk_f16_f32 v34, v34, v35
	v_cvt_pk_f16_f32 v35, v42, v43
	global_store_dwordx4 v[44:45], v[32:35], off offset:256
	v_cvt_f32_f16_e32 v36, v102
	v_cvt_f32_f16_sdwa v37, v102 dst_sel:DWORD dst_unused:UNUSED_PAD src0_sel:WORD_1
	v_cvt_f32_f16_e32 v32, v100
	v_cvt_f32_f16_sdwa v33, v100 dst_sel:DWORD dst_unused:UNUSED_PAD src0_sel:WORD_1
	v_cvt_f32_f16_e32 v34, v101
	v_cvt_f32_f16_sdwa v35, v101 dst_sel:DWORD dst_unused:UNUSED_PAD src0_sel:WORD_1
	v_cvt_f32_f16_e32 v38, v103
	v_cvt_f32_f16_sdwa v39, v103 dst_sel:DWORD dst_unused:UNUSED_PAD src0_sel:WORD_1
	v_sub_f32_e32 v33, v33, v80
	v_sub_f32_e32 v32, v32, v80
	v_sub_f32_e32 v35, v35, v80
	v_sub_f32_e32 v34, v34, v80
	v_pk_mul_f32 v[34:35], v[80:81], v[34:35] op_sel:[1,0]
	v_pk_mul_f32 v[32:33], v[80:81], v[32:33] op_sel:[1,0]
	v_pk_fma_f32 v[34:35], v[204:205], v[34:35], v[216:217]
	v_pk_fma_f32 v[32:33], v[206:207], v[32:33], v[218:219]
	v_pk_fma_f32 v[30:31], v[30:31], v[130:131], v[34:35]
	v_pk_fma_f32 v[28:29], v[28:29], v[128:129], v[32:33]
	v_sub_f32_e32 v33, v37, v80
	v_sub_f32_e32 v32, v36, v80
	v_sub_f32_e32 v35, v39, v80
	v_sub_f32_e32 v34, v38, v80
	v_pk_mul_f32 v[34:35], v[80:81], v[34:35] op_sel:[1,0]
	v_pk_mul_f32 v[32:33], v[80:81], v[32:33] op_sel:[1,0]
	v_pk_fma_f32 v[34:35], v[208:209], v[34:35], v[212:213]
	v_pk_fma_f32 v[32:33], v[210:211], v[32:33], v[214:215]
	v_pk_fma_f32 v[34:35], v[26:27], v[114:115], v[34:35]
	v_pk_fma_f32 v[26:27], v[24:25], v[112:113], v[32:33]
	v_cvt_pk_f16_f32 v24, v28, v29
	v_lshl_add_u64 v[28:29], s[16:17], 0, v[82:83]
	v_cvt_pk_f16_f32 v25, v30, v31
	v_cvt_pk_f16_f32 v26, v26, v27
	v_cvt_pk_f16_f32 v27, v34, v35
	v_lshl_add_u64 v[28:29], v[28:29], 0, v[220:221]
	global_store_dwordx4 v[28:29], v[24:27], off
	v_cvt_f32_f16_e32 v30, v74
	v_cvt_f32_f16_sdwa v31, v74 dst_sel:DWORD dst_unused:UNUSED_PAD src0_sel:WORD_1
	v_cvt_f32_f16_e32 v24, v72
	v_cvt_f32_f16_sdwa v25, v72 dst_sel:DWORD dst_unused:UNUSED_PAD src0_sel:WORD_1
	v_cvt_f32_f16_e32 v26, v73
	v_cvt_f32_f16_sdwa v27, v73 dst_sel:DWORD dst_unused:UNUSED_PAD src0_sel:WORD_1
	v_cvt_f32_f16_e32 v32, v75
	v_cvt_f32_f16_sdwa v33, v75 dst_sel:DWORD dst_unused:UNUSED_PAD src0_sel:WORD_1
	v_sub_f32_e32 v25, v25, v80
	v_sub_f32_e32 v24, v24, v80
	v_sub_f32_e32 v27, v27, v80
	v_sub_f32_e32 v26, v26, v80
	v_pk_mul_f32 v[26:27], v[80:81], v[26:27] op_sel:[1,0]
	v_pk_mul_f32 v[24:25], v[80:81], v[24:25] op_sel:[1,0]
	v_pk_fma_f32 v[26:27], v[196:197], v[26:27], v[200:201]
	v_pk_fma_f32 v[24:25], v[198:199], v[24:25], v[202:203]
	v_pk_fma_f32 v[22:23], v[22:23], v[126:127], v[26:27]
	v_pk_fma_f32 v[20:21], v[20:21], v[124:125], v[24:25]
	v_sub_f32_e32 v25, v31, v80
	v_sub_f32_e32 v24, v30, v80
	v_sub_f32_e32 v27, v33, v80
	v_sub_f32_e32 v26, v32, v80
	v_pk_mul_f32 v[26:27], v[80:81], v[26:27] op_sel:[1,0]
	v_pk_mul_f32 v[24:25], v[80:81], v[24:25] op_sel:[1,0]
	v_pk_fma_f32 v[26:27], v[188:189], v[26:27], v[192:193]
	v_pk_fma_f32 v[24:25], v[190:191], v[24:25], v[194:195]
	v_pk_fma_f32 v[26:27], v[18:19], v[110:111], v[26:27]
	v_pk_fma_f32 v[18:19], v[16:17], v[108:109], v[24:25]
	v_cvt_pk_f16_f32 v16, v20, v21
	v_cvt_pk_f16_f32 v17, v22, v23
	v_cvt_pk_f16_f32 v18, v18, v19
	v_cvt_pk_f16_f32 v19, v26, v27
	global_store_dwordx4 v[28:29], v[16:19], off offset:256
	v_cvt_f32_f16_e32 v20, v70
	v_cvt_f32_f16_sdwa v21, v70 dst_sel:DWORD dst_unused:UNUSED_PAD src0_sel:WORD_1
	v_cvt_f32_f16_e32 v16, v68
	v_cvt_f32_f16_sdwa v17, v68 dst_sel:DWORD dst_unused:UNUSED_PAD src0_sel:WORD_1
	v_cvt_f32_f16_e32 v18, v69
	v_cvt_f32_f16_sdwa v19, v69 dst_sel:DWORD dst_unused:UNUSED_PAD src0_sel:WORD_1
	v_cvt_f32_f16_e32 v22, v71
	v_cvt_f32_f16_sdwa v23, v71 dst_sel:DWORD dst_unused:UNUSED_PAD src0_sel:WORD_1
	v_sub_f32_e32 v17, v17, v76
	v_sub_f32_e32 v16, v16, v76
	v_sub_f32_e32 v19, v19, v76
	v_sub_f32_e32 v18, v18, v76
	v_pk_mul_f32 v[18:19], v[76:77], v[18:19] op_sel:[1,0]
	v_pk_mul_f32 v[16:17], v[76:77], v[16:17] op_sel:[1,0]
	v_pk_fma_f32 v[18:19], v[204:205], v[18:19], v[216:217]
	v_pk_fma_f32 v[16:17], v[206:207], v[16:17], v[218:219]
	v_pk_fma_f32 v[14:15], v[14:15], v[130:131], v[18:19]
	v_pk_fma_f32 v[12:13], v[12:13], v[128:129], v[16:17]
	v_sub_f32_e32 v17, v21, v76
	v_sub_f32_e32 v16, v20, v76
	v_sub_f32_e32 v19, v23, v76
	v_sub_f32_e32 v18, v22, v76
	v_pk_mul_f32 v[18:19], v[76:77], v[18:19] op_sel:[1,0]
	v_pk_mul_f32 v[16:17], v[76:77], v[16:17] op_sel:[1,0]
	v_pk_fma_f32 v[18:19], v[208:209], v[18:19], v[212:213]
	v_pk_fma_f32 v[16:17], v[210:211], v[16:17], v[214:215]
	v_pk_fma_f32 v[18:19], v[10:11], v[114:115], v[18:19]
	v_pk_fma_f32 v[10:11], v[8:9], v[112:113], v[16:17]
	v_cvt_pk_f16_f32 v8, v12, v13
	v_lshl_add_u64 v[12:13], s[16:17], 0, v[78:79]
	v_cvt_pk_f16_f32 v9, v14, v15
	v_cvt_pk_f16_f32 v10, v10, v11
	v_cvt_pk_f16_f32 v11, v18, v19
	v_lshl_add_u64 v[12:13], v[12:13], 0, v[220:221]
	global_store_dwordx4 v[12:13], v[8:11], off
	v_cvt_f32_f16_e32 v14, v66
	v_cvt_f32_f16_sdwa v15, v66 dst_sel:DWORD dst_unused:UNUSED_PAD src0_sel:WORD_1
	v_cvt_f32_f16_e32 v8, v64
	v_cvt_f32_f16_sdwa v9, v64 dst_sel:DWORD dst_unused:UNUSED_PAD src0_sel:WORD_1
	v_cvt_f32_f16_e32 v10, v65
	v_cvt_f32_f16_sdwa v11, v65 dst_sel:DWORD dst_unused:UNUSED_PAD src0_sel:WORD_1
	v_cvt_f32_f16_e32 v16, v67
	v_cvt_f32_f16_sdwa v17, v67 dst_sel:DWORD dst_unused:UNUSED_PAD src0_sel:WORD_1
	v_sub_f32_e32 v9, v9, v76
	v_sub_f32_e32 v8, v8, v76
	v_sub_f32_e32 v11, v11, v76
	v_sub_f32_e32 v10, v10, v76
	v_pk_mul_f32 v[10:11], v[76:77], v[10:11] op_sel:[1,0]
	v_pk_mul_f32 v[8:9], v[76:77], v[8:9] op_sel:[1,0]
	v_pk_fma_f32 v[10:11], v[196:197], v[10:11], v[200:201]
	v_pk_fma_f32 v[8:9], v[198:199], v[8:9], v[202:203]
	v_pk_fma_f32 v[6:7], v[6:7], v[126:127], v[10:11]
	v_pk_fma_f32 v[4:5], v[4:5], v[124:125], v[8:9]
	v_sub_f32_e32 v9, v15, v76
	v_sub_f32_e32 v8, v14, v76
	v_sub_f32_e32 v11, v17, v76
	v_sub_f32_e32 v10, v16, v76
	v_pk_mul_f32 v[10:11], v[76:77], v[10:11] op_sel:[1,0]
	v_pk_mul_f32 v[8:9], v[76:77], v[8:9] op_sel:[1,0]
	v_pk_fma_f32 v[10:11], v[188:189], v[10:11], v[192:193]
	v_pk_fma_f32 v[8:9], v[190:191], v[8:9], v[194:195]
	v_pk_fma_f32 v[10:11], v[2:3], v[110:111], v[10:11]
	v_pk_fma_f32 v[2:3], v[0:1], v[108:109], v[8:9]
	v_cvt_pk_f16_f32 v0, v4, v5
	v_cvt_pk_f16_f32 v1, v6, v7
	v_cvt_pk_f16_f32 v2, v2, v3
	v_cvt_pk_f16_f32 v3, v10, v11
	global_store_dwordx4 v[12:13], v[0:3], off offset:256
	s_cbranch_vccz .LBB0_871
	s_waitcnt vmcnt(0)
	s_cmpk_gt_u32 s21, 0xff
	s_cbranch_scc1 .LBB0_886
	s_barrier
